# closing barrier of each MFMA segment 3 MFMAs before its end (was 2)
# speedup vs baseline: 1.0034x; 1.0007x over previous
.LBB0_120:
	ds_read_b128 v[128:131], v178
	ds_read_b128 v[132:135], v178 offset:1024
	ds_read_b128 v[154:157], v178 offset:2048
	ds_read_b128 v[158:161], v178 offset:3072
	ds_read_b128 v[162:165], v179
	ds_read_b128 v[166:169], v179 offset:1024
	ds_read_b128 v[182:185], v179 offset:2048
	ds_read_b128 v[186:189], v179 offset:3072
	s_add_u32 s67, s88, 0xfffc0080
	s_addc_u32 s68, s89, -1
	s_cmp_eq_u32 s66, 12
	s_cselect_b32 s93, s52, s68
	s_cselect_b32 s92, s53, s67
	s_cselect_b32 s91, s56, s59
	s_cselect_b32 s90, s57, s58
	v_lshl_add_u64 v[170:171], s[88:89], 0, v[144:145]
	s_add_i32 m0, s17, 0xc000
	ds_read_b128 v[190:193], v180
	ds_read_b128 v[194:197], v180 offset:1024
	ds_read_b128 v[198:201], v180 offset:2048
	ds_read_b128 v[202:205], v180 offset:3072
	ds_read_b128 v[206:209], v180 offset:4096
	ds_read_b128 v[210:213], v180 offset:5120
	ds_read_b128 v[214:217], v180 offset:6144
	ds_read_b128 v[218:221], v180 offset:7168
	global_load_lds_dwordx4 v[170:171], off
	s_add_i32 m0, s17, 0xe000
	v_lshl_add_u64 v[170:171], s[88:89], 0, v[148:149]
	global_load_lds_dwordx4 v[170:171], off
	s_cmp_eq_u32 s66, -2
	s_waitcnt vmcnt(8) lgkmcnt(0)
	s_barrier
	s_setprio 1
	s_cbranch_scc1 .Lzv_0_0
	v_mfma_f32_16x16x32_bf16 v[124:127], v[128:131], v[190:193], v[124:127]
	v_mfma_f32_16x16x32_bf16 v[124:127], v[132:135], v[194:197], v[124:127]
	v_mfma_f32_16x16x32_bf16 v[116:119], v[154:157], v[190:193], v[116:119]
	v_mfma_f32_16x16x32_bf16 v[116:119], v[158:161], v[194:197], v[116:119]
	v_mfma_f32_16x16x32_bf16 v[108:111], v[128:131], v[198:201], v[108:111]
	v_mfma_f32_16x16x32_bf16 v[108:111], v[132:135], v[202:205], v[108:111]
	v_mfma_f32_16x16x32_bf16 v[100:103], v[154:157], v[198:201], v[100:103]
	v_mfma_f32_16x16x32_bf16 v[100:103], v[158:161], v[202:205], v[100:103]
	v_mfma_f32_16x16x32_bf16 v[92:95], v[128:131], v[206:209], v[92:95]
	v_mfma_f32_16x16x32_bf16 v[92:95], v[132:135], v[210:213], v[92:95]
	v_mfma_f32_16x16x32_bf16 v[84:87], v[154:157], v[206:209], v[84:87]
	v_mfma_f32_16x16x32_bf16 v[84:87], v[158:161], v[210:213], v[84:87]
	v_mfma_f32_16x16x32_bf16 v[76:79], v[128:131], v[214:217], v[76:79]
	v_mfma_f32_16x16x32_bf16 v[76:79], v[132:135], v[218:221], v[76:79]
	v_mfma_f32_16x16x32_bf16 v[68:71], v[154:157], v[214:217], v[68:71]
	v_mfma_f32_16x16x32_bf16 v[68:71], v[158:161], v[218:221], v[68:71]
	v_mfma_f32_16x16x32_bf16 v[120:123], v[162:165], v[190:193], v[120:123]
	v_mfma_f32_16x16x32_bf16 v[120:123], v[166:169], v[194:197], v[120:123]
	v_mfma_f32_16x16x32_bf16 v[112:115], v[182:185], v[190:193], v[112:115]
	v_mfma_f32_16x16x32_bf16 v[112:115], v[186:189], v[194:197], v[112:115]
	v_mfma_f32_16x16x32_bf16 v[104:107], v[162:165], v[198:201], v[104:107]
	v_mfma_f32_16x16x32_bf16 v[104:107], v[166:169], v[202:205], v[104:107]
	v_mfma_f32_16x16x32_bf16 v[96:99], v[182:185], v[198:201], v[96:99]
	v_mfma_f32_16x16x32_bf16 v[96:99], v[186:189], v[202:205], v[96:99]
	v_mfma_f32_16x16x32_bf16 v[88:91], v[162:165], v[206:209], v[88:91]
	v_mfma_f32_16x16x32_bf16 v[88:91], v[166:169], v[210:213], v[88:91]
	v_mfma_f32_16x16x32_bf16 v[80:83], v[182:185], v[206:209], v[80:83]
	v_mfma_f32_16x16x32_bf16 v[80:83], v[186:189], v[210:213], v[80:83]
	v_mfma_f32_16x16x32_bf16 v[72:75], v[162:165], v[214:217], v[72:75]
	s_setprio 3
	s_barrier
	v_mfma_f32_16x16x32_bf16 v[72:75], v[166:169], v[218:221], v[72:75]
	v_mfma_f32_16x16x32_bf16 v[64:67], v[182:185], v[214:217], v[64:67]
	v_mfma_f32_16x16x32_bf16 v[64:67], v[186:189], v[218:221], v[64:67]
	s_setprio 0
.Lzj_0_0:
	s_add_i32 s67, s25, s16
	v_lshl_add_u64 v[170:171], s[90:91], 0, v[140:141]
	s_mov_b32 m0, s67
	ds_read_b128 v[190:193], v180 offset:16384
	ds_read_b128 v[194:197], v180 offset:17408
	ds_read_b128 v[198:201], v180 offset:18432
	ds_read_b128 v[202:205], v180 offset:19456
	ds_read_b128 v[206:209], v180 offset:20480
	ds_read_b128 v[210:213], v180 offset:21504
	ds_read_b128 v[214:217], v180 offset:22528
	ds_read_b128 v[218:221], v180 offset:23552
	global_load_lds_dwordx4 v[170:171], off
	s_add_i32 m0, s67, 0x2000
	s_add_u32 s68, s90, 0x40000
	v_lshl_add_u64 v[222:223], s[90:91], 0, v[136:137]
	s_addc_u32 s69, s91, 0
	s_add_i32 s67, s26, s16
	global_load_lds_dwordx4 v[222:223], off
	v_lshl_add_u64 v[224:225], s[68:69], 0, v[140:141]
	s_mov_b32 m0, s67
	global_load_lds_dwordx4 v[224:225], off
	s_add_i32 m0, s67, 0x2000
	v_lshl_add_u64 v[224:225], s[68:69], 0, v[136:137]
	global_load_lds_dwordx4 v[224:225], off
	s_mov_b32 m0, s17
	v_lshl_add_u64 v[224:225], s[92:93], 0, v[142:143]
	global_load_lds_dwordx4 v[224:225], off
	s_mov_b32 m0, s18
	v_lshl_add_u64 v[226:227], s[92:93], 0, v[138:139]
	global_load_lds_dwordx4 v[226:227], off
	s_cmp_eq_u32 s66, -2
	s_waitcnt vmcnt(8) lgkmcnt(0)
	s_barrier
	s_setprio 1
	s_cbranch_scc1 .Lzv_0_1
	v_mfma_f32_16x16x32_bf16 v[60:63], v[128:131], v[190:193], v[60:63]
	v_mfma_f32_16x16x32_bf16 v[60:63], v[132:135], v[194:197], v[60:63]
	v_mfma_f32_16x16x32_bf16 v[52:55], v[154:157], v[190:193], v[52:55]
	v_mfma_f32_16x16x32_bf16 v[52:55], v[158:161], v[194:197], v[52:55]
	v_mfma_f32_16x16x32_bf16 v[44:47], v[128:131], v[198:201], v[44:47]
	v_mfma_f32_16x16x32_bf16 v[44:47], v[132:135], v[202:205], v[44:47]
	v_mfma_f32_16x16x32_bf16 v[36:39], v[154:157], v[198:201], v[36:39]
	v_mfma_f32_16x16x32_bf16 v[36:39], v[158:161], v[202:205], v[36:39]
	v_mfma_f32_16x16x32_bf16 v[28:31], v[128:131], v[206:209], v[28:31]
	v_mfma_f32_16x16x32_bf16 v[28:31], v[132:135], v[210:213], v[28:31]
	v_mfma_f32_16x16x32_bf16 v[20:23], v[154:157], v[206:209], v[20:23]
	v_mfma_f32_16x16x32_bf16 v[20:23], v[158:161], v[210:213], v[20:23]
	v_mfma_f32_16x16x32_bf16 v[12:15], v[128:131], v[214:217], v[12:15]
	v_mfma_f32_16x16x32_bf16 v[12:15], v[132:135], v[218:221], v[12:15]
	v_mfma_f32_16x16x32_bf16 v[4:7], v[154:157], v[214:217], v[4:7]
	v_mfma_f32_16x16x32_bf16 v[4:7], v[158:161], v[218:221], v[4:7]
	v_mfma_f32_16x16x32_bf16 v[56:59], v[162:165], v[190:193], v[56:59]
	v_mfma_f32_16x16x32_bf16 v[56:59], v[166:169], v[194:197], v[56:59]
	v_mfma_f32_16x16x32_bf16 v[48:51], v[182:185], v[190:193], v[48:51]
	v_mfma_f32_16x16x32_bf16 v[48:51], v[186:189], v[194:197], v[48:51]
	v_mfma_f32_16x16x32_bf16 v[40:43], v[162:165], v[198:201], v[40:43]
	v_mfma_f32_16x16x32_bf16 v[40:43], v[166:169], v[202:205], v[40:43]
	v_mfma_f32_16x16x32_bf16 v[32:35], v[182:185], v[198:201], v[32:35]
	v_mfma_f32_16x16x32_bf16 v[32:35], v[186:189], v[202:205], v[32:35]
	v_mfma_f32_16x16x32_bf16 v[24:27], v[162:165], v[206:209], v[24:27]
	v_mfma_f32_16x16x32_bf16 v[24:27], v[166:169], v[210:213], v[24:27]
	v_mfma_f32_16x16x32_bf16 v[16:19], v[182:185], v[206:209], v[16:19]
	v_mfma_f32_16x16x32_bf16 v[16:19], v[186:189], v[210:213], v[16:19]
	v_mfma_f32_16x16x32_bf16 v[8:11], v[162:165], v[214:217], v[8:11]
	s_setprio 3
	s_barrier
	v_mfma_f32_16x16x32_bf16 v[8:11], v[166:169], v[218:221], v[8:11]
	v_mfma_f32_16x16x32_bf16 v[0:3], v[182:185], v[214:217], v[0:3]
	v_mfma_f32_16x16x32_bf16 v[0:3], v[186:189], v[218:221], v[0:3]
	s_setprio 0
.Lzj_0_1:
	s_add_i32 s67, 0, 0x18000
	s_add_i32 s73, 0, 0x1c000
	v_add_u32_e32 v158, s67, v175
	v_add_u32_e32 v186, s73, v175
	ds_read_b128 v[128:131], v158
	ds_read_b128 v[132:135], v158 offset:1024
	ds_read_b128 v[154:157], v158 offset:2048
	ds_read_b128 v[158:161], v158 offset:3072
	ds_read_b128 v[162:165], v186
	ds_read_b128 v[166:169], v186 offset:1024
	ds_read_b128 v[182:185], v186 offset:2048
	ds_read_b128 v[186:189], v186 offset:3072
	s_add_u32 s68, s92, 0x40000
	s_addc_u32 s69, s93, 0
	s_mov_b32 m0, s19
	v_lshl_add_u64 v[228:229], s[68:69], 0, v[142:143]
	ds_read_b128 v[190:193], v180 offset:32768
	ds_read_b128 v[194:197], v180 offset:33792
	ds_read_b128 v[198:201], v180 offset:34816
	ds_read_b128 v[202:205], v180 offset:35840
	ds_read_b128 v[206:209], v180 offset:36864
	ds_read_b128 v[210:213], v180 offset:37888
	ds_read_b128 v[214:217], v180 offset:38912
	ds_read_b128 v[218:221], v180 offset:39936
	global_load_lds_dwordx4 v[228:229], off
	s_mov_b32 m0, s20
	v_lshl_add_u64 v[228:229], s[68:69], 0, v[138:139]
	global_load_lds_dwordx4 v[228:229], off
	s_waitcnt vmcnt(8) lgkmcnt(0)
	s_barrier
	s_setprio 1
	v_mfma_f32_16x16x32_bf16 v[124:127], v[128:131], v[190:193], v[124:127]
	v_mfma_f32_16x16x32_bf16 v[124:127], v[132:135], v[194:197], v[124:127]
	v_mfma_f32_16x16x32_bf16 v[116:119], v[154:157], v[190:193], v[116:119]
	v_mfma_f32_16x16x32_bf16 v[116:119], v[158:161], v[194:197], v[116:119]
	v_mfma_f32_16x16x32_bf16 v[108:111], v[128:131], v[198:201], v[108:111]
	v_mfma_f32_16x16x32_bf16 v[108:111], v[132:135], v[202:205], v[108:111]
	v_mfma_f32_16x16x32_bf16 v[100:103], v[154:157], v[198:201], v[100:103]
	v_mfma_f32_16x16x32_bf16 v[100:103], v[158:161], v[202:205], v[100:103]
	v_mfma_f32_16x16x32_bf16 v[92:95], v[128:131], v[206:209], v[92:95]
	v_mfma_f32_16x16x32_bf16 v[92:95], v[132:135], v[210:213], v[92:95]
	v_mfma_f32_16x16x32_bf16 v[84:87], v[154:157], v[206:209], v[84:87]
	v_mfma_f32_16x16x32_bf16 v[84:87], v[158:161], v[210:213], v[84:87]
	v_mfma_f32_16x16x32_bf16 v[76:79], v[128:131], v[214:217], v[76:79]
	v_mfma_f32_16x16x32_bf16 v[76:79], v[132:135], v[218:221], v[76:79]
	v_mfma_f32_16x16x32_bf16 v[68:71], v[154:157], v[214:217], v[68:71]
	v_mfma_f32_16x16x32_bf16 v[68:71], v[158:161], v[218:221], v[68:71]
	v_mfma_f32_16x16x32_bf16 v[120:123], v[162:165], v[190:193], v[120:123]
	v_mfma_f32_16x16x32_bf16 v[120:123], v[166:169], v[194:197], v[120:123]
	v_mfma_f32_16x16x32_bf16 v[112:115], v[182:185], v[190:193], v[112:115]
	v_mfma_f32_16x16x32_bf16 v[112:115], v[186:189], v[194:197], v[112:115]
	v_mfma_f32_16x16x32_bf16 v[104:107], v[162:165], v[198:201], v[104:107]
	v_mfma_f32_16x16x32_bf16 v[104:107], v[166:169], v[202:205], v[104:107]
	v_mfma_f32_16x16x32_bf16 v[96:99], v[182:185], v[198:201], v[96:99]
	v_mfma_f32_16x16x32_bf16 v[96:99], v[186:189], v[202:205], v[96:99]
	v_mfma_f32_16x16x32_bf16 v[88:91], v[162:165], v[206:209], v[88:91]
	v_mfma_f32_16x16x32_bf16 v[88:91], v[166:169], v[210:213], v[88:91]
	v_mfma_f32_16x16x32_bf16 v[80:83], v[182:185], v[206:209], v[80:83]
	v_mfma_f32_16x16x32_bf16 v[80:83], v[186:189], v[210:213], v[80:83]
	v_mfma_f32_16x16x32_bf16 v[72:75], v[162:165], v[214:217], v[72:75]
	s_setprio 3
	s_barrier
	v_mfma_f32_16x16x32_bf16 v[72:75], v[166:169], v[218:221], v[72:75]
	v_mfma_f32_16x16x32_bf16 v[64:67], v[182:185], v[214:217], v[64:67]
	v_mfma_f32_16x16x32_bf16 v[64:67], v[186:189], v[218:221], v[64:67]
	s_setprio 0
	s_add_i32 s67, s67, s16
	v_lshl_add_u64 v[170:171], v[170:171], 0, s[74:75]
	s_mov_b32 m0, s67
	ds_read_b128 v[190:193], v180 offset:49152
	ds_read_b128 v[194:197], v180 offset:50176
	ds_read_b128 v[198:201], v180 offset:51200
	ds_read_b128 v[202:205], v180 offset:52224
	ds_read_b128 v[206:209], v180 offset:53248
	ds_read_b128 v[210:213], v180 offset:54272
	ds_read_b128 v[214:217], v180 offset:55296
	ds_read_b128 v[218:221], v180 offset:56320
	global_load_lds_dwordx4 v[170:171], off
	s_add_i32 m0, s67, 0x2000
	s_add_u32 s68, s90, 0x40080
	v_lshl_add_u64 v[170:171], v[222:223], 0, s[74:75]
	s_addc_u32 s69, s91, 0
	s_add_i32 s67, s73, s16
	global_load_lds_dwordx4 v[170:171], off
	s_mov_b32 m0, s67
	v_lshl_add_u64 v[170:171], s[68:69], 0, v[140:141]
	global_load_lds_dwordx4 v[170:171], off
	s_add_i32 m0, s67, 0x2000
	v_lshl_add_u64 v[170:171], s[68:69], 0, v[136:137]
	global_load_lds_dwordx4 v[170:171], off
	s_mov_b32 m0, s23
	v_lshl_add_u64 v[170:171], v[224:225], 0, s[74:75]
	global_load_lds_dwordx4 v[170:171], off
	s_mov_b32 m0, s24
	v_lshl_add_u64 v[170:171], v[226:227], 0, s[74:75]
	global_load_lds_dwordx4 v[170:171], off
	s_waitcnt vmcnt(8) lgkmcnt(0)
	s_barrier
	s_setprio 1
	v_mfma_f32_16x16x32_bf16 v[60:63], v[128:131], v[190:193], v[60:63]
	v_mfma_f32_16x16x32_bf16 v[60:63], v[132:135], v[194:197], v[60:63]
	v_mfma_f32_16x16x32_bf16 v[52:55], v[154:157], v[190:193], v[52:55]
	v_mfma_f32_16x16x32_bf16 v[52:55], v[158:161], v[194:197], v[52:55]
	v_mfma_f32_16x16x32_bf16 v[44:47], v[128:131], v[198:201], v[44:47]
	v_mfma_f32_16x16x32_bf16 v[44:47], v[132:135], v[202:205], v[44:47]
	v_mfma_f32_16x16x32_bf16 v[36:39], v[154:157], v[198:201], v[36:39]
	v_mfma_f32_16x16x32_bf16 v[36:39], v[158:161], v[202:205], v[36:39]
	v_mfma_f32_16x16x32_bf16 v[28:31], v[128:131], v[206:209], v[28:31]
	v_mfma_f32_16x16x32_bf16 v[28:31], v[132:135], v[210:213], v[28:31]
	v_mfma_f32_16x16x32_bf16 v[20:23], v[154:157], v[206:209], v[20:23]
	v_mfma_f32_16x16x32_bf16 v[20:23], v[158:161], v[210:213], v[20:23]
	v_mfma_f32_16x16x32_bf16 v[12:15], v[128:131], v[214:217], v[12:15]
	v_mfma_f32_16x16x32_bf16 v[12:15], v[132:135], v[218:221], v[12:15]
	v_mfma_f32_16x16x32_bf16 v[4:7], v[154:157], v[214:217], v[4:7]
	v_mfma_f32_16x16x32_bf16 v[4:7], v[158:161], v[218:221], v[4:7]
	v_mfma_f32_16x16x32_bf16 v[56:59], v[162:165], v[190:193], v[56:59]
	v_mfma_f32_16x16x32_bf16 v[56:59], v[166:169], v[194:197], v[56:59]
	v_mfma_f32_16x16x32_bf16 v[48:51], v[182:185], v[190:193], v[48:51]
	v_mfma_f32_16x16x32_bf16 v[48:51], v[186:189], v[194:197], v[48:51]
	v_mfma_f32_16x16x32_bf16 v[40:43], v[162:165], v[198:201], v[40:43]
	v_mfma_f32_16x16x32_bf16 v[40:43], v[166:169], v[202:205], v[40:43]
	v_mfma_f32_16x16x32_bf16 v[32:35], v[182:185], v[198:201], v[32:35]
	v_mfma_f32_16x16x32_bf16 v[32:35], v[186:189], v[202:205], v[32:35]
	v_mfma_f32_16x16x32_bf16 v[24:27], v[162:165], v[206:209], v[24:27]
	v_mfma_f32_16x16x32_bf16 v[24:27], v[166:169], v[210:213], v[24:27]
	v_mfma_f32_16x16x32_bf16 v[16:19], v[182:185], v[206:209], v[16:19]
	v_mfma_f32_16x16x32_bf16 v[16:19], v[186:189], v[210:213], v[16:19]
	v_mfma_f32_16x16x32_bf16 v[8:11], v[162:165], v[214:217], v[8:11]
	s_setprio 3
	s_barrier
	v_mfma_f32_16x16x32_bf16 v[8:11], v[166:169], v[218:221], v[8:11]
	v_mfma_f32_16x16x32_bf16 v[0:3], v[182:185], v[214:217], v[0:3]
	v_mfma_f32_16x16x32_bf16 v[0:3], v[186:189], v[218:221], v[0:3]
	s_setprio 0
	s_add_i32 s66, s66, 2
	s_add_u32 s88, s88, 0x100
	s_addc_u32 s89, s89, 0
	s_add_u32 s58, s58, 0x100
	s_addc_u32 s59, s59, 0
	s_cmp_gt_u32 s66, 13
	s_cbranch_scc0 .LBB0_120
	s_branch .Lzskip_0
.Lzv_0_0:
	v_mfma_f32_16x16x32_bf16 v[124:127], v[128:131], v[190:193], 0
	v_mfma_f32_16x16x32_bf16 v[124:127], v[132:135], v[194:197], v[124:127]
	v_mfma_f32_16x16x32_bf16 v[116:119], v[154:157], v[190:193], 0
	v_mfma_f32_16x16x32_bf16 v[116:119], v[158:161], v[194:197], v[116:119]
	v_mfma_f32_16x16x32_bf16 v[108:111], v[128:131], v[198:201], 0
	v_mfma_f32_16x16x32_bf16 v[108:111], v[132:135], v[202:205], v[108:111]
	v_mfma_f32_16x16x32_bf16 v[100:103], v[154:157], v[198:201], 0
	v_mfma_f32_16x16x32_bf16 v[100:103], v[158:161], v[202:205], v[100:103]
	v_mfma_f32_16x16x32_bf16 v[92:95], v[128:131], v[206:209], 0
	v_mfma_f32_16x16x32_bf16 v[92:95], v[132:135], v[210:213], v[92:95]
	v_mfma_f32_16x16x32_bf16 v[84:87], v[154:157], v[206:209], 0
	v_mfma_f32_16x16x32_bf16 v[84:87], v[158:161], v[210:213], v[84:87]
	v_mfma_f32_16x16x32_bf16 v[76:79], v[128:131], v[214:217], 0
	v_mfma_f32_16x16x32_bf16 v[76:79], v[132:135], v[218:221], v[76:79]
	v_mfma_f32_16x16x32_bf16 v[68:71], v[154:157], v[214:217], 0
	v_mfma_f32_16x16x32_bf16 v[68:71], v[158:161], v[218:221], v[68:71]
	v_mfma_f32_16x16x32_bf16 v[120:123], v[162:165], v[190:193], 0
	v_mfma_f32_16x16x32_bf16 v[120:123], v[166:169], v[194:197], v[120:123]
	v_mfma_f32_16x16x32_bf16 v[112:115], v[182:185], v[190:193], 0
	v_mfma_f32_16x16x32_bf16 v[112:115], v[186:189], v[194:197], v[112:115]
	v_mfma_f32_16x16x32_bf16 v[104:107], v[162:165], v[198:201], 0
	v_mfma_f32_16x16x32_bf16 v[104:107], v[166:169], v[202:205], v[104:107]
	v_mfma_f32_16x16x32_bf16 v[96:99], v[182:185], v[198:201], 0
	v_mfma_f32_16x16x32_bf16 v[96:99], v[186:189], v[202:205], v[96:99]
	v_mfma_f32_16x16x32_bf16 v[88:91], v[162:165], v[206:209], 0
	v_mfma_f32_16x16x32_bf16 v[88:91], v[166:169], v[210:213], v[88:91]
	v_mfma_f32_16x16x32_bf16 v[80:83], v[182:185], v[206:209], 0
	v_mfma_f32_16x16x32_bf16 v[80:83], v[186:189], v[210:213], v[80:83]
	v_mfma_f32_16x16x32_bf16 v[72:75], v[162:165], v[214:217], 0
	s_setprio 3
	s_barrier
	v_mfma_f32_16x16x32_bf16 v[72:75], v[166:169], v[218:221], v[72:75]
	v_mfma_f32_16x16x32_bf16 v[64:67], v[182:185], v[214:217], 0
	v_mfma_f32_16x16x32_bf16 v[64:67], v[186:189], v[218:221], v[64:67]
	s_setprio 0
	s_branch .Lzj_0_0
.Lzv_0_1:
	v_mfma_f32_16x16x32_bf16 v[60:63], v[128:131], v[190:193], 0
	v_mfma_f32_16x16x32_bf16 v[60:63], v[132:135], v[194:197], v[60:63]
	v_mfma_f32_16x16x32_bf16 v[52:55], v[154:157], v[190:193], 0
	v_mfma_f32_16x16x32_bf16 v[52:55], v[158:161], v[194:197], v[52:55]
	v_mfma_f32_16x16x32_bf16 v[44:47], v[128:131], v[198:201], 0
	v_mfma_f32_16x16x32_bf16 v[44:47], v[132:135], v[202:205], v[44:47]
	v_mfma_f32_16x16x32_bf16 v[36:39], v[154:157], v[198:201], 0
	v_mfma_f32_16x16x32_bf16 v[36:39], v[158:161], v[202:205], v[36:39]
	v_mfma_f32_16x16x32_bf16 v[28:31], v[128:131], v[206:209], 0
	v_mfma_f32_16x16x32_bf16 v[28:31], v[132:135], v[210:213], v[28:31]
	v_mfma_f32_16x16x32_bf16 v[20:23], v[154:157], v[206:209], 0
	v_mfma_f32_16x16x32_bf16 v[20:23], v[158:161], v[210:213], v[20:23]
	v_mfma_f32_16x16x32_bf16 v[12:15], v[128:131], v[214:217], 0
	v_mfma_f32_16x16x32_bf16 v[12:15], v[132:135], v[218:221], v[12:15]
	v_mfma_f32_16x16x32_bf16 v[4:7], v[154:157], v[214:217], 0
	v_mfma_f32_16x16x32_bf16 v[4:7], v[158:161], v[218:221], v[4:7]
	v_mfma_f32_16x16x32_bf16 v[56:59], v[162:165], v[190:193], 0
	v_mfma_f32_16x16x32_bf16 v[56:59], v[166:169], v[194:197], v[56:59]
	v_mfma_f32_16x16x32_bf16 v[48:51], v[182:185], v[190:193], 0
	v_mfma_f32_16x16x32_bf16 v[48:51], v[186:189], v[194:197], v[48:51]
	v_mfma_f32_16x16x32_bf16 v[40:43], v[162:165], v[198:201], 0
	v_mfma_f32_16x16x32_bf16 v[40:43], v[166:169], v[202:205], v[40:43]
	v_mfma_f32_16x16x32_bf16 v[32:35], v[182:185], v[198:201], 0
	v_mfma_f32_16x16x32_bf16 v[32:35], v[186:189], v[202:205], v[32:35]
	v_mfma_f32_16x16x32_bf16 v[24:27], v[162:165], v[206:209], 0
	v_mfma_f32_16x16x32_bf16 v[24:27], v[166:169], v[210:213], v[24:27]
	v_mfma_f32_16x16x32_bf16 v[16:19], v[182:185], v[206:209], 0
	v_mfma_f32_16x16x32_bf16 v[16:19], v[186:189], v[210:213], v[16:19]
	v_mfma_f32_16x16x32_bf16 v[8:11], v[162:165], v[214:217], 0
	s_setprio 3
	s_barrier
	v_mfma_f32_16x16x32_bf16 v[8:11], v[166:169], v[218:221], v[8:11]
	v_mfma_f32_16x16x32_bf16 v[0:3], v[182:185], v[214:217], 0
	v_mfma_f32_16x16x32_bf16 v[0:3], v[186:189], v[218:221], v[0:3]
	s_setprio 0
	s_branch .Lzj_0_1

.LBB0_272:
	ds_read_b128 v[120:123], v245
	ds_read_b128 v[124:127], v245 offset:1024
	ds_read_b128 v[128:131], v245 offset:2048
	ds_read_b128 v[132:135], v245 offset:3072
	ds_read_b128 v[144:147], v246
	ds_read_b128 v[148:151], v246 offset:1024
	ds_read_b128 v[152:155], v246 offset:2048
	ds_read_b128 v[156:159], v246 offset:3072
	s_add_u32 s59, s86, 0xfff50080
	s_addc_u32 s66, s87, -1
	s_cmp_eq_u32 s58, 40
	s_cselect_b32 s91, s11, s66
	s_cselect_b32 s90, s10, s59
	s_cselect_b32 s89, s85, s57
	s_cselect_b32 s88, s84, s56
	v_lshl_add_u64 v[204:205], s[86:87], 0, v[200:201]
	s_add_i32 m0, s16, 0xc000
	ds_read_b128 v[160:163], v247
	ds_read_b128 v[164:167], v247 offset:1024
	ds_read_b128 v[168:171], v247 offset:2048
	ds_read_b128 v[172:175], v247 offset:3072
	ds_read_b128 v[176:179], v247 offset:4096
	ds_read_b128 v[180:183], v247 offset:5120
	ds_read_b128 v[184:187], v247 offset:6144
	ds_read_b128 v[188:191], v247 offset:7168
	global_load_lds_dwordx4 v[204:205], off
	s_add_i32 m0, s16, 0xe000
	v_lshl_add_u64 v[204:205], s[86:87], 0, v[202:203]
	global_load_lds_dwordx4 v[204:205], off
	s_cmp_eq_u32 s58, -2
	s_waitcnt vmcnt(8) lgkmcnt(0)
	s_barrier
	s_setprio 1
	s_cbranch_scc1 .Lzv_1_0
	v_mfma_f32_16x16x32_bf16 v[140:143], v[120:123], v[160:163], v[140:143]
	v_mfma_f32_16x16x32_bf16 v[140:143], v[124:127], v[164:167], v[140:143]
	v_mfma_f32_16x16x32_bf16 v[136:139], v[128:131], v[160:163], v[136:139]
	v_mfma_f32_16x16x32_bf16 v[136:139], v[132:135], v[164:167], v[136:139]
	v_mfma_f32_16x16x32_bf16 v[108:111], v[120:123], v[168:171], v[108:111]
	v_mfma_f32_16x16x32_bf16 v[108:111], v[124:127], v[172:175], v[108:111]
	v_mfma_f32_16x16x32_bf16 v[104:107], v[128:131], v[168:171], v[104:107]
	v_mfma_f32_16x16x32_bf16 v[104:107], v[132:135], v[172:175], v[104:107]
	v_mfma_f32_16x16x32_bf16 v[92:95], v[120:123], v[176:179], v[92:95]
	v_mfma_f32_16x16x32_bf16 v[92:95], v[124:127], v[180:183], v[92:95]
	v_mfma_f32_16x16x32_bf16 v[88:91], v[128:131], v[176:179], v[88:91]
	v_mfma_f32_16x16x32_bf16 v[88:91], v[132:135], v[180:183], v[88:91]
	v_mfma_f32_16x16x32_bf16 v[76:79], v[120:123], v[184:187], v[76:79]
	v_mfma_f32_16x16x32_bf16 v[76:79], v[124:127], v[188:191], v[76:79]
	v_mfma_f32_16x16x32_bf16 v[72:75], v[128:131], v[184:187], v[72:75]
	v_mfma_f32_16x16x32_bf16 v[72:75], v[132:135], v[188:191], v[72:75]
	v_mfma_f32_16x16x32_bf16 v[116:119], v[144:147], v[160:163], v[116:119]
	v_mfma_f32_16x16x32_bf16 v[116:119], v[148:151], v[164:167], v[116:119]
	v_mfma_f32_16x16x32_bf16 v[112:115], v[152:155], v[160:163], v[112:115]
	v_mfma_f32_16x16x32_bf16 v[112:115], v[156:159], v[164:167], v[112:115]
	v_mfma_f32_16x16x32_bf16 v[100:103], v[144:147], v[168:171], v[100:103]
	v_mfma_f32_16x16x32_bf16 v[100:103], v[148:151], v[172:175], v[100:103]
	v_mfma_f32_16x16x32_bf16 v[96:99], v[152:155], v[168:171], v[96:99]
	v_mfma_f32_16x16x32_bf16 v[96:99], v[156:159], v[172:175], v[96:99]
	v_mfma_f32_16x16x32_bf16 v[84:87], v[144:147], v[176:179], v[84:87]
	v_mfma_f32_16x16x32_bf16 v[84:87], v[148:151], v[180:183], v[84:87]
	v_mfma_f32_16x16x32_bf16 v[80:83], v[152:155], v[176:179], v[80:83]
	v_mfma_f32_16x16x32_bf16 v[80:83], v[156:159], v[180:183], v[80:83]
	v_mfma_f32_16x16x32_bf16 v[68:71], v[144:147], v[184:187], v[68:71]
	s_setprio 3
	s_barrier
	v_mfma_f32_16x16x32_bf16 v[68:71], v[148:151], v[188:191], v[68:71]
	v_mfma_f32_16x16x32_bf16 v[64:67], v[152:155], v[184:187], v[64:67]
	v_mfma_f32_16x16x32_bf16 v[64:67], v[156:159], v[188:191], v[64:67]
	s_setprio 0
.Lzj_1_0:
	s_add_i32 s59, s26, s15
	v_lshl_add_u64 v[204:205], s[88:89], 0, v[194:195]
	s_mov_b32 m0, s59
	ds_read_b128 v[160:163], v247 offset:16384
	ds_read_b128 v[164:167], v247 offset:17408
	ds_read_b128 v[168:171], v247 offset:18432
	ds_read_b128 v[172:175], v247 offset:19456
	ds_read_b128 v[176:179], v247 offset:20480
	ds_read_b128 v[180:183], v247 offset:21504
	ds_read_b128 v[184:187], v247 offset:22528
	ds_read_b128 v[188:191], v247 offset:23552
	global_load_lds_dwordx4 v[204:205], off
	s_add_i32 m0, s59, 0x2000
	s_add_u32 s66, s88, 0xb0000
	v_lshl_add_u64 v[206:207], s[88:89], 0, v[198:199]
	s_addc_u32 s67, s89, 0
	s_add_i32 s59, s27, s15
	global_load_lds_dwordx4 v[206:207], off
	v_lshl_add_u64 v[208:209], s[66:67], 0, v[194:195]
	s_mov_b32 m0, s59
	global_load_lds_dwordx4 v[208:209], off
	s_add_i32 m0, s59, 0x2000
	v_lshl_add_u64 v[208:209], s[66:67], 0, v[198:199]
	global_load_lds_dwordx4 v[208:209], off
	s_mov_b32 m0, s16
	v_lshl_add_u64 v[208:209], s[90:91], 0, v[192:193]
	global_load_lds_dwordx4 v[208:209], off
	s_mov_b32 m0, s17
	v_lshl_add_u64 v[210:211], s[90:91], 0, v[196:197]
	global_load_lds_dwordx4 v[210:211], off
	s_cmp_eq_u32 s58, -2
	s_waitcnt vmcnt(8) lgkmcnt(0)
	s_barrier
	s_setprio 1
	s_cbranch_scc1 .Lzv_1_1
	v_mfma_f32_16x16x32_bf16 v[60:63], v[120:123], v[160:163], v[60:63]
	v_mfma_f32_16x16x32_bf16 v[60:63], v[124:127], v[164:167], v[60:63]
	v_mfma_f32_16x16x32_bf16 v[56:59], v[128:131], v[160:163], v[56:59]
	v_mfma_f32_16x16x32_bf16 v[56:59], v[132:135], v[164:167], v[56:59]
	v_mfma_f32_16x16x32_bf16 v[44:47], v[120:123], v[168:171], v[44:47]
	v_mfma_f32_16x16x32_bf16 v[44:47], v[124:127], v[172:175], v[44:47]
	v_mfma_f32_16x16x32_bf16 v[40:43], v[128:131], v[168:171], v[40:43]
	v_mfma_f32_16x16x32_bf16 v[40:43], v[132:135], v[172:175], v[40:43]
	v_mfma_f32_16x16x32_bf16 v[28:31], v[120:123], v[176:179], v[28:31]
	v_mfma_f32_16x16x32_bf16 v[28:31], v[124:127], v[180:183], v[28:31]
	v_mfma_f32_16x16x32_bf16 v[24:27], v[128:131], v[176:179], v[24:27]
	v_mfma_f32_16x16x32_bf16 v[24:27], v[132:135], v[180:183], v[24:27]
	v_mfma_f32_16x16x32_bf16 v[12:15], v[120:123], v[184:187], v[12:15]
	v_mfma_f32_16x16x32_bf16 v[12:15], v[124:127], v[188:191], v[12:15]
	v_mfma_f32_16x16x32_bf16 v[8:11], v[128:131], v[184:187], v[8:11]
	v_mfma_f32_16x16x32_bf16 v[8:11], v[132:135], v[188:191], v[8:11]
	v_mfma_f32_16x16x32_bf16 v[52:55], v[144:147], v[160:163], v[52:55]
	v_mfma_f32_16x16x32_bf16 v[52:55], v[148:151], v[164:167], v[52:55]
	v_mfma_f32_16x16x32_bf16 v[48:51], v[152:155], v[160:163], v[48:51]
	v_mfma_f32_16x16x32_bf16 v[48:51], v[156:159], v[164:167], v[48:51]
	v_mfma_f32_16x16x32_bf16 v[36:39], v[144:147], v[168:171], v[36:39]
	v_mfma_f32_16x16x32_bf16 v[36:39], v[148:151], v[172:175], v[36:39]
	v_mfma_f32_16x16x32_bf16 v[32:35], v[152:155], v[168:171], v[32:35]
	v_mfma_f32_16x16x32_bf16 v[32:35], v[156:159], v[172:175], v[32:35]
	v_mfma_f32_16x16x32_bf16 v[20:23], v[144:147], v[176:179], v[20:23]
	v_mfma_f32_16x16x32_bf16 v[20:23], v[148:151], v[180:183], v[20:23]
	v_mfma_f32_16x16x32_bf16 v[16:19], v[152:155], v[176:179], v[16:19]
	v_mfma_f32_16x16x32_bf16 v[16:19], v[156:159], v[180:183], v[16:19]
	v_mfma_f32_16x16x32_bf16 v[4:7], v[144:147], v[184:187], v[4:7]
	s_setprio 3
	s_barrier
	v_mfma_f32_16x16x32_bf16 v[4:7], v[148:151], v[188:191], v[4:7]
	v_mfma_f32_16x16x32_bf16 v[0:3], v[152:155], v[184:187], v[0:3]
	v_mfma_f32_16x16x32_bf16 v[0:3], v[156:159], v[188:191], v[0:3]
	s_setprio 0
.Lzj_1_1:
	s_add_i32 s59, 0, 0x18000
	s_add_i32 s68, 0, 0x1c000
	v_add_u32_e32 v132, s59, v243
	v_add_u32_e32 v156, s68, v243
	ds_read_b128 v[120:123], v132
	ds_read_b128 v[124:127], v132 offset:1024
	ds_read_b128 v[128:131], v132 offset:2048
	ds_read_b128 v[132:135], v132 offset:3072
	ds_read_b128 v[144:147], v156
	ds_read_b128 v[148:151], v156 offset:1024
	ds_read_b128 v[152:155], v156 offset:2048
	ds_read_b128 v[156:159], v156 offset:3072
	s_add_u32 s66, s90, 0xb0000
	s_addc_u32 s67, s91, 0
	s_mov_b32 m0, s18
	v_lshl_add_u64 v[212:213], s[66:67], 0, v[192:193]
	ds_read_b128 v[160:163], v247 offset:32768
	ds_read_b128 v[164:167], v247 offset:33792
	ds_read_b128 v[168:171], v247 offset:34816
	ds_read_b128 v[172:175], v247 offset:35840
	ds_read_b128 v[176:179], v247 offset:36864
	ds_read_b128 v[180:183], v247 offset:37888
	ds_read_b128 v[184:187], v247 offset:38912
	ds_read_b128 v[188:191], v247 offset:39936
	global_load_lds_dwordx4 v[212:213], off
	s_mov_b32 m0, s19
	v_lshl_add_u64 v[212:213], s[66:67], 0, v[196:197]
	global_load_lds_dwordx4 v[212:213], off
	s_waitcnt vmcnt(8) lgkmcnt(0)
	s_barrier
	s_setprio 1
	v_mfma_f32_16x16x32_bf16 v[140:143], v[120:123], v[160:163], v[140:143]
	v_mfma_f32_16x16x32_bf16 v[140:143], v[124:127], v[164:167], v[140:143]
	v_mfma_f32_16x16x32_bf16 v[136:139], v[128:131], v[160:163], v[136:139]
	v_mfma_f32_16x16x32_bf16 v[136:139], v[132:135], v[164:167], v[136:139]
	v_mfma_f32_16x16x32_bf16 v[108:111], v[120:123], v[168:171], v[108:111]
	v_mfma_f32_16x16x32_bf16 v[108:111], v[124:127], v[172:175], v[108:111]
	v_mfma_f32_16x16x32_bf16 v[104:107], v[128:131], v[168:171], v[104:107]
	v_mfma_f32_16x16x32_bf16 v[104:107], v[132:135], v[172:175], v[104:107]
	v_mfma_f32_16x16x32_bf16 v[92:95], v[120:123], v[176:179], v[92:95]
	v_mfma_f32_16x16x32_bf16 v[92:95], v[124:127], v[180:183], v[92:95]
	v_mfma_f32_16x16x32_bf16 v[88:91], v[128:131], v[176:179], v[88:91]
	v_mfma_f32_16x16x32_bf16 v[88:91], v[132:135], v[180:183], v[88:91]
	v_mfma_f32_16x16x32_bf16 v[76:79], v[120:123], v[184:187], v[76:79]
	v_mfma_f32_16x16x32_bf16 v[76:79], v[124:127], v[188:191], v[76:79]
	v_mfma_f32_16x16x32_bf16 v[72:75], v[128:131], v[184:187], v[72:75]
	v_mfma_f32_16x16x32_bf16 v[72:75], v[132:135], v[188:191], v[72:75]
	v_mfma_f32_16x16x32_bf16 v[116:119], v[144:147], v[160:163], v[116:119]
	v_mfma_f32_16x16x32_bf16 v[116:119], v[148:151], v[164:167], v[116:119]
	v_mfma_f32_16x16x32_bf16 v[112:115], v[152:155], v[160:163], v[112:115]
	v_mfma_f32_16x16x32_bf16 v[112:115], v[156:159], v[164:167], v[112:115]
	v_mfma_f32_16x16x32_bf16 v[100:103], v[144:147], v[168:171], v[100:103]
	v_mfma_f32_16x16x32_bf16 v[100:103], v[148:151], v[172:175], v[100:103]
	v_mfma_f32_16x16x32_bf16 v[96:99], v[152:155], v[168:171], v[96:99]
	v_mfma_f32_16x16x32_bf16 v[96:99], v[156:159], v[172:175], v[96:99]
	v_mfma_f32_16x16x32_bf16 v[84:87], v[144:147], v[176:179], v[84:87]
	v_mfma_f32_16x16x32_bf16 v[84:87], v[148:151], v[180:183], v[84:87]
	v_mfma_f32_16x16x32_bf16 v[80:83], v[152:155], v[176:179], v[80:83]
	v_mfma_f32_16x16x32_bf16 v[80:83], v[156:159], v[180:183], v[80:83]
	v_mfma_f32_16x16x32_bf16 v[68:71], v[144:147], v[184:187], v[68:71]
	s_setprio 3
	s_barrier
	v_mfma_f32_16x16x32_bf16 v[68:71], v[148:151], v[188:191], v[68:71]
	v_mfma_f32_16x16x32_bf16 v[64:67], v[152:155], v[184:187], v[64:67]
	v_mfma_f32_16x16x32_bf16 v[64:67], v[156:159], v[188:191], v[64:67]
	s_setprio 0
	s_add_i32 s59, s59, s15
	v_lshl_add_u64 v[204:205], v[204:205], 0, s[80:81]
	s_mov_b32 m0, s59
	ds_read_b128 v[160:163], v247 offset:49152
	ds_read_b128 v[164:167], v247 offset:50176
	ds_read_b128 v[168:171], v247 offset:51200
	ds_read_b128 v[172:175], v247 offset:52224
	ds_read_b128 v[176:179], v247 offset:53248
	ds_read_b128 v[180:183], v247 offset:54272
	ds_read_b128 v[184:187], v247 offset:55296
	ds_read_b128 v[188:191], v247 offset:56320
	global_load_lds_dwordx4 v[204:205], off
	s_add_i32 m0, s59, 0x2000
	s_add_u32 s66, s88, 0xb0080
	v_lshl_add_u64 v[204:205], v[206:207], 0, s[80:81]
	s_addc_u32 s67, s89, 0
	s_add_i32 s59, s68, s15
	global_load_lds_dwordx4 v[204:205], off
	s_mov_b32 m0, s59
	v_lshl_add_u64 v[204:205], s[66:67], 0, v[194:195]
	global_load_lds_dwordx4 v[204:205], off
	s_add_i32 m0, s59, 0x2000
	v_lshl_add_u64 v[204:205], s[66:67], 0, v[198:199]
	global_load_lds_dwordx4 v[204:205], off
	s_mov_b32 m0, s21
	v_lshl_add_u64 v[204:205], v[208:209], 0, s[80:81]
	global_load_lds_dwordx4 v[204:205], off
	s_mov_b32 m0, s22
	v_lshl_add_u64 v[204:205], v[210:211], 0, s[80:81]
	global_load_lds_dwordx4 v[204:205], off
	s_waitcnt vmcnt(8) lgkmcnt(0)
	s_barrier
	s_setprio 1
	v_mfma_f32_16x16x32_bf16 v[60:63], v[120:123], v[160:163], v[60:63]
	v_mfma_f32_16x16x32_bf16 v[60:63], v[124:127], v[164:167], v[60:63]
	v_mfma_f32_16x16x32_bf16 v[56:59], v[128:131], v[160:163], v[56:59]
	v_mfma_f32_16x16x32_bf16 v[56:59], v[132:135], v[164:167], v[56:59]
	v_mfma_f32_16x16x32_bf16 v[44:47], v[120:123], v[168:171], v[44:47]
	v_mfma_f32_16x16x32_bf16 v[44:47], v[124:127], v[172:175], v[44:47]
	v_mfma_f32_16x16x32_bf16 v[40:43], v[128:131], v[168:171], v[40:43]
	v_mfma_f32_16x16x32_bf16 v[40:43], v[132:135], v[172:175], v[40:43]
	v_mfma_f32_16x16x32_bf16 v[28:31], v[120:123], v[176:179], v[28:31]
	v_mfma_f32_16x16x32_bf16 v[28:31], v[124:127], v[180:183], v[28:31]
	v_mfma_f32_16x16x32_bf16 v[24:27], v[128:131], v[176:179], v[24:27]
	v_mfma_f32_16x16x32_bf16 v[24:27], v[132:135], v[180:183], v[24:27]
	v_mfma_f32_16x16x32_bf16 v[12:15], v[120:123], v[184:187], v[12:15]
	v_mfma_f32_16x16x32_bf16 v[12:15], v[124:127], v[188:191], v[12:15]
	v_mfma_f32_16x16x32_bf16 v[8:11], v[128:131], v[184:187], v[8:11]
	v_mfma_f32_16x16x32_bf16 v[8:11], v[132:135], v[188:191], v[8:11]
	v_mfma_f32_16x16x32_bf16 v[52:55], v[144:147], v[160:163], v[52:55]
	v_mfma_f32_16x16x32_bf16 v[52:55], v[148:151], v[164:167], v[52:55]
	v_mfma_f32_16x16x32_bf16 v[48:51], v[152:155], v[160:163], v[48:51]
	v_mfma_f32_16x16x32_bf16 v[48:51], v[156:159], v[164:167], v[48:51]
	v_mfma_f32_16x16x32_bf16 v[36:39], v[144:147], v[168:171], v[36:39]
	v_mfma_f32_16x16x32_bf16 v[36:39], v[148:151], v[172:175], v[36:39]
	v_mfma_f32_16x16x32_bf16 v[32:35], v[152:155], v[168:171], v[32:35]
	v_mfma_f32_16x16x32_bf16 v[32:35], v[156:159], v[172:175], v[32:35]
	v_mfma_f32_16x16x32_bf16 v[20:23], v[144:147], v[176:179], v[20:23]
	v_mfma_f32_16x16x32_bf16 v[20:23], v[148:151], v[180:183], v[20:23]
	v_mfma_f32_16x16x32_bf16 v[16:19], v[152:155], v[176:179], v[16:19]
	v_mfma_f32_16x16x32_bf16 v[16:19], v[156:159], v[180:183], v[16:19]
	v_mfma_f32_16x16x32_bf16 v[4:7], v[144:147], v[184:187], v[4:7]
	s_setprio 3
	s_barrier
	v_mfma_f32_16x16x32_bf16 v[4:7], v[148:151], v[188:191], v[4:7]
	v_mfma_f32_16x16x32_bf16 v[0:3], v[152:155], v[184:187], v[0:3]
	v_mfma_f32_16x16x32_bf16 v[0:3], v[156:159], v[188:191], v[0:3]
	s_setprio 0
	s_add_i32 s58, s58, 2
	s_add_u32 s86, s86, 0x100
	s_addc_u32 s87, s87, 0
	s_add_u32 s56, s56, 0x100
	s_addc_u32 s57, s57, 0
	s_cmp_gt_u32 s58, 41
	s_cbranch_scc0 .LBB0_272
	s_branch .Lzskip_1
.Lzv_1_0:
	v_mfma_f32_16x16x32_bf16 v[140:143], v[120:123], v[160:163], 0
	v_mfma_f32_16x16x32_bf16 v[140:143], v[124:127], v[164:167], v[140:143]
	v_mfma_f32_16x16x32_bf16 v[136:139], v[128:131], v[160:163], 0
	v_mfma_f32_16x16x32_bf16 v[136:139], v[132:135], v[164:167], v[136:139]
	v_mfma_f32_16x16x32_bf16 v[108:111], v[120:123], v[168:171], 0
	v_mfma_f32_16x16x32_bf16 v[108:111], v[124:127], v[172:175], v[108:111]
	v_mfma_f32_16x16x32_bf16 v[104:107], v[128:131], v[168:171], 0
	v_mfma_f32_16x16x32_bf16 v[104:107], v[132:135], v[172:175], v[104:107]
	v_mfma_f32_16x16x32_bf16 v[92:95], v[120:123], v[176:179], 0
	v_mfma_f32_16x16x32_bf16 v[92:95], v[124:127], v[180:183], v[92:95]
	v_mfma_f32_16x16x32_bf16 v[88:91], v[128:131], v[176:179], 0
	v_mfma_f32_16x16x32_bf16 v[88:91], v[132:135], v[180:183], v[88:91]
	v_mfma_f32_16x16x32_bf16 v[76:79], v[120:123], v[184:187], 0
	v_mfma_f32_16x16x32_bf16 v[76:79], v[124:127], v[188:191], v[76:79]
	v_mfma_f32_16x16x32_bf16 v[72:75], v[128:131], v[184:187], 0
	v_mfma_f32_16x16x32_bf16 v[72:75], v[132:135], v[188:191], v[72:75]
	v_mfma_f32_16x16x32_bf16 v[116:119], v[144:147], v[160:163], 0
	v_mfma_f32_16x16x32_bf16 v[116:119], v[148:151], v[164:167], v[116:119]
	v_mfma_f32_16x16x32_bf16 v[112:115], v[152:155], v[160:163], 0
	v_mfma_f32_16x16x32_bf16 v[112:115], v[156:159], v[164:167], v[112:115]
	v_mfma_f32_16x16x32_bf16 v[100:103], v[144:147], v[168:171], 0
	v_mfma_f32_16x16x32_bf16 v[100:103], v[148:151], v[172:175], v[100:103]
	v_mfma_f32_16x16x32_bf16 v[96:99], v[152:155], v[168:171], 0
	v_mfma_f32_16x16x32_bf16 v[96:99], v[156:159], v[172:175], v[96:99]
	v_mfma_f32_16x16x32_bf16 v[84:87], v[144:147], v[176:179], 0
	v_mfma_f32_16x16x32_bf16 v[84:87], v[148:151], v[180:183], v[84:87]
	v_mfma_f32_16x16x32_bf16 v[80:83], v[152:155], v[176:179], 0
	v_mfma_f32_16x16x32_bf16 v[80:83], v[156:159], v[180:183], v[80:83]
	v_mfma_f32_16x16x32_bf16 v[68:71], v[144:147], v[184:187], 0
	s_setprio 3
	s_barrier
	v_mfma_f32_16x16x32_bf16 v[68:71], v[148:151], v[188:191], v[68:71]
	v_mfma_f32_16x16x32_bf16 v[64:67], v[152:155], v[184:187], 0
	v_mfma_f32_16x16x32_bf16 v[64:67], v[156:159], v[188:191], v[64:67]
	s_setprio 0
	s_branch .Lzj_1_0
.Lzv_1_1:
	v_mfma_f32_16x16x32_bf16 v[60:63], v[120:123], v[160:163], 0
	v_mfma_f32_16x16x32_bf16 v[60:63], v[124:127], v[164:167], v[60:63]
	v_mfma_f32_16x16x32_bf16 v[56:59], v[128:131], v[160:163], 0
	v_mfma_f32_16x16x32_bf16 v[56:59], v[132:135], v[164:167], v[56:59]
	v_mfma_f32_16x16x32_bf16 v[44:47], v[120:123], v[168:171], 0
	v_mfma_f32_16x16x32_bf16 v[44:47], v[124:127], v[172:175], v[44:47]
	v_mfma_f32_16x16x32_bf16 v[40:43], v[128:131], v[168:171], 0
	v_mfma_f32_16x16x32_bf16 v[40:43], v[132:135], v[172:175], v[40:43]
	v_mfma_f32_16x16x32_bf16 v[28:31], v[120:123], v[176:179], 0
	v_mfma_f32_16x16x32_bf16 v[28:31], v[124:127], v[180:183], v[28:31]
	v_mfma_f32_16x16x32_bf16 v[24:27], v[128:131], v[176:179], 0
	v_mfma_f32_16x16x32_bf16 v[24:27], v[132:135], v[180:183], v[24:27]
	v_mfma_f32_16x16x32_bf16 v[12:15], v[120:123], v[184:187], 0
	v_mfma_f32_16x16x32_bf16 v[12:15], v[124:127], v[188:191], v[12:15]
	v_mfma_f32_16x16x32_bf16 v[8:11], v[128:131], v[184:187], 0
	v_mfma_f32_16x16x32_bf16 v[8:11], v[132:135], v[188:191], v[8:11]
	v_mfma_f32_16x16x32_bf16 v[52:55], v[144:147], v[160:163], 0
	v_mfma_f32_16x16x32_bf16 v[52:55], v[148:151], v[164:167], v[52:55]
	v_mfma_f32_16x16x32_bf16 v[48:51], v[152:155], v[160:163], 0
	v_mfma_f32_16x16x32_bf16 v[48:51], v[156:159], v[164:167], v[48:51]
	v_mfma_f32_16x16x32_bf16 v[36:39], v[144:147], v[168:171], 0
	v_mfma_f32_16x16x32_bf16 v[36:39], v[148:151], v[172:175], v[36:39]
	v_mfma_f32_16x16x32_bf16 v[32:35], v[152:155], v[168:171], 0
	v_mfma_f32_16x16x32_bf16 v[32:35], v[156:159], v[172:175], v[32:35]
	v_mfma_f32_16x16x32_bf16 v[20:23], v[144:147], v[176:179], 0
	v_mfma_f32_16x16x32_bf16 v[20:23], v[148:151], v[180:183], v[20:23]
	v_mfma_f32_16x16x32_bf16 v[16:19], v[152:155], v[176:179], 0
	v_mfma_f32_16x16x32_bf16 v[16:19], v[156:159], v[180:183], v[16:19]
	v_mfma_f32_16x16x32_bf16 v[4:7], v[144:147], v[184:187], 0
	s_setprio 3
	s_barrier
	v_mfma_f32_16x16x32_bf16 v[4:7], v[148:151], v[188:191], v[4:7]
	v_mfma_f32_16x16x32_bf16 v[0:3], v[152:155], v[184:187], 0
	v_mfma_f32_16x16x32_bf16 v[0:3], v[156:159], v[188:191], v[0:3]
	s_setprio 0
	s_branch .Lzj_1_1

.LBB0_429:
	ds_read_b128 v[128:131], v203
	ds_read_b128 v[132:135], v203 offset:1024
	ds_read_b128 v[136:139], v203 offset:2048
	ds_read_b128 v[164:167], v203 offset:3072
	ds_read_b128 v[168:171], v204
	ds_read_b128 v[172:175], v204 offset:1024
	ds_read_b128 v[176:179], v204 offset:2048
	ds_read_b128 v[180:183], v204 offset:3072
	s_add_u32 s6, s88, 0xfffc0080
	s_addc_u32 s7, s89, -1
	s_cmp_eq_u32 s21, 12
	s_cselect_b32 vcc_hi, s15, s7
	s_cselect_b32 vcc_lo, s16, s6
	s_cselect_b32 s7, s17, s20
	s_cselect_b32 s6, s18, s19
	v_lshl_add_u64 v[196:197], s[88:89], 0, v[156:157]
	s_add_i32 m0, s58, 0xc000
	ds_read_b128 v[184:187], v205
	ds_read_b128 v[188:191], v205 offset:1024
	ds_read_b128 v[192:195], v205 offset:2048
	ds_read_b128 v[212:215], v205 offset:3072
	ds_read_b128 v[216:219], v205 offset:4096
	ds_read_b128 v[220:223], v205 offset:5120
	ds_read_b128 v[224:227], v205 offset:6144
	ds_read_b128 v[228:231], v205 offset:7168
	global_load_lds_dwordx4 v[196:197], off
	s_add_i32 m0, s58, 0xe000
	v_lshl_add_u64 v[196:197], s[88:89], 0, v[158:159]
	global_load_lds_dwordx4 v[196:197], off
	s_cmp_eq_u32 s21, -2
	s_waitcnt vmcnt(8) lgkmcnt(0)
	s_barrier
	s_setprio 1
	s_cbranch_scc1 .Lzv_2_0
	v_mfma_f32_16x16x32_bf16 v[124:127], v[128:131], v[184:187], v[124:127]
	v_mfma_f32_16x16x32_bf16 v[124:127], v[132:135], v[188:191], v[124:127]
	v_mfma_f32_16x16x32_bf16 v[116:119], v[136:139], v[184:187], v[116:119]
	v_mfma_f32_16x16x32_bf16 v[116:119], v[164:167], v[188:191], v[116:119]
	v_mfma_f32_16x16x32_bf16 v[108:111], v[128:131], v[192:195], v[108:111]
	v_mfma_f32_16x16x32_bf16 v[108:111], v[132:135], v[212:215], v[108:111]
	v_mfma_f32_16x16x32_bf16 v[100:103], v[136:139], v[192:195], v[100:103]
	v_mfma_f32_16x16x32_bf16 v[100:103], v[164:167], v[212:215], v[100:103]
	v_mfma_f32_16x16x32_bf16 v[92:95], v[128:131], v[216:219], v[92:95]
	v_mfma_f32_16x16x32_bf16 v[92:95], v[132:135], v[220:223], v[92:95]
	v_mfma_f32_16x16x32_bf16 v[84:87], v[136:139], v[216:219], v[84:87]
	v_mfma_f32_16x16x32_bf16 v[84:87], v[164:167], v[220:223], v[84:87]
	v_mfma_f32_16x16x32_bf16 v[76:79], v[128:131], v[224:227], v[76:79]
	v_mfma_f32_16x16x32_bf16 v[76:79], v[132:135], v[228:231], v[76:79]
	v_mfma_f32_16x16x32_bf16 v[68:71], v[136:139], v[224:227], v[68:71]
	v_mfma_f32_16x16x32_bf16 v[68:71], v[164:167], v[228:231], v[68:71]
	v_mfma_f32_16x16x32_bf16 v[120:123], v[168:171], v[184:187], v[120:123]
	v_mfma_f32_16x16x32_bf16 v[120:123], v[172:175], v[188:191], v[120:123]
	v_mfma_f32_16x16x32_bf16 v[112:115], v[176:179], v[184:187], v[112:115]
	v_mfma_f32_16x16x32_bf16 v[112:115], v[180:183], v[188:191], v[112:115]
	v_mfma_f32_16x16x32_bf16 v[104:107], v[168:171], v[192:195], v[104:107]
	v_mfma_f32_16x16x32_bf16 v[104:107], v[172:175], v[212:215], v[104:107]
	v_mfma_f32_16x16x32_bf16 v[96:99], v[176:179], v[192:195], v[96:99]
	v_mfma_f32_16x16x32_bf16 v[96:99], v[180:183], v[212:215], v[96:99]
	v_mfma_f32_16x16x32_bf16 v[88:91], v[168:171], v[216:219], v[88:91]
	v_mfma_f32_16x16x32_bf16 v[88:91], v[172:175], v[220:223], v[88:91]
	v_mfma_f32_16x16x32_bf16 v[80:83], v[176:179], v[216:219], v[80:83]
	v_mfma_f32_16x16x32_bf16 v[80:83], v[180:183], v[220:223], v[80:83]
	v_mfma_f32_16x16x32_bf16 v[72:75], v[168:171], v[224:227], v[72:75]
	s_setprio 3
	s_barrier
	v_mfma_f32_16x16x32_bf16 v[72:75], v[172:175], v[228:231], v[72:75]
	v_mfma_f32_16x16x32_bf16 v[64:67], v[176:179], v[224:227], v[64:67]
	v_mfma_f32_16x16x32_bf16 v[64:67], v[180:183], v[228:231], v[64:67]
	s_setprio 0
.Lzj_2_0:
	s_add_i32 s22, s76, s57
	v_lshl_add_u64 v[196:197], s[6:7], 0, v[142:143]
	s_mov_b32 m0, s22
	ds_read_b128 v[184:187], v205 offset:16384
	ds_read_b128 v[188:191], v205 offset:17408
	ds_read_b128 v[192:195], v205 offset:18432
	ds_read_b128 v[212:215], v205 offset:19456
	ds_read_b128 v[216:219], v205 offset:20480
	ds_read_b128 v[220:223], v205 offset:21504
	ds_read_b128 v[224:227], v205 offset:22528
	ds_read_b128 v[228:231], v205 offset:23552
	global_load_lds_dwordx4 v[196:197], off
	s_add_i32 m0, s22, 0x2000
	s_add_u32 s22, s6, 0x40000
	v_lshl_add_u64 v[232:233], s[6:7], 0, v[146:147]
	s_addc_u32 s23, s7, 0
	s_add_i32 s24, s77, s57
	global_load_lds_dwordx4 v[232:233], off
	v_lshl_add_u64 v[234:235], s[22:23], 0, v[142:143]
	s_mov_b32 m0, s24
	global_load_lds_dwordx4 v[234:235], off
	s_add_i32 m0, s24, 0x2000
	v_lshl_add_u64 v[234:235], s[22:23], 0, v[146:147]
	global_load_lds_dwordx4 v[234:235], off
	s_mov_b32 m0, s58
	v_lshl_add_u64 v[234:235], vcc, 0, v[140:141]
	global_load_lds_dwordx4 v[234:235], off
	s_mov_b32 m0, s59
	v_lshl_add_u64 v[236:237], vcc, 0, v[144:145]
	global_load_lds_dwordx4 v[236:237], off
	s_cmp_eq_u32 s21, -2
	s_waitcnt vmcnt(8) lgkmcnt(0)
	s_barrier
	s_setprio 1
	s_cbranch_scc1 .Lzv_2_1
	v_mfma_f32_16x16x32_bf16 v[60:63], v[128:131], v[184:187], v[60:63]
	v_mfma_f32_16x16x32_bf16 v[60:63], v[132:135], v[188:191], v[60:63]
	v_mfma_f32_16x16x32_bf16 v[52:55], v[136:139], v[184:187], v[52:55]
	v_mfma_f32_16x16x32_bf16 v[52:55], v[164:167], v[188:191], v[52:55]
	v_mfma_f32_16x16x32_bf16 v[44:47], v[128:131], v[192:195], v[44:47]
	v_mfma_f32_16x16x32_bf16 v[44:47], v[132:135], v[212:215], v[44:47]
	v_mfma_f32_16x16x32_bf16 v[36:39], v[136:139], v[192:195], v[36:39]
	v_mfma_f32_16x16x32_bf16 v[36:39], v[164:167], v[212:215], v[36:39]
	v_mfma_f32_16x16x32_bf16 v[28:31], v[128:131], v[216:219], v[28:31]
	v_mfma_f32_16x16x32_bf16 v[28:31], v[132:135], v[220:223], v[28:31]
	v_mfma_f32_16x16x32_bf16 v[20:23], v[136:139], v[216:219], v[20:23]
	v_mfma_f32_16x16x32_bf16 v[20:23], v[164:167], v[220:223], v[20:23]
	v_mfma_f32_16x16x32_bf16 v[12:15], v[128:131], v[224:227], v[12:15]
	v_mfma_f32_16x16x32_bf16 v[12:15], v[132:135], v[228:231], v[12:15]
	v_mfma_f32_16x16x32_bf16 v[4:7], v[136:139], v[224:227], v[4:7]
	v_mfma_f32_16x16x32_bf16 v[4:7], v[164:167], v[228:231], v[4:7]
	v_mfma_f32_16x16x32_bf16 v[56:59], v[168:171], v[184:187], v[56:59]
	v_mfma_f32_16x16x32_bf16 v[56:59], v[172:175], v[188:191], v[56:59]
	v_mfma_f32_16x16x32_bf16 v[48:51], v[176:179], v[184:187], v[48:51]
	v_mfma_f32_16x16x32_bf16 v[48:51], v[180:183], v[188:191], v[48:51]
	v_mfma_f32_16x16x32_bf16 v[40:43], v[168:171], v[192:195], v[40:43]
	v_mfma_f32_16x16x32_bf16 v[40:43], v[172:175], v[212:215], v[40:43]
	v_mfma_f32_16x16x32_bf16 v[32:35], v[176:179], v[192:195], v[32:35]
	v_mfma_f32_16x16x32_bf16 v[32:35], v[180:183], v[212:215], v[32:35]
	v_mfma_f32_16x16x32_bf16 v[24:27], v[168:171], v[216:219], v[24:27]
	v_mfma_f32_16x16x32_bf16 v[24:27], v[172:175], v[220:223], v[24:27]
	v_mfma_f32_16x16x32_bf16 v[16:19], v[176:179], v[216:219], v[16:19]
	v_mfma_f32_16x16x32_bf16 v[16:19], v[180:183], v[220:223], v[16:19]
	v_mfma_f32_16x16x32_bf16 v[8:11], v[168:171], v[224:227], v[8:11]
	s_setprio 3
	s_barrier
	v_mfma_f32_16x16x32_bf16 v[8:11], v[172:175], v[228:231], v[8:11]
	v_mfma_f32_16x16x32_bf16 v[0:3], v[176:179], v[224:227], v[0:3]
	v_mfma_f32_16x16x32_bf16 v[0:3], v[180:183], v[228:231], v[0:3]
	s_setprio 0
.Lzj_2_1:
	s_add_i32 s24, 0, 0x18000
	v_add_u32_e32 v150, s24, v200
	s_add_i32 s25, 0, 0x1c000
	ds_read_b128 v[128:131], v150
	ds_read_b128 v[132:135], v150 offset:1024
	ds_read_b128 v[136:139], v150 offset:2048
	ds_read_b128 v[164:167], v150 offset:3072
	v_add_u32_e32 v150, s25, v200
	ds_read_b128 v[168:171], v150
	ds_read_b128 v[172:175], v150 offset:1024
	ds_read_b128 v[176:179], v150 offset:2048
	ds_read_b128 v[180:183], v150 offset:3072
	s_add_u32 s22, vcc_lo, 0x40000
	s_addc_u32 s23, vcc_hi, 0
	s_mov_b32 m0, s66
	v_lshl_add_u64 v[238:239], s[22:23], 0, v[140:141]
	ds_read_b128 v[184:187], v205 offset:32768
	ds_read_b128 v[188:191], v205 offset:33792
	ds_read_b128 v[192:195], v205 offset:34816
	ds_read_b128 v[212:215], v205 offset:35840
	ds_read_b128 v[216:219], v205 offset:36864
	ds_read_b128 v[220:223], v205 offset:37888
	ds_read_b128 v[224:227], v205 offset:38912
	ds_read_b128 v[228:231], v205 offset:39936
	global_load_lds_dwordx4 v[238:239], off
	s_mov_b32 m0, s67
	v_lshl_add_u64 v[238:239], s[22:23], 0, v[144:145]
	global_load_lds_dwordx4 v[238:239], off
	s_waitcnt vmcnt(8) lgkmcnt(0)
	s_barrier
	s_setprio 1
	v_mfma_f32_16x16x32_bf16 v[124:127], v[128:131], v[184:187], v[124:127]
	v_mfma_f32_16x16x32_bf16 v[124:127], v[132:135], v[188:191], v[124:127]
	v_mfma_f32_16x16x32_bf16 v[116:119], v[136:139], v[184:187], v[116:119]
	v_mfma_f32_16x16x32_bf16 v[116:119], v[164:167], v[188:191], v[116:119]
	v_mfma_f32_16x16x32_bf16 v[108:111], v[128:131], v[192:195], v[108:111]
	v_mfma_f32_16x16x32_bf16 v[108:111], v[132:135], v[212:215], v[108:111]
	v_mfma_f32_16x16x32_bf16 v[100:103], v[136:139], v[192:195], v[100:103]
	v_mfma_f32_16x16x32_bf16 v[100:103], v[164:167], v[212:215], v[100:103]
	v_mfma_f32_16x16x32_bf16 v[92:95], v[128:131], v[216:219], v[92:95]
	v_mfma_f32_16x16x32_bf16 v[92:95], v[132:135], v[220:223], v[92:95]
	v_mfma_f32_16x16x32_bf16 v[84:87], v[136:139], v[216:219], v[84:87]
	v_mfma_f32_16x16x32_bf16 v[84:87], v[164:167], v[220:223], v[84:87]
	v_mfma_f32_16x16x32_bf16 v[76:79], v[128:131], v[224:227], v[76:79]
	v_mfma_f32_16x16x32_bf16 v[76:79], v[132:135], v[228:231], v[76:79]
	v_mfma_f32_16x16x32_bf16 v[68:71], v[136:139], v[224:227], v[68:71]
	v_mfma_f32_16x16x32_bf16 v[68:71], v[164:167], v[228:231], v[68:71]
	v_mfma_f32_16x16x32_bf16 v[120:123], v[168:171], v[184:187], v[120:123]
	v_mfma_f32_16x16x32_bf16 v[120:123], v[172:175], v[188:191], v[120:123]
	v_mfma_f32_16x16x32_bf16 v[112:115], v[176:179], v[184:187], v[112:115]
	v_mfma_f32_16x16x32_bf16 v[112:115], v[180:183], v[188:191], v[112:115]
	v_mfma_f32_16x16x32_bf16 v[104:107], v[168:171], v[192:195], v[104:107]
	v_mfma_f32_16x16x32_bf16 v[104:107], v[172:175], v[212:215], v[104:107]
	v_mfma_f32_16x16x32_bf16 v[96:99], v[176:179], v[192:195], v[96:99]
	v_mfma_f32_16x16x32_bf16 v[96:99], v[180:183], v[212:215], v[96:99]
	v_mfma_f32_16x16x32_bf16 v[88:91], v[168:171], v[216:219], v[88:91]
	v_mfma_f32_16x16x32_bf16 v[88:91], v[172:175], v[220:223], v[88:91]
	v_mfma_f32_16x16x32_bf16 v[80:83], v[176:179], v[216:219], v[80:83]
	v_mfma_f32_16x16x32_bf16 v[80:83], v[180:183], v[220:223], v[80:83]
	v_mfma_f32_16x16x32_bf16 v[72:75], v[168:171], v[224:227], v[72:75]
	s_setprio 3
	s_barrier
	v_mfma_f32_16x16x32_bf16 v[72:75], v[172:175], v[228:231], v[72:75]
	v_mfma_f32_16x16x32_bf16 v[64:67], v[176:179], v[224:227], v[64:67]
	v_mfma_f32_16x16x32_bf16 v[64:67], v[180:183], v[228:231], v[64:67]
	s_setprio 0
	s_add_i32 s22, s24, s57
	v_lshl_add_u64 v[196:197], v[196:197], 0, s[80:81]
	s_mov_b32 m0, s22
	ds_read_b128 v[184:187], v205 offset:49152
	ds_read_b128 v[188:191], v205 offset:50176
	ds_read_b128 v[192:195], v205 offset:51200
	ds_read_b128 v[212:215], v205 offset:52224
	ds_read_b128 v[216:219], v205 offset:53248
	ds_read_b128 v[220:223], v205 offset:54272
	ds_read_b128 v[224:227], v205 offset:55296
	ds_read_b128 v[228:231], v205 offset:56320
	global_load_lds_dwordx4 v[196:197], off
	s_add_i32 m0, s22, 0x2000
	s_add_u32 s6, s6, 0x40080
	v_lshl_add_u64 v[196:197], v[232:233], 0, s[80:81]
	s_addc_u32 s7, s7, 0
	s_add_i32 s22, s25, s57
	global_load_lds_dwordx4 v[196:197], off
	s_mov_b32 m0, s22
	v_lshl_add_u64 v[196:197], s[6:7], 0, v[142:143]
	global_load_lds_dwordx4 v[196:197], off
	s_add_i32 m0, s22, 0x2000
	v_lshl_add_u64 v[196:197], s[6:7], 0, v[146:147]
	global_load_lds_dwordx4 v[196:197], off
	s_mov_b32 m0, s93
	v_lshl_add_u64 v[196:197], v[234:235], 0, s[80:81]
	global_load_lds_dwordx4 v[196:197], off
	s_mov_b32 m0, s69
	v_lshl_add_u64 v[196:197], v[236:237], 0, s[80:81]
	global_load_lds_dwordx4 v[196:197], off
	s_waitcnt vmcnt(8) lgkmcnt(0)
	s_barrier
	s_setprio 1
	v_mfma_f32_16x16x32_bf16 v[60:63], v[128:131], v[184:187], v[60:63]
	v_mfma_f32_16x16x32_bf16 v[60:63], v[132:135], v[188:191], v[60:63]
	v_mfma_f32_16x16x32_bf16 v[52:55], v[136:139], v[184:187], v[52:55]
	v_mfma_f32_16x16x32_bf16 v[52:55], v[164:167], v[188:191], v[52:55]
	v_mfma_f32_16x16x32_bf16 v[44:47], v[128:131], v[192:195], v[44:47]
	v_mfma_f32_16x16x32_bf16 v[44:47], v[132:135], v[212:215], v[44:47]
	v_mfma_f32_16x16x32_bf16 v[36:39], v[136:139], v[192:195], v[36:39]
	v_mfma_f32_16x16x32_bf16 v[36:39], v[164:167], v[212:215], v[36:39]
	v_mfma_f32_16x16x32_bf16 v[28:31], v[128:131], v[216:219], v[28:31]
	v_mfma_f32_16x16x32_bf16 v[28:31], v[132:135], v[220:223], v[28:31]
	v_mfma_f32_16x16x32_bf16 v[20:23], v[136:139], v[216:219], v[20:23]
	v_mfma_f32_16x16x32_bf16 v[20:23], v[164:167], v[220:223], v[20:23]
	v_mfma_f32_16x16x32_bf16 v[12:15], v[128:131], v[224:227], v[12:15]
	v_mfma_f32_16x16x32_bf16 v[12:15], v[132:135], v[228:231], v[12:15]
	v_mfma_f32_16x16x32_bf16 v[4:7], v[136:139], v[224:227], v[4:7]
	v_mfma_f32_16x16x32_bf16 v[4:7], v[164:167], v[228:231], v[4:7]
	v_mfma_f32_16x16x32_bf16 v[56:59], v[168:171], v[184:187], v[56:59]
	v_mfma_f32_16x16x32_bf16 v[56:59], v[172:175], v[188:191], v[56:59]
	v_mfma_f32_16x16x32_bf16 v[48:51], v[176:179], v[184:187], v[48:51]
	v_mfma_f32_16x16x32_bf16 v[48:51], v[180:183], v[188:191], v[48:51]
	v_mfma_f32_16x16x32_bf16 v[40:43], v[168:171], v[192:195], v[40:43]
	v_mfma_f32_16x16x32_bf16 v[40:43], v[172:175], v[212:215], v[40:43]
	v_mfma_f32_16x16x32_bf16 v[32:35], v[176:179], v[192:195], v[32:35]
	v_mfma_f32_16x16x32_bf16 v[32:35], v[180:183], v[212:215], v[32:35]
	v_mfma_f32_16x16x32_bf16 v[24:27], v[168:171], v[216:219], v[24:27]
	v_mfma_f32_16x16x32_bf16 v[24:27], v[172:175], v[220:223], v[24:27]
	v_mfma_f32_16x16x32_bf16 v[16:19], v[176:179], v[216:219], v[16:19]
	v_mfma_f32_16x16x32_bf16 v[16:19], v[180:183], v[220:223], v[16:19]
	v_mfma_f32_16x16x32_bf16 v[8:11], v[168:171], v[224:227], v[8:11]
	s_setprio 3
	s_barrier
	v_mfma_f32_16x16x32_bf16 v[8:11], v[172:175], v[228:231], v[8:11]
	v_mfma_f32_16x16x32_bf16 v[0:3], v[176:179], v[224:227], v[0:3]
	v_mfma_f32_16x16x32_bf16 v[0:3], v[180:183], v[228:231], v[0:3]
	s_setprio 0
	s_add_i32 s21, s21, 2
	s_add_u32 s88, s88, 0x100
	s_addc_u32 s89, s89, 0
	s_add_u32 s19, s19, 0x100
	s_addc_u32 s20, s20, 0
	s_cmp_gt_u32 s21, 13
	s_cbranch_scc0 .LBB0_429
	s_branch .Lzskip_2
.Lzv_2_0:
	v_mfma_f32_16x16x32_bf16 v[124:127], v[128:131], v[184:187], 0
	v_mfma_f32_16x16x32_bf16 v[124:127], v[132:135], v[188:191], v[124:127]
	v_mfma_f32_16x16x32_bf16 v[116:119], v[136:139], v[184:187], 0
	v_mfma_f32_16x16x32_bf16 v[116:119], v[164:167], v[188:191], v[116:119]
	v_mfma_f32_16x16x32_bf16 v[108:111], v[128:131], v[192:195], 0
	v_mfma_f32_16x16x32_bf16 v[108:111], v[132:135], v[212:215], v[108:111]
	v_mfma_f32_16x16x32_bf16 v[100:103], v[136:139], v[192:195], 0
	v_mfma_f32_16x16x32_bf16 v[100:103], v[164:167], v[212:215], v[100:103]
	v_mfma_f32_16x16x32_bf16 v[92:95], v[128:131], v[216:219], 0
	v_mfma_f32_16x16x32_bf16 v[92:95], v[132:135], v[220:223], v[92:95]
	v_mfma_f32_16x16x32_bf16 v[84:87], v[136:139], v[216:219], 0
	v_mfma_f32_16x16x32_bf16 v[84:87], v[164:167], v[220:223], v[84:87]
	v_mfma_f32_16x16x32_bf16 v[76:79], v[128:131], v[224:227], 0
	v_mfma_f32_16x16x32_bf16 v[76:79], v[132:135], v[228:231], v[76:79]
	v_mfma_f32_16x16x32_bf16 v[68:71], v[136:139], v[224:227], 0
	v_mfma_f32_16x16x32_bf16 v[68:71], v[164:167], v[228:231], v[68:71]
	v_mfma_f32_16x16x32_bf16 v[120:123], v[168:171], v[184:187], 0
	v_mfma_f32_16x16x32_bf16 v[120:123], v[172:175], v[188:191], v[120:123]
	v_mfma_f32_16x16x32_bf16 v[112:115], v[176:179], v[184:187], 0
	v_mfma_f32_16x16x32_bf16 v[112:115], v[180:183], v[188:191], v[112:115]
	v_mfma_f32_16x16x32_bf16 v[104:107], v[168:171], v[192:195], 0
	v_mfma_f32_16x16x32_bf16 v[104:107], v[172:175], v[212:215], v[104:107]
	v_mfma_f32_16x16x32_bf16 v[96:99], v[176:179], v[192:195], 0
	v_mfma_f32_16x16x32_bf16 v[96:99], v[180:183], v[212:215], v[96:99]
	v_mfma_f32_16x16x32_bf16 v[88:91], v[168:171], v[216:219], 0
	v_mfma_f32_16x16x32_bf16 v[88:91], v[172:175], v[220:223], v[88:91]
	v_mfma_f32_16x16x32_bf16 v[80:83], v[176:179], v[216:219], 0
	v_mfma_f32_16x16x32_bf16 v[80:83], v[180:183], v[220:223], v[80:83]
	v_mfma_f32_16x16x32_bf16 v[72:75], v[168:171], v[224:227], 0
	s_setprio 3
	s_barrier
	v_mfma_f32_16x16x32_bf16 v[72:75], v[172:175], v[228:231], v[72:75]
	v_mfma_f32_16x16x32_bf16 v[64:67], v[176:179], v[224:227], 0
	v_mfma_f32_16x16x32_bf16 v[64:67], v[180:183], v[228:231], v[64:67]
	s_setprio 0
	s_branch .Lzj_2_0
.Lzv_2_1:
	v_mfma_f32_16x16x32_bf16 v[60:63], v[128:131], v[184:187], 0
	v_mfma_f32_16x16x32_bf16 v[60:63], v[132:135], v[188:191], v[60:63]
	v_mfma_f32_16x16x32_bf16 v[52:55], v[136:139], v[184:187], 0
	v_mfma_f32_16x16x32_bf16 v[52:55], v[164:167], v[188:191], v[52:55]
	v_mfma_f32_16x16x32_bf16 v[44:47], v[128:131], v[192:195], 0
	v_mfma_f32_16x16x32_bf16 v[44:47], v[132:135], v[212:215], v[44:47]
	v_mfma_f32_16x16x32_bf16 v[36:39], v[136:139], v[192:195], 0
	v_mfma_f32_16x16x32_bf16 v[36:39], v[164:167], v[212:215], v[36:39]
	v_mfma_f32_16x16x32_bf16 v[28:31], v[128:131], v[216:219], 0
	v_mfma_f32_16x16x32_bf16 v[28:31], v[132:135], v[220:223], v[28:31]
	v_mfma_f32_16x16x32_bf16 v[20:23], v[136:139], v[216:219], 0
	v_mfma_f32_16x16x32_bf16 v[20:23], v[164:167], v[220:223], v[20:23]
	v_mfma_f32_16x16x32_bf16 v[12:15], v[128:131], v[224:227], 0
	v_mfma_f32_16x16x32_bf16 v[12:15], v[132:135], v[228:231], v[12:15]
	v_mfma_f32_16x16x32_bf16 v[4:7], v[136:139], v[224:227], 0
	v_mfma_f32_16x16x32_bf16 v[4:7], v[164:167], v[228:231], v[4:7]
	v_mfma_f32_16x16x32_bf16 v[56:59], v[168:171], v[184:187], 0
	v_mfma_f32_16x16x32_bf16 v[56:59], v[172:175], v[188:191], v[56:59]
	v_mfma_f32_16x16x32_bf16 v[48:51], v[176:179], v[184:187], 0
	v_mfma_f32_16x16x32_bf16 v[48:51], v[180:183], v[188:191], v[48:51]
	v_mfma_f32_16x16x32_bf16 v[40:43], v[168:171], v[192:195], 0
	v_mfma_f32_16x16x32_bf16 v[40:43], v[172:175], v[212:215], v[40:43]
	v_mfma_f32_16x16x32_bf16 v[32:35], v[176:179], v[192:195], 0
	v_mfma_f32_16x16x32_bf16 v[32:35], v[180:183], v[212:215], v[32:35]
	v_mfma_f32_16x16x32_bf16 v[24:27], v[168:171], v[216:219], 0
	v_mfma_f32_16x16x32_bf16 v[24:27], v[172:175], v[220:223], v[24:27]
	v_mfma_f32_16x16x32_bf16 v[16:19], v[176:179], v[216:219], 0
	v_mfma_f32_16x16x32_bf16 v[16:19], v[180:183], v[220:223], v[16:19]
	v_mfma_f32_16x16x32_bf16 v[8:11], v[168:171], v[224:227], 0
	s_setprio 3
	s_barrier
	v_mfma_f32_16x16x32_bf16 v[8:11], v[172:175], v[228:231], v[8:11]
	v_mfma_f32_16x16x32_bf16 v[0:3], v[176:179], v[224:227], 0
	v_mfma_f32_16x16x32_bf16 v[0:3], v[180:183], v[228:231], v[0:3]
	s_setprio 0
	s_branch .Lzj_2_1

.LBB0_993:
	ds_read_b128 v[120:123], v245
	ds_read_b128 v[124:127], v245 offset:1024
	ds_read_b128 v[128:131], v245 offset:2048
	ds_read_b128 v[132:135], v245 offset:3072
	ds_read_b128 v[144:147], v246
	ds_read_b128 v[148:151], v246 offset:1024
	ds_read_b128 v[152:155], v246 offset:2048
	ds_read_b128 v[156:159], v246 offset:3072
	s_add_u32 s59, s82, 0xfffc0080
	s_addc_u32 s66, s83, -1
	s_cmp_eq_u32 s58, 12
	s_cselect_b32 s87, s53, s66
	s_cselect_b32 s86, s54, s59
	s_cselect_b32 s85, s51, s57
	s_cselect_b32 s84, s55, s56
	v_lshl_add_u64 v[204:205], s[82:83], 0, v[200:201]
	s_add_i32 m0, s16, 0xc000
	ds_read_b128 v[160:163], v247
	ds_read_b128 v[164:167], v247 offset:1024
	ds_read_b128 v[168:171], v247 offset:2048
	ds_read_b128 v[172:175], v247 offset:3072
	ds_read_b128 v[176:179], v247 offset:4096
	ds_read_b128 v[180:183], v247 offset:5120
	ds_read_b128 v[184:187], v247 offset:6144
	ds_read_b128 v[188:191], v247 offset:7168
	global_load_lds_dwordx4 v[204:205], off
	s_add_i32 m0, s16, 0xe000
	v_lshl_add_u64 v[204:205], s[82:83], 0, v[202:203]
	global_load_lds_dwordx4 v[204:205], off
	s_cmp_eq_u32 s58, -2
	s_waitcnt vmcnt(8) lgkmcnt(0)
	s_barrier
	s_setprio 1
	s_cbranch_scc1 .Lzv_3_0
	v_mfma_f32_16x16x32_bf16 v[140:143], v[120:123], v[160:163], v[140:143]
	v_mfma_f32_16x16x32_bf16 v[140:143], v[124:127], v[164:167], v[140:143]
	v_mfma_f32_16x16x32_bf16 v[136:139], v[128:131], v[160:163], v[136:139]
	v_mfma_f32_16x16x32_bf16 v[136:139], v[132:135], v[164:167], v[136:139]
	v_mfma_f32_16x16x32_bf16 v[108:111], v[120:123], v[168:171], v[108:111]
	v_mfma_f32_16x16x32_bf16 v[108:111], v[124:127], v[172:175], v[108:111]
	v_mfma_f32_16x16x32_bf16 v[104:107], v[128:131], v[168:171], v[104:107]
	v_mfma_f32_16x16x32_bf16 v[104:107], v[132:135], v[172:175], v[104:107]
	v_mfma_f32_16x16x32_bf16 v[92:95], v[120:123], v[176:179], v[92:95]
	v_mfma_f32_16x16x32_bf16 v[92:95], v[124:127], v[180:183], v[92:95]
	v_mfma_f32_16x16x32_bf16 v[88:91], v[128:131], v[176:179], v[88:91]
	v_mfma_f32_16x16x32_bf16 v[88:91], v[132:135], v[180:183], v[88:91]
	v_mfma_f32_16x16x32_bf16 v[76:79], v[120:123], v[184:187], v[76:79]
	v_mfma_f32_16x16x32_bf16 v[76:79], v[124:127], v[188:191], v[76:79]
	v_mfma_f32_16x16x32_bf16 v[72:75], v[128:131], v[184:187], v[72:75]
	v_mfma_f32_16x16x32_bf16 v[72:75], v[132:135], v[188:191], v[72:75]
	v_mfma_f32_16x16x32_bf16 v[116:119], v[144:147], v[160:163], v[116:119]
	v_mfma_f32_16x16x32_bf16 v[116:119], v[148:151], v[164:167], v[116:119]
	v_mfma_f32_16x16x32_bf16 v[112:115], v[152:155], v[160:163], v[112:115]
	v_mfma_f32_16x16x32_bf16 v[112:115], v[156:159], v[164:167], v[112:115]
	v_mfma_f32_16x16x32_bf16 v[100:103], v[144:147], v[168:171], v[100:103]
	v_mfma_f32_16x16x32_bf16 v[100:103], v[148:151], v[172:175], v[100:103]
	v_mfma_f32_16x16x32_bf16 v[96:99], v[152:155], v[168:171], v[96:99]
	v_mfma_f32_16x16x32_bf16 v[96:99], v[156:159], v[172:175], v[96:99]
	v_mfma_f32_16x16x32_bf16 v[84:87], v[144:147], v[176:179], v[84:87]
	v_mfma_f32_16x16x32_bf16 v[84:87], v[148:151], v[180:183], v[84:87]
	v_mfma_f32_16x16x32_bf16 v[80:83], v[152:155], v[176:179], v[80:83]
	v_mfma_f32_16x16x32_bf16 v[80:83], v[156:159], v[180:183], v[80:83]
	v_mfma_f32_16x16x32_bf16 v[68:71], v[144:147], v[184:187], v[68:71]
	s_setprio 3
	s_barrier
	v_mfma_f32_16x16x32_bf16 v[68:71], v[148:151], v[188:191], v[68:71]
	v_mfma_f32_16x16x32_bf16 v[64:67], v[152:155], v[184:187], v[64:67]
	v_mfma_f32_16x16x32_bf16 v[64:67], v[156:159], v[188:191], v[64:67]
	s_setprio 0
.Lzj_3_0:
	s_add_i32 s59, s26, s15
	v_lshl_add_u64 v[204:205], s[84:85], 0, v[194:195]
	s_mov_b32 m0, s59
	ds_read_b128 v[160:163], v247 offset:16384
	ds_read_b128 v[164:167], v247 offset:17408
	ds_read_b128 v[168:171], v247 offset:18432
	ds_read_b128 v[172:175], v247 offset:19456
	ds_read_b128 v[176:179], v247 offset:20480
	ds_read_b128 v[180:183], v247 offset:21504
	ds_read_b128 v[184:187], v247 offset:22528
	ds_read_b128 v[188:191], v247 offset:23552
	global_load_lds_dwordx4 v[204:205], off
	s_add_i32 m0, s59, 0x2000
	s_add_u32 s66, s84, 0x40000
	v_lshl_add_u64 v[206:207], s[84:85], 0, v[198:199]
	s_addc_u32 s67, s85, 0
	s_add_i32 s59, s27, s15
	global_load_lds_dwordx4 v[206:207], off
	v_lshl_add_u64 v[208:209], s[66:67], 0, v[194:195]
	s_mov_b32 m0, s59
	global_load_lds_dwordx4 v[208:209], off
	s_add_i32 m0, s59, 0x2000
	v_lshl_add_u64 v[208:209], s[66:67], 0, v[198:199]
	global_load_lds_dwordx4 v[208:209], off
	s_mov_b32 m0, s16
	v_lshl_add_u64 v[208:209], s[86:87], 0, v[192:193]
	global_load_lds_dwordx4 v[208:209], off
	s_mov_b32 m0, s17
	v_lshl_add_u64 v[210:211], s[86:87], 0, v[196:197]
	global_load_lds_dwordx4 v[210:211], off
	s_cmp_eq_u32 s58, -2
	s_waitcnt vmcnt(8) lgkmcnt(0)
	s_barrier
	s_setprio 1
	s_cbranch_scc1 .Lzv_3_1
	v_mfma_f32_16x16x32_bf16 v[60:63], v[120:123], v[160:163], v[60:63]
	v_mfma_f32_16x16x32_bf16 v[60:63], v[124:127], v[164:167], v[60:63]
	v_mfma_f32_16x16x32_bf16 v[56:59], v[128:131], v[160:163], v[56:59]
	v_mfma_f32_16x16x32_bf16 v[56:59], v[132:135], v[164:167], v[56:59]
	v_mfma_f32_16x16x32_bf16 v[44:47], v[120:123], v[168:171], v[44:47]
	v_mfma_f32_16x16x32_bf16 v[44:47], v[124:127], v[172:175], v[44:47]
	v_mfma_f32_16x16x32_bf16 v[40:43], v[128:131], v[168:171], v[40:43]
	v_mfma_f32_16x16x32_bf16 v[40:43], v[132:135], v[172:175], v[40:43]
	v_mfma_f32_16x16x32_bf16 v[28:31], v[120:123], v[176:179], v[28:31]
	v_mfma_f32_16x16x32_bf16 v[28:31], v[124:127], v[180:183], v[28:31]
	v_mfma_f32_16x16x32_bf16 v[24:27], v[128:131], v[176:179], v[24:27]
	v_mfma_f32_16x16x32_bf16 v[24:27], v[132:135], v[180:183], v[24:27]
	v_mfma_f32_16x16x32_bf16 v[12:15], v[120:123], v[184:187], v[12:15]
	v_mfma_f32_16x16x32_bf16 v[12:15], v[124:127], v[188:191], v[12:15]
	v_mfma_f32_16x16x32_bf16 v[8:11], v[128:131], v[184:187], v[8:11]
	v_mfma_f32_16x16x32_bf16 v[8:11], v[132:135], v[188:191], v[8:11]
	v_mfma_f32_16x16x32_bf16 v[52:55], v[144:147], v[160:163], v[52:55]
	v_mfma_f32_16x16x32_bf16 v[52:55], v[148:151], v[164:167], v[52:55]
	v_mfma_f32_16x16x32_bf16 v[48:51], v[152:155], v[160:163], v[48:51]
	v_mfma_f32_16x16x32_bf16 v[48:51], v[156:159], v[164:167], v[48:51]
	v_mfma_f32_16x16x32_bf16 v[36:39], v[144:147], v[168:171], v[36:39]
	v_mfma_f32_16x16x32_bf16 v[36:39], v[148:151], v[172:175], v[36:39]
	v_mfma_f32_16x16x32_bf16 v[32:35], v[152:155], v[168:171], v[32:35]
	v_mfma_f32_16x16x32_bf16 v[32:35], v[156:159], v[172:175], v[32:35]
	v_mfma_f32_16x16x32_bf16 v[20:23], v[144:147], v[176:179], v[20:23]
	v_mfma_f32_16x16x32_bf16 v[20:23], v[148:151], v[180:183], v[20:23]
	v_mfma_f32_16x16x32_bf16 v[16:19], v[152:155], v[176:179], v[16:19]
	v_mfma_f32_16x16x32_bf16 v[16:19], v[156:159], v[180:183], v[16:19]
	v_mfma_f32_16x16x32_bf16 v[4:7], v[144:147], v[184:187], v[4:7]
	s_setprio 3
	s_barrier
	v_mfma_f32_16x16x32_bf16 v[4:7], v[148:151], v[188:191], v[4:7]
	v_mfma_f32_16x16x32_bf16 v[0:3], v[152:155], v[184:187], v[0:3]
	v_mfma_f32_16x16x32_bf16 v[0:3], v[156:159], v[188:191], v[0:3]
	s_setprio 0
.Lzj_3_1:
	s_add_i32 s59, 0, 0x18000
	s_add_i32 s68, 0, 0x1c000
	v_add_u32_e32 v132, s59, v243
	v_add_u32_e32 v156, s68, v243
	ds_read_b128 v[120:123], v132
	ds_read_b128 v[124:127], v132 offset:1024
	ds_read_b128 v[128:131], v132 offset:2048
	ds_read_b128 v[132:135], v132 offset:3072
	ds_read_b128 v[144:147], v156
	ds_read_b128 v[148:151], v156 offset:1024
	ds_read_b128 v[152:155], v156 offset:2048
	ds_read_b128 v[156:159], v156 offset:3072
	s_add_u32 s66, s86, 0x40000
	s_addc_u32 s67, s87, 0
	s_mov_b32 m0, s18
	v_lshl_add_u64 v[212:213], s[66:67], 0, v[192:193]
	ds_read_b128 v[160:163], v247 offset:32768
	ds_read_b128 v[164:167], v247 offset:33792
	ds_read_b128 v[168:171], v247 offset:34816
	ds_read_b128 v[172:175], v247 offset:35840
	ds_read_b128 v[176:179], v247 offset:36864
	ds_read_b128 v[180:183], v247 offset:37888
	ds_read_b128 v[184:187], v247 offset:38912
	ds_read_b128 v[188:191], v247 offset:39936
	global_load_lds_dwordx4 v[212:213], off
	s_mov_b32 m0, s19
	v_lshl_add_u64 v[212:213], s[66:67], 0, v[196:197]
	global_load_lds_dwordx4 v[212:213], off
	s_waitcnt vmcnt(8) lgkmcnt(0)
	s_barrier
	s_setprio 1
	v_mfma_f32_16x16x32_bf16 v[140:143], v[120:123], v[160:163], v[140:143]
	v_mfma_f32_16x16x32_bf16 v[140:143], v[124:127], v[164:167], v[140:143]
	v_mfma_f32_16x16x32_bf16 v[136:139], v[128:131], v[160:163], v[136:139]
	v_mfma_f32_16x16x32_bf16 v[136:139], v[132:135], v[164:167], v[136:139]
	v_mfma_f32_16x16x32_bf16 v[108:111], v[120:123], v[168:171], v[108:111]
	v_mfma_f32_16x16x32_bf16 v[108:111], v[124:127], v[172:175], v[108:111]
	v_mfma_f32_16x16x32_bf16 v[104:107], v[128:131], v[168:171], v[104:107]
	v_mfma_f32_16x16x32_bf16 v[104:107], v[132:135], v[172:175], v[104:107]
	v_mfma_f32_16x16x32_bf16 v[92:95], v[120:123], v[176:179], v[92:95]
	v_mfma_f32_16x16x32_bf16 v[92:95], v[124:127], v[180:183], v[92:95]
	v_mfma_f32_16x16x32_bf16 v[88:91], v[128:131], v[176:179], v[88:91]
	v_mfma_f32_16x16x32_bf16 v[88:91], v[132:135], v[180:183], v[88:91]
	v_mfma_f32_16x16x32_bf16 v[76:79], v[120:123], v[184:187], v[76:79]
	v_mfma_f32_16x16x32_bf16 v[76:79], v[124:127], v[188:191], v[76:79]
	v_mfma_f32_16x16x32_bf16 v[72:75], v[128:131], v[184:187], v[72:75]
	v_mfma_f32_16x16x32_bf16 v[72:75], v[132:135], v[188:191], v[72:75]
	v_mfma_f32_16x16x32_bf16 v[116:119], v[144:147], v[160:163], v[116:119]
	v_mfma_f32_16x16x32_bf16 v[116:119], v[148:151], v[164:167], v[116:119]
	v_mfma_f32_16x16x32_bf16 v[112:115], v[152:155], v[160:163], v[112:115]
	v_mfma_f32_16x16x32_bf16 v[112:115], v[156:159], v[164:167], v[112:115]
	v_mfma_f32_16x16x32_bf16 v[100:103], v[144:147], v[168:171], v[100:103]
	v_mfma_f32_16x16x32_bf16 v[100:103], v[148:151], v[172:175], v[100:103]
	v_mfma_f32_16x16x32_bf16 v[96:99], v[152:155], v[168:171], v[96:99]
	v_mfma_f32_16x16x32_bf16 v[96:99], v[156:159], v[172:175], v[96:99]
	v_mfma_f32_16x16x32_bf16 v[84:87], v[144:147], v[176:179], v[84:87]
	v_mfma_f32_16x16x32_bf16 v[84:87], v[148:151], v[180:183], v[84:87]
	v_mfma_f32_16x16x32_bf16 v[80:83], v[152:155], v[176:179], v[80:83]
	v_mfma_f32_16x16x32_bf16 v[80:83], v[156:159], v[180:183], v[80:83]
	v_mfma_f32_16x16x32_bf16 v[68:71], v[144:147], v[184:187], v[68:71]
	s_setprio 3
	s_barrier
	v_mfma_f32_16x16x32_bf16 v[68:71], v[148:151], v[188:191], v[68:71]
	v_mfma_f32_16x16x32_bf16 v[64:67], v[152:155], v[184:187], v[64:67]
	v_mfma_f32_16x16x32_bf16 v[64:67], v[156:159], v[188:191], v[64:67]
	s_setprio 0
	s_add_i32 s59, s59, s15
	v_lshl_add_u64 v[204:205], v[204:205], 0, s[46:47]
	s_mov_b32 m0, s59
	ds_read_b128 v[160:163], v247 offset:49152
	ds_read_b128 v[164:167], v247 offset:50176
	ds_read_b128 v[168:171], v247 offset:51200
	ds_read_b128 v[172:175], v247 offset:52224
	ds_read_b128 v[176:179], v247 offset:53248
	ds_read_b128 v[180:183], v247 offset:54272
	ds_read_b128 v[184:187], v247 offset:55296
	ds_read_b128 v[188:191], v247 offset:56320
	global_load_lds_dwordx4 v[204:205], off
	s_add_i32 m0, s59, 0x2000
	s_add_u32 s66, s84, 0x40080
	v_lshl_add_u64 v[204:205], v[206:207], 0, s[46:47]
	s_addc_u32 s67, s85, 0
	s_add_i32 s59, s68, s15
	global_load_lds_dwordx4 v[204:205], off
	s_mov_b32 m0, s59
	v_lshl_add_u64 v[204:205], s[66:67], 0, v[194:195]
	global_load_lds_dwordx4 v[204:205], off
	s_add_i32 m0, s59, 0x2000
	v_lshl_add_u64 v[204:205], s[66:67], 0, v[198:199]
	global_load_lds_dwordx4 v[204:205], off
	s_mov_b32 m0, s21
	v_lshl_add_u64 v[204:205], v[208:209], 0, s[46:47]
	global_load_lds_dwordx4 v[204:205], off
	s_mov_b32 m0, s22
	v_lshl_add_u64 v[204:205], v[210:211], 0, s[46:47]
	global_load_lds_dwordx4 v[204:205], off
	s_waitcnt vmcnt(8) lgkmcnt(0)
	s_barrier
	s_setprio 1
	v_mfma_f32_16x16x32_bf16 v[60:63], v[120:123], v[160:163], v[60:63]
	v_mfma_f32_16x16x32_bf16 v[60:63], v[124:127], v[164:167], v[60:63]
	v_mfma_f32_16x16x32_bf16 v[56:59], v[128:131], v[160:163], v[56:59]
	v_mfma_f32_16x16x32_bf16 v[56:59], v[132:135], v[164:167], v[56:59]
	v_mfma_f32_16x16x32_bf16 v[44:47], v[120:123], v[168:171], v[44:47]
	v_mfma_f32_16x16x32_bf16 v[44:47], v[124:127], v[172:175], v[44:47]
	v_mfma_f32_16x16x32_bf16 v[40:43], v[128:131], v[168:171], v[40:43]
	v_mfma_f32_16x16x32_bf16 v[40:43], v[132:135], v[172:175], v[40:43]
	v_mfma_f32_16x16x32_bf16 v[28:31], v[120:123], v[176:179], v[28:31]
	v_mfma_f32_16x16x32_bf16 v[28:31], v[124:127], v[180:183], v[28:31]
	v_mfma_f32_16x16x32_bf16 v[24:27], v[128:131], v[176:179], v[24:27]
	v_mfma_f32_16x16x32_bf16 v[24:27], v[132:135], v[180:183], v[24:27]
	v_mfma_f32_16x16x32_bf16 v[12:15], v[120:123], v[184:187], v[12:15]
	v_mfma_f32_16x16x32_bf16 v[12:15], v[124:127], v[188:191], v[12:15]
	v_mfma_f32_16x16x32_bf16 v[8:11], v[128:131], v[184:187], v[8:11]
	v_mfma_f32_16x16x32_bf16 v[8:11], v[132:135], v[188:191], v[8:11]
	v_mfma_f32_16x16x32_bf16 v[52:55], v[144:147], v[160:163], v[52:55]
	v_mfma_f32_16x16x32_bf16 v[52:55], v[148:151], v[164:167], v[52:55]
	v_mfma_f32_16x16x32_bf16 v[48:51], v[152:155], v[160:163], v[48:51]
	v_mfma_f32_16x16x32_bf16 v[48:51], v[156:159], v[164:167], v[48:51]
	v_mfma_f32_16x16x32_bf16 v[36:39], v[144:147], v[168:171], v[36:39]
	v_mfma_f32_16x16x32_bf16 v[36:39], v[148:151], v[172:175], v[36:39]
	v_mfma_f32_16x16x32_bf16 v[32:35], v[152:155], v[168:171], v[32:35]
	v_mfma_f32_16x16x32_bf16 v[32:35], v[156:159], v[172:175], v[32:35]
	v_mfma_f32_16x16x32_bf16 v[20:23], v[144:147], v[176:179], v[20:23]
	v_mfma_f32_16x16x32_bf16 v[20:23], v[148:151], v[180:183], v[20:23]
	v_mfma_f32_16x16x32_bf16 v[16:19], v[152:155], v[176:179], v[16:19]
	v_mfma_f32_16x16x32_bf16 v[16:19], v[156:159], v[180:183], v[16:19]
	v_mfma_f32_16x16x32_bf16 v[4:7], v[144:147], v[184:187], v[4:7]
	s_setprio 3
	s_barrier
	v_mfma_f32_16x16x32_bf16 v[4:7], v[148:151], v[188:191], v[4:7]
	v_mfma_f32_16x16x32_bf16 v[0:3], v[152:155], v[184:187], v[0:3]
	v_mfma_f32_16x16x32_bf16 v[0:3], v[156:159], v[188:191], v[0:3]
	s_setprio 0
	s_add_i32 s58, s58, 2
	s_add_u32 s82, s82, 0x100
	s_addc_u32 s83, s83, 0
	s_add_u32 s56, s56, 0x100
	s_addc_u32 s57, s57, 0
	s_cmp_gt_u32 s58, 13
	s_cbranch_scc0 .LBB0_993
	s_branch .Lzskip_3

.LBB0_1148:
	ds_read_b128 v[146:149], v174
	ds_read_b128 v[150:153], v174 offset:1024
	ds_read_b128 v[154:157], v174 offset:2048
	ds_read_b128 v[158:161], v174 offset:3072
	ds_read_b128 v[162:165], v175
	ds_read_b128 v[178:181], v175 offset:1024
	ds_read_b128 v[182:185], v175 offset:2048
	ds_read_b128 v[186:189], v175 offset:3072
	s_add_u32 s67, s78, 0xfffc0080
	s_addc_u32 s68, s79, -1
	s_cmp_eq_u32 s66, 12
	s_cselect_b32 s83, s49, s68
	s_cselect_b32 s82, s54, s67
	s_cselect_b32 s81, s47, s59
	s_cselect_b32 s80, s55, s58
	v_lshl_add_u64 v[166:167], s[78:79], 0, v[136:137]
	s_add_i32 m0, s17, 0xc000
	ds_read_b128 v[190:193], v176
	ds_read_b128 v[194:197], v176 offset:1024
	ds_read_b128 v[198:201], v176 offset:2048
	ds_read_b128 v[202:205], v176 offset:3072
	ds_read_b128 v[206:209], v176 offset:4096
	ds_read_b128 v[210:213], v176 offset:5120
	ds_read_b128 v[214:217], v176 offset:6144
	ds_read_b128 v[218:221], v176 offset:7168
	global_load_lds_dwordx4 v[166:167], off
	s_add_i32 m0, s17, 0xe000
	v_lshl_add_u64 v[166:167], s[78:79], 0, v[140:141]
	global_load_lds_dwordx4 v[166:167], off
	s_cmp_eq_u32 s66, -2
	s_waitcnt vmcnt(8) lgkmcnt(0)
	s_barrier
	s_setprio 1
	s_cbranch_scc1 .Lzv_4_0
	v_mfma_f32_16x16x32_bf16 v[124:127], v[146:149], v[190:193], v[124:127]
	v_mfma_f32_16x16x32_bf16 v[124:127], v[150:153], v[194:197], v[124:127]
	v_mfma_f32_16x16x32_bf16 v[116:119], v[154:157], v[190:193], v[116:119]
	v_mfma_f32_16x16x32_bf16 v[116:119], v[158:161], v[194:197], v[116:119]
	v_mfma_f32_16x16x32_bf16 v[108:111], v[146:149], v[198:201], v[108:111]
	v_mfma_f32_16x16x32_bf16 v[108:111], v[150:153], v[202:205], v[108:111]
	v_mfma_f32_16x16x32_bf16 v[100:103], v[154:157], v[198:201], v[100:103]
	v_mfma_f32_16x16x32_bf16 v[100:103], v[158:161], v[202:205], v[100:103]
	v_mfma_f32_16x16x32_bf16 v[92:95], v[146:149], v[206:209], v[92:95]
	v_mfma_f32_16x16x32_bf16 v[92:95], v[150:153], v[210:213], v[92:95]
	v_mfma_f32_16x16x32_bf16 v[84:87], v[154:157], v[206:209], v[84:87]
	v_mfma_f32_16x16x32_bf16 v[84:87], v[158:161], v[210:213], v[84:87]
	v_mfma_f32_16x16x32_bf16 v[76:79], v[146:149], v[214:217], v[76:79]
	v_mfma_f32_16x16x32_bf16 v[76:79], v[150:153], v[218:221], v[76:79]
	v_mfma_f32_16x16x32_bf16 v[68:71], v[154:157], v[214:217], v[68:71]
	v_mfma_f32_16x16x32_bf16 v[68:71], v[158:161], v[218:221], v[68:71]
	v_mfma_f32_16x16x32_bf16 v[120:123], v[162:165], v[190:193], v[120:123]
	v_mfma_f32_16x16x32_bf16 v[120:123], v[178:181], v[194:197], v[120:123]
	v_mfma_f32_16x16x32_bf16 v[112:115], v[182:185], v[190:193], v[112:115]
	v_mfma_f32_16x16x32_bf16 v[112:115], v[186:189], v[194:197], v[112:115]
	v_mfma_f32_16x16x32_bf16 v[104:107], v[162:165], v[198:201], v[104:107]
	v_mfma_f32_16x16x32_bf16 v[104:107], v[178:181], v[202:205], v[104:107]
	v_mfma_f32_16x16x32_bf16 v[96:99], v[182:185], v[198:201], v[96:99]
	v_mfma_f32_16x16x32_bf16 v[96:99], v[186:189], v[202:205], v[96:99]
	v_mfma_f32_16x16x32_bf16 v[88:91], v[162:165], v[206:209], v[88:91]
	v_mfma_f32_16x16x32_bf16 v[88:91], v[178:181], v[210:213], v[88:91]
	v_mfma_f32_16x16x32_bf16 v[80:83], v[182:185], v[206:209], v[80:83]
	v_mfma_f32_16x16x32_bf16 v[80:83], v[186:189], v[210:213], v[80:83]
	v_mfma_f32_16x16x32_bf16 v[72:75], v[162:165], v[214:217], v[72:75]
	s_setprio 3
	s_barrier
	v_mfma_f32_16x16x32_bf16 v[72:75], v[178:181], v[218:221], v[72:75]
	v_mfma_f32_16x16x32_bf16 v[64:67], v[182:185], v[214:217], v[64:67]
	v_mfma_f32_16x16x32_bf16 v[64:67], v[186:189], v[218:221], v[64:67]
	s_setprio 0
.Lzj_4_0:
	s_add_i32 s67, s25, s16
	v_lshl_add_u64 v[166:167], s[80:81], 0, v[132:133]
	s_mov_b32 m0, s67
	ds_read_b128 v[190:193], v176 offset:16384
	ds_read_b128 v[194:197], v176 offset:17408
	ds_read_b128 v[198:201], v176 offset:18432
	ds_read_b128 v[202:205], v176 offset:19456
	ds_read_b128 v[206:209], v176 offset:20480
	ds_read_b128 v[210:213], v176 offset:21504
	ds_read_b128 v[214:217], v176 offset:22528
	ds_read_b128 v[218:221], v176 offset:23552
	global_load_lds_dwordx4 v[166:167], off
	s_add_i32 m0, s67, 0x2000
	s_add_u32 s68, s80, 0x40000
	v_lshl_add_u64 v[222:223], s[80:81], 0, v[128:129]
	s_addc_u32 s69, s81, 0
	s_add_i32 s67, s26, s16
	global_load_lds_dwordx4 v[222:223], off
	v_lshl_add_u64 v[224:225], s[68:69], 0, v[132:133]
	s_mov_b32 m0, s67
	global_load_lds_dwordx4 v[224:225], off
	s_add_i32 m0, s67, 0x2000
	v_lshl_add_u64 v[224:225], s[68:69], 0, v[128:129]
	global_load_lds_dwordx4 v[224:225], off
	s_mov_b32 m0, s17
	v_lshl_add_u64 v[224:225], s[82:83], 0, v[134:135]
	global_load_lds_dwordx4 v[224:225], off
	s_mov_b32 m0, s18
	v_lshl_add_u64 v[226:227], s[82:83], 0, v[130:131]
	global_load_lds_dwordx4 v[226:227], off
	s_cmp_eq_u32 s66, -2
	s_waitcnt vmcnt(8) lgkmcnt(0)
	s_barrier
	s_setprio 1
	s_cbranch_scc1 .Lzv_4_1
	v_mfma_f32_16x16x32_bf16 v[60:63], v[146:149], v[190:193], v[60:63]
	v_mfma_f32_16x16x32_bf16 v[60:63], v[150:153], v[194:197], v[60:63]
	v_mfma_f32_16x16x32_bf16 v[52:55], v[154:157], v[190:193], v[52:55]
	v_mfma_f32_16x16x32_bf16 v[52:55], v[158:161], v[194:197], v[52:55]
	v_mfma_f32_16x16x32_bf16 v[44:47], v[146:149], v[198:201], v[44:47]
	v_mfma_f32_16x16x32_bf16 v[44:47], v[150:153], v[202:205], v[44:47]
	v_mfma_f32_16x16x32_bf16 v[36:39], v[154:157], v[198:201], v[36:39]
	v_mfma_f32_16x16x32_bf16 v[36:39], v[158:161], v[202:205], v[36:39]
	v_mfma_f32_16x16x32_bf16 v[28:31], v[146:149], v[206:209], v[28:31]
	v_mfma_f32_16x16x32_bf16 v[28:31], v[150:153], v[210:213], v[28:31]
	v_mfma_f32_16x16x32_bf16 v[20:23], v[154:157], v[206:209], v[20:23]
	v_mfma_f32_16x16x32_bf16 v[20:23], v[158:161], v[210:213], v[20:23]
	v_mfma_f32_16x16x32_bf16 v[12:15], v[146:149], v[214:217], v[12:15]
	v_mfma_f32_16x16x32_bf16 v[12:15], v[150:153], v[218:221], v[12:15]
	v_mfma_f32_16x16x32_bf16 v[4:7], v[154:157], v[214:217], v[4:7]
	v_mfma_f32_16x16x32_bf16 v[4:7], v[158:161], v[218:221], v[4:7]
	v_mfma_f32_16x16x32_bf16 v[56:59], v[162:165], v[190:193], v[56:59]
	v_mfma_f32_16x16x32_bf16 v[56:59], v[178:181], v[194:197], v[56:59]
	v_mfma_f32_16x16x32_bf16 v[48:51], v[182:185], v[190:193], v[48:51]
	v_mfma_f32_16x16x32_bf16 v[48:51], v[186:189], v[194:197], v[48:51]
	v_mfma_f32_16x16x32_bf16 v[40:43], v[162:165], v[198:201], v[40:43]
	v_mfma_f32_16x16x32_bf16 v[40:43], v[178:181], v[202:205], v[40:43]
	v_mfma_f32_16x16x32_bf16 v[32:35], v[182:185], v[198:201], v[32:35]
	v_mfma_f32_16x16x32_bf16 v[32:35], v[186:189], v[202:205], v[32:35]
	v_mfma_f32_16x16x32_bf16 v[24:27], v[162:165], v[206:209], v[24:27]
	v_mfma_f32_16x16x32_bf16 v[24:27], v[178:181], v[210:213], v[24:27]
	v_mfma_f32_16x16x32_bf16 v[16:19], v[182:185], v[206:209], v[16:19]
	v_mfma_f32_16x16x32_bf16 v[16:19], v[186:189], v[210:213], v[16:19]
	v_mfma_f32_16x16x32_bf16 v[8:11], v[162:165], v[214:217], v[8:11]
	s_setprio 3
	s_barrier
	v_mfma_f32_16x16x32_bf16 v[8:11], v[178:181], v[218:221], v[8:11]
	v_mfma_f32_16x16x32_bf16 v[0:3], v[182:185], v[214:217], v[0:3]
	v_mfma_f32_16x16x32_bf16 v[0:3], v[186:189], v[218:221], v[0:3]
	s_setprio 0
.Lzj_4_1:
	s_add_i32 s67, 0, 0x18000
	s_add_i32 s73, 0, 0x1c000
	v_add_u32_e32 v158, s67, v171
	v_add_u32_e32 v186, s73, v171
	ds_read_b128 v[146:149], v158
	ds_read_b128 v[150:153], v158 offset:1024
	ds_read_b128 v[154:157], v158 offset:2048
	ds_read_b128 v[158:161], v158 offset:3072
	ds_read_b128 v[162:165], v186
	ds_read_b128 v[178:181], v186 offset:1024
	ds_read_b128 v[182:185], v186 offset:2048
	ds_read_b128 v[186:189], v186 offset:3072
	s_add_u32 s68, s82, 0x40000
	s_addc_u32 s69, s83, 0
	s_mov_b32 m0, s19
	v_lshl_add_u64 v[228:229], s[68:69], 0, v[134:135]
	ds_read_b128 v[190:193], v176 offset:32768
	ds_read_b128 v[194:197], v176 offset:33792
	ds_read_b128 v[198:201], v176 offset:34816
	ds_read_b128 v[202:205], v176 offset:35840
	ds_read_b128 v[206:209], v176 offset:36864
	ds_read_b128 v[210:213], v176 offset:37888
	ds_read_b128 v[214:217], v176 offset:38912
	ds_read_b128 v[218:221], v176 offset:39936
	global_load_lds_dwordx4 v[228:229], off
	s_mov_b32 m0, s20
	v_lshl_add_u64 v[228:229], s[68:69], 0, v[130:131]
	global_load_lds_dwordx4 v[228:229], off
	s_waitcnt vmcnt(8) lgkmcnt(0)
	s_barrier
	s_setprio 1
	v_mfma_f32_16x16x32_bf16 v[124:127], v[146:149], v[190:193], v[124:127]
	v_mfma_f32_16x16x32_bf16 v[124:127], v[150:153], v[194:197], v[124:127]
	v_mfma_f32_16x16x32_bf16 v[116:119], v[154:157], v[190:193], v[116:119]
	v_mfma_f32_16x16x32_bf16 v[116:119], v[158:161], v[194:197], v[116:119]
	v_mfma_f32_16x16x32_bf16 v[108:111], v[146:149], v[198:201], v[108:111]
	v_mfma_f32_16x16x32_bf16 v[108:111], v[150:153], v[202:205], v[108:111]
	v_mfma_f32_16x16x32_bf16 v[100:103], v[154:157], v[198:201], v[100:103]
	v_mfma_f32_16x16x32_bf16 v[100:103], v[158:161], v[202:205], v[100:103]
	v_mfma_f32_16x16x32_bf16 v[92:95], v[146:149], v[206:209], v[92:95]
	v_mfma_f32_16x16x32_bf16 v[92:95], v[150:153], v[210:213], v[92:95]
	v_mfma_f32_16x16x32_bf16 v[84:87], v[154:157], v[206:209], v[84:87]
	v_mfma_f32_16x16x32_bf16 v[84:87], v[158:161], v[210:213], v[84:87]
	v_mfma_f32_16x16x32_bf16 v[76:79], v[146:149], v[214:217], v[76:79]
	v_mfma_f32_16x16x32_bf16 v[76:79], v[150:153], v[218:221], v[76:79]
	v_mfma_f32_16x16x32_bf16 v[68:71], v[154:157], v[214:217], v[68:71]
	v_mfma_f32_16x16x32_bf16 v[68:71], v[158:161], v[218:221], v[68:71]
	v_mfma_f32_16x16x32_bf16 v[120:123], v[162:165], v[190:193], v[120:123]
	v_mfma_f32_16x16x32_bf16 v[120:123], v[178:181], v[194:197], v[120:123]
	v_mfma_f32_16x16x32_bf16 v[112:115], v[182:185], v[190:193], v[112:115]
	v_mfma_f32_16x16x32_bf16 v[112:115], v[186:189], v[194:197], v[112:115]
	v_mfma_f32_16x16x32_bf16 v[104:107], v[162:165], v[198:201], v[104:107]
	v_mfma_f32_16x16x32_bf16 v[104:107], v[178:181], v[202:205], v[104:107]
	v_mfma_f32_16x16x32_bf16 v[96:99], v[182:185], v[198:201], v[96:99]
	v_mfma_f32_16x16x32_bf16 v[96:99], v[186:189], v[202:205], v[96:99]
	v_mfma_f32_16x16x32_bf16 v[88:91], v[162:165], v[206:209], v[88:91]
	v_mfma_f32_16x16x32_bf16 v[88:91], v[178:181], v[210:213], v[88:91]
	v_mfma_f32_16x16x32_bf16 v[80:83], v[182:185], v[206:209], v[80:83]
	v_mfma_f32_16x16x32_bf16 v[80:83], v[186:189], v[210:213], v[80:83]
	v_mfma_f32_16x16x32_bf16 v[72:75], v[162:165], v[214:217], v[72:75]
	s_setprio 3
	s_barrier
	v_mfma_f32_16x16x32_bf16 v[72:75], v[178:181], v[218:221], v[72:75]
	v_mfma_f32_16x16x32_bf16 v[64:67], v[182:185], v[214:217], v[64:67]
	v_mfma_f32_16x16x32_bf16 v[64:67], v[186:189], v[218:221], v[64:67]
	s_setprio 0
	s_add_i32 s67, s67, s16
	v_lshl_add_u64 v[166:167], v[166:167], 0, s[10:11]
	s_mov_b32 m0, s67
	ds_read_b128 v[190:193], v176 offset:49152
	ds_read_b128 v[194:197], v176 offset:50176
	ds_read_b128 v[198:201], v176 offset:51200
	ds_read_b128 v[202:205], v176 offset:52224
	ds_read_b128 v[206:209], v176 offset:53248
	ds_read_b128 v[210:213], v176 offset:54272
	ds_read_b128 v[214:217], v176 offset:55296
	ds_read_b128 v[218:221], v176 offset:56320
	global_load_lds_dwordx4 v[166:167], off
	s_add_i32 m0, s67, 0x2000
	s_add_u32 s68, s80, 0x40080
	v_lshl_add_u64 v[166:167], v[222:223], 0, s[10:11]
	s_addc_u32 s69, s81, 0
	s_add_i32 s67, s73, s16
	global_load_lds_dwordx4 v[166:167], off
	s_mov_b32 m0, s67
	v_lshl_add_u64 v[166:167], s[68:69], 0, v[132:133]
	global_load_lds_dwordx4 v[166:167], off
	s_add_i32 m0, s67, 0x2000
	v_lshl_add_u64 v[166:167], s[68:69], 0, v[128:129]
	global_load_lds_dwordx4 v[166:167], off
	s_mov_b32 m0, s23
	v_lshl_add_u64 v[166:167], v[224:225], 0, s[10:11]
	global_load_lds_dwordx4 v[166:167], off
	s_mov_b32 m0, s24
	v_lshl_add_u64 v[166:167], v[226:227], 0, s[10:11]
	global_load_lds_dwordx4 v[166:167], off
	s_waitcnt vmcnt(8) lgkmcnt(0)
	s_barrier
	s_setprio 1
	v_mfma_f32_16x16x32_bf16 v[60:63], v[146:149], v[190:193], v[60:63]
	v_mfma_f32_16x16x32_bf16 v[60:63], v[150:153], v[194:197], v[60:63]
	v_mfma_f32_16x16x32_bf16 v[52:55], v[154:157], v[190:193], v[52:55]
	v_mfma_f32_16x16x32_bf16 v[52:55], v[158:161], v[194:197], v[52:55]
	v_mfma_f32_16x16x32_bf16 v[44:47], v[146:149], v[198:201], v[44:47]
	v_mfma_f32_16x16x32_bf16 v[44:47], v[150:153], v[202:205], v[44:47]
	v_mfma_f32_16x16x32_bf16 v[36:39], v[154:157], v[198:201], v[36:39]
	v_mfma_f32_16x16x32_bf16 v[36:39], v[158:161], v[202:205], v[36:39]
	v_mfma_f32_16x16x32_bf16 v[28:31], v[146:149], v[206:209], v[28:31]
	v_mfma_f32_16x16x32_bf16 v[28:31], v[150:153], v[210:213], v[28:31]
	v_mfma_f32_16x16x32_bf16 v[20:23], v[154:157], v[206:209], v[20:23]
	v_mfma_f32_16x16x32_bf16 v[20:23], v[158:161], v[210:213], v[20:23]
	v_mfma_f32_16x16x32_bf16 v[12:15], v[146:149], v[214:217], v[12:15]
	v_mfma_f32_16x16x32_bf16 v[12:15], v[150:153], v[218:221], v[12:15]
	v_mfma_f32_16x16x32_bf16 v[4:7], v[154:157], v[214:217], v[4:7]
	v_mfma_f32_16x16x32_bf16 v[4:7], v[158:161], v[218:221], v[4:7]
	v_mfma_f32_16x16x32_bf16 v[56:59], v[162:165], v[190:193], v[56:59]
	v_mfma_f32_16x16x32_bf16 v[56:59], v[178:181], v[194:197], v[56:59]
	v_mfma_f32_16x16x32_bf16 v[48:51], v[182:185], v[190:193], v[48:51]
	v_mfma_f32_16x16x32_bf16 v[48:51], v[186:189], v[194:197], v[48:51]
	v_mfma_f32_16x16x32_bf16 v[40:43], v[162:165], v[198:201], v[40:43]
	v_mfma_f32_16x16x32_bf16 v[40:43], v[178:181], v[202:205], v[40:43]
	v_mfma_f32_16x16x32_bf16 v[32:35], v[182:185], v[198:201], v[32:35]
	v_mfma_f32_16x16x32_bf16 v[32:35], v[186:189], v[202:205], v[32:35]
	v_mfma_f32_16x16x32_bf16 v[24:27], v[162:165], v[206:209], v[24:27]
	v_mfma_f32_16x16x32_bf16 v[24:27], v[178:181], v[210:213], v[24:27]
	v_mfma_f32_16x16x32_bf16 v[16:19], v[182:185], v[206:209], v[16:19]
	v_mfma_f32_16x16x32_bf16 v[16:19], v[186:189], v[210:213], v[16:19]
	v_mfma_f32_16x16x32_bf16 v[8:11], v[162:165], v[214:217], v[8:11]
	s_setprio 3
	s_barrier
	v_mfma_f32_16x16x32_bf16 v[8:11], v[178:181], v[218:221], v[8:11]
	v_mfma_f32_16x16x32_bf16 v[0:3], v[182:185], v[214:217], v[0:3]
	v_mfma_f32_16x16x32_bf16 v[0:3], v[186:189], v[218:221], v[0:3]
	s_setprio 0
	s_add_i32 s66, s66, 2
	s_add_u32 s78, s78, 0x100
	s_addc_u32 s79, s79, 0
	s_add_u32 s58, s58, 0x100
	s_addc_u32 s59, s59, 0
	s_cmp_gt_u32 s66, 13
	s_cbranch_scc0 .LBB0_1148
	s_branch .Lzskip_4
.Lzv_4_0:
	v_mfma_f32_16x16x32_bf16 v[124:127], v[146:149], v[190:193], 0
	v_mfma_f32_16x16x32_bf16 v[124:127], v[150:153], v[194:197], v[124:127]
	v_mfma_f32_16x16x32_bf16 v[116:119], v[154:157], v[190:193], 0
	v_mfma_f32_16x16x32_bf16 v[116:119], v[158:161], v[194:197], v[116:119]
	v_mfma_f32_16x16x32_bf16 v[108:111], v[146:149], v[198:201], 0
	v_mfma_f32_16x16x32_bf16 v[108:111], v[150:153], v[202:205], v[108:111]
	v_mfma_f32_16x16x32_bf16 v[100:103], v[154:157], v[198:201], 0
	v_mfma_f32_16x16x32_bf16 v[100:103], v[158:161], v[202:205], v[100:103]
	v_mfma_f32_16x16x32_bf16 v[92:95], v[146:149], v[206:209], 0
	v_mfma_f32_16x16x32_bf16 v[92:95], v[150:153], v[210:213], v[92:95]
	v_mfma_f32_16x16x32_bf16 v[84:87], v[154:157], v[206:209], 0
	v_mfma_f32_16x16x32_bf16 v[84:87], v[158:161], v[210:213], v[84:87]
	v_mfma_f32_16x16x32_bf16 v[76:79], v[146:149], v[214:217], 0
	v_mfma_f32_16x16x32_bf16 v[76:79], v[150:153], v[218:221], v[76:79]
	v_mfma_f32_16x16x32_bf16 v[68:71], v[154:157], v[214:217], 0
	v_mfma_f32_16x16x32_bf16 v[68:71], v[158:161], v[218:221], v[68:71]
	v_mfma_f32_16x16x32_bf16 v[120:123], v[162:165], v[190:193], 0
	v_mfma_f32_16x16x32_bf16 v[120:123], v[178:181], v[194:197], v[120:123]
	v_mfma_f32_16x16x32_bf16 v[112:115], v[182:185], v[190:193], 0
	v_mfma_f32_16x16x32_bf16 v[112:115], v[186:189], v[194:197], v[112:115]
	v_mfma_f32_16x16x32_bf16 v[104:107], v[162:165], v[198:201], 0
	v_mfma_f32_16x16x32_bf16 v[104:107], v[178:181], v[202:205], v[104:107]
	v_mfma_f32_16x16x32_bf16 v[96:99], v[182:185], v[198:201], 0
	v_mfma_f32_16x16x32_bf16 v[96:99], v[186:189], v[202:205], v[96:99]
	v_mfma_f32_16x16x32_bf16 v[88:91], v[162:165], v[206:209], 0
	v_mfma_f32_16x16x32_bf16 v[88:91], v[178:181], v[210:213], v[88:91]
	v_mfma_f32_16x16x32_bf16 v[80:83], v[182:185], v[206:209], 0
	v_mfma_f32_16x16x32_bf16 v[80:83], v[186:189], v[210:213], v[80:83]
	v_mfma_f32_16x16x32_bf16 v[72:75], v[162:165], v[214:217], 0
	s_setprio 3
	s_barrier
	v_mfma_f32_16x16x32_bf16 v[72:75], v[178:181], v[218:221], v[72:75]
	v_mfma_f32_16x16x32_bf16 v[64:67], v[182:185], v[214:217], 0
	v_mfma_f32_16x16x32_bf16 v[64:67], v[186:189], v[218:221], v[64:67]
	s_setprio 0
	s_branch .Lzj_4_0
.Lzv_4_1:
	v_mfma_f32_16x16x32_bf16 v[60:63], v[146:149], v[190:193], 0
	v_mfma_f32_16x16x32_bf16 v[60:63], v[150:153], v[194:197], v[60:63]
	v_mfma_f32_16x16x32_bf16 v[52:55], v[154:157], v[190:193], 0
	v_mfma_f32_16x16x32_bf16 v[52:55], v[158:161], v[194:197], v[52:55]
	v_mfma_f32_16x16x32_bf16 v[44:47], v[146:149], v[198:201], 0
	v_mfma_f32_16x16x32_bf16 v[44:47], v[150:153], v[202:205], v[44:47]
	v_mfma_f32_16x16x32_bf16 v[36:39], v[154:157], v[198:201], 0
	v_mfma_f32_16x16x32_bf16 v[36:39], v[158:161], v[202:205], v[36:39]
	v_mfma_f32_16x16x32_bf16 v[28:31], v[146:149], v[206:209], 0
	v_mfma_f32_16x16x32_bf16 v[28:31], v[150:153], v[210:213], v[28:31]
	v_mfma_f32_16x16x32_bf16 v[20:23], v[154:157], v[206:209], 0
	v_mfma_f32_16x16x32_bf16 v[20:23], v[158:161], v[210:213], v[20:23]
	v_mfma_f32_16x16x32_bf16 v[12:15], v[146:149], v[214:217], 0
	v_mfma_f32_16x16x32_bf16 v[12:15], v[150:153], v[218:221], v[12:15]
	v_mfma_f32_16x16x32_bf16 v[4:7], v[154:157], v[214:217], 0
	v_mfma_f32_16x16x32_bf16 v[4:7], v[158:161], v[218:221], v[4:7]
	v_mfma_f32_16x16x32_bf16 v[56:59], v[162:165], v[190:193], 0
	v_mfma_f32_16x16x32_bf16 v[56:59], v[178:181], v[194:197], v[56:59]
	v_mfma_f32_16x16x32_bf16 v[48:51], v[182:185], v[190:193], 0
	v_mfma_f32_16x16x32_bf16 v[48:51], v[186:189], v[194:197], v[48:51]
	v_mfma_f32_16x16x32_bf16 v[40:43], v[162:165], v[198:201], 0
	v_mfma_f32_16x16x32_bf16 v[40:43], v[178:181], v[202:205], v[40:43]
	v_mfma_f32_16x16x32_bf16 v[32:35], v[182:185], v[198:201], 0
	v_mfma_f32_16x16x32_bf16 v[32:35], v[186:189], v[202:205], v[32:35]
	v_mfma_f32_16x16x32_bf16 v[24:27], v[162:165], v[206:209], 0
	v_mfma_f32_16x16x32_bf16 v[24:27], v[178:181], v[210:213], v[24:27]
	v_mfma_f32_16x16x32_bf16 v[16:19], v[182:185], v[206:209], 0
	v_mfma_f32_16x16x32_bf16 v[16:19], v[186:189], v[210:213], v[16:19]
	v_mfma_f32_16x16x32_bf16 v[8:11], v[162:165], v[214:217], 0
	s_setprio 3
	s_barrier
	v_mfma_f32_16x16x32_bf16 v[8:11], v[178:181], v[218:221], v[8:11]
	v_mfma_f32_16x16x32_bf16 v[0:3], v[182:185], v[214:217], 0
	v_mfma_f32_16x16x32_bf16 v[0:3], v[186:189], v[218:221], v[0:3]
	s_setprio 0
	s_branch .Lzj_4_1

.LBB0_1299:
	ds_read_b128 v[120:123], v245
	ds_read_b128 v[124:127], v245 offset:1024
	ds_read_b128 v[128:131], v245 offset:2048
	ds_read_b128 v[132:135], v245 offset:3072
	ds_read_b128 v[144:147], v246
	ds_read_b128 v[148:151], v246 offset:1024
	ds_read_b128 v[152:155], v246 offset:2048
	ds_read_b128 v[156:159], v246 offset:3072
	s_add_u32 s66, s76, 0xfff50080
	s_addc_u32 s67, s77, -1
	s_cmp_eq_u32 s59, 40
	s_cselect_b32 s81, s9, s67
	s_cselect_b32 s80, s8, s66
	s_cselect_b32 s79, s53, s58
	s_cselect_b32 s78, s52, s55
	v_lshl_add_u64 v[204:205], s[76:77], 0, v[200:201]
	s_add_i32 m0, s16, 0xc000
	ds_read_b128 v[160:163], v247
	ds_read_b128 v[164:167], v247 offset:1024
	ds_read_b128 v[168:171], v247 offset:2048
	ds_read_b128 v[172:175], v247 offset:3072
	ds_read_b128 v[176:179], v247 offset:4096
	ds_read_b128 v[180:183], v247 offset:5120
	ds_read_b128 v[184:187], v247 offset:6144
	ds_read_b128 v[188:191], v247 offset:7168
	global_load_lds_dwordx4 v[204:205], off
	s_add_i32 m0, s16, 0xe000
	v_lshl_add_u64 v[204:205], s[76:77], 0, v[202:203]
	global_load_lds_dwordx4 v[204:205], off
	s_cmp_eq_u32 s59, -2
	s_waitcnt vmcnt(8) lgkmcnt(0)
	s_barrier
	s_setprio 1
	s_cbranch_scc1 .Lzv_5_0
	v_mfma_f32_16x16x32_bf16 v[140:143], v[120:123], v[160:163], v[140:143]
	v_mfma_f32_16x16x32_bf16 v[140:143], v[124:127], v[164:167], v[140:143]
	v_mfma_f32_16x16x32_bf16 v[136:139], v[128:131], v[160:163], v[136:139]
	v_mfma_f32_16x16x32_bf16 v[136:139], v[132:135], v[164:167], v[136:139]
	v_mfma_f32_16x16x32_bf16 v[108:111], v[120:123], v[168:171], v[108:111]
	v_mfma_f32_16x16x32_bf16 v[108:111], v[124:127], v[172:175], v[108:111]
	v_mfma_f32_16x16x32_bf16 v[104:107], v[128:131], v[168:171], v[104:107]
	v_mfma_f32_16x16x32_bf16 v[104:107], v[132:135], v[172:175], v[104:107]
	v_mfma_f32_16x16x32_bf16 v[92:95], v[120:123], v[176:179], v[92:95]
	v_mfma_f32_16x16x32_bf16 v[92:95], v[124:127], v[180:183], v[92:95]
	v_mfma_f32_16x16x32_bf16 v[88:91], v[128:131], v[176:179], v[88:91]
	v_mfma_f32_16x16x32_bf16 v[88:91], v[132:135], v[180:183], v[88:91]
	v_mfma_f32_16x16x32_bf16 v[76:79], v[120:123], v[184:187], v[76:79]
	v_mfma_f32_16x16x32_bf16 v[76:79], v[124:127], v[188:191], v[76:79]
	v_mfma_f32_16x16x32_bf16 v[72:75], v[128:131], v[184:187], v[72:75]
	v_mfma_f32_16x16x32_bf16 v[72:75], v[132:135], v[188:191], v[72:75]
	v_mfma_f32_16x16x32_bf16 v[116:119], v[144:147], v[160:163], v[116:119]
	v_mfma_f32_16x16x32_bf16 v[116:119], v[148:151], v[164:167], v[116:119]
	v_mfma_f32_16x16x32_bf16 v[112:115], v[152:155], v[160:163], v[112:115]
	v_mfma_f32_16x16x32_bf16 v[112:115], v[156:159], v[164:167], v[112:115]
	v_mfma_f32_16x16x32_bf16 v[100:103], v[144:147], v[168:171], v[100:103]
	v_mfma_f32_16x16x32_bf16 v[100:103], v[148:151], v[172:175], v[100:103]
	v_mfma_f32_16x16x32_bf16 v[96:99], v[152:155], v[168:171], v[96:99]
	v_mfma_f32_16x16x32_bf16 v[96:99], v[156:159], v[172:175], v[96:99]
	v_mfma_f32_16x16x32_bf16 v[84:87], v[144:147], v[176:179], v[84:87]
	v_mfma_f32_16x16x32_bf16 v[84:87], v[148:151], v[180:183], v[84:87]
	v_mfma_f32_16x16x32_bf16 v[80:83], v[152:155], v[176:179], v[80:83]
	v_mfma_f32_16x16x32_bf16 v[80:83], v[156:159], v[180:183], v[80:83]
	v_mfma_f32_16x16x32_bf16 v[68:71], v[144:147], v[184:187], v[68:71]
	s_setprio 3
	s_barrier
	v_mfma_f32_16x16x32_bf16 v[68:71], v[148:151], v[188:191], v[68:71]
	v_mfma_f32_16x16x32_bf16 v[64:67], v[152:155], v[184:187], v[64:67]
	v_mfma_f32_16x16x32_bf16 v[64:67], v[156:159], v[188:191], v[64:67]
	s_setprio 0
.Lzj_5_0:
	s_add_i32 s66, s26, s15
	v_lshl_add_u64 v[204:205], s[78:79], 0, v[194:195]
	s_mov_b32 m0, s66
	ds_read_b128 v[160:163], v247 offset:16384
	ds_read_b128 v[164:167], v247 offset:17408
	ds_read_b128 v[168:171], v247 offset:18432
	ds_read_b128 v[172:175], v247 offset:19456
	ds_read_b128 v[176:179], v247 offset:20480
	ds_read_b128 v[180:183], v247 offset:21504
	ds_read_b128 v[184:187], v247 offset:22528
	ds_read_b128 v[188:191], v247 offset:23552
	global_load_lds_dwordx4 v[204:205], off
	s_add_i32 m0, s66, 0x2000
	s_add_u32 s66, s78, 0xb0000
	v_lshl_add_u64 v[206:207], s[78:79], 0, v[198:199]
	s_addc_u32 s67, s79, 0
	s_add_i32 s68, s27, s15
	global_load_lds_dwordx4 v[206:207], off
	v_lshl_add_u64 v[208:209], s[66:67], 0, v[194:195]
	s_mov_b32 m0, s68
	global_load_lds_dwordx4 v[208:209], off
	s_add_i32 m0, s68, 0x2000
	v_lshl_add_u64 v[208:209], s[66:67], 0, v[198:199]
	global_load_lds_dwordx4 v[208:209], off
	s_mov_b32 m0, s16
	v_lshl_add_u64 v[208:209], s[80:81], 0, v[192:193]
	global_load_lds_dwordx4 v[208:209], off
	s_mov_b32 m0, s17
	v_lshl_add_u64 v[210:211], s[80:81], 0, v[196:197]
	global_load_lds_dwordx4 v[210:211], off
	s_cmp_eq_u32 s59, -2
	s_waitcnt vmcnt(8) lgkmcnt(0)
	s_barrier
	s_setprio 1
	s_cbranch_scc1 .Lzv_5_1
	v_mfma_f32_16x16x32_bf16 v[60:63], v[120:123], v[160:163], v[60:63]
	v_mfma_f32_16x16x32_bf16 v[60:63], v[124:127], v[164:167], v[60:63]
	v_mfma_f32_16x16x32_bf16 v[56:59], v[128:131], v[160:163], v[56:59]
	v_mfma_f32_16x16x32_bf16 v[56:59], v[132:135], v[164:167], v[56:59]
	v_mfma_f32_16x16x32_bf16 v[44:47], v[120:123], v[168:171], v[44:47]
	v_mfma_f32_16x16x32_bf16 v[44:47], v[124:127], v[172:175], v[44:47]
	v_mfma_f32_16x16x32_bf16 v[40:43], v[128:131], v[168:171], v[40:43]
	v_mfma_f32_16x16x32_bf16 v[40:43], v[132:135], v[172:175], v[40:43]
	v_mfma_f32_16x16x32_bf16 v[28:31], v[120:123], v[176:179], v[28:31]
	v_mfma_f32_16x16x32_bf16 v[28:31], v[124:127], v[180:183], v[28:31]
	v_mfma_f32_16x16x32_bf16 v[24:27], v[128:131], v[176:179], v[24:27]
	v_mfma_f32_16x16x32_bf16 v[24:27], v[132:135], v[180:183], v[24:27]
	v_mfma_f32_16x16x32_bf16 v[12:15], v[120:123], v[184:187], v[12:15]
	v_mfma_f32_16x16x32_bf16 v[12:15], v[124:127], v[188:191], v[12:15]
	v_mfma_f32_16x16x32_bf16 v[8:11], v[128:131], v[184:187], v[8:11]
	v_mfma_f32_16x16x32_bf16 v[8:11], v[132:135], v[188:191], v[8:11]
	v_mfma_f32_16x16x32_bf16 v[52:55], v[144:147], v[160:163], v[52:55]
	v_mfma_f32_16x16x32_bf16 v[52:55], v[148:151], v[164:167], v[52:55]
	v_mfma_f32_16x16x32_bf16 v[48:51], v[152:155], v[160:163], v[48:51]
	v_mfma_f32_16x16x32_bf16 v[48:51], v[156:159], v[164:167], v[48:51]
	v_mfma_f32_16x16x32_bf16 v[36:39], v[144:147], v[168:171], v[36:39]
	v_mfma_f32_16x16x32_bf16 v[36:39], v[148:151], v[172:175], v[36:39]
	v_mfma_f32_16x16x32_bf16 v[32:35], v[152:155], v[168:171], v[32:35]
	v_mfma_f32_16x16x32_bf16 v[32:35], v[156:159], v[172:175], v[32:35]
	v_mfma_f32_16x16x32_bf16 v[20:23], v[144:147], v[176:179], v[20:23]
	v_mfma_f32_16x16x32_bf16 v[20:23], v[148:151], v[180:183], v[20:23]
	v_mfma_f32_16x16x32_bf16 v[16:19], v[152:155], v[176:179], v[16:19]
	v_mfma_f32_16x16x32_bf16 v[16:19], v[156:159], v[180:183], v[16:19]
	v_mfma_f32_16x16x32_bf16 v[4:7], v[144:147], v[184:187], v[4:7]
	s_setprio 3
	s_barrier
	v_mfma_f32_16x16x32_bf16 v[4:7], v[148:151], v[188:191], v[4:7]
	v_mfma_f32_16x16x32_bf16 v[0:3], v[152:155], v[184:187], v[0:3]
	v_mfma_f32_16x16x32_bf16 v[0:3], v[156:159], v[188:191], v[0:3]
	s_setprio 0
.Lzj_5_1:
	s_add_i32 s68, 0, 0x18000
	s_add_i32 s69, 0, 0x1c000
	v_add_u32_e32 v132, s68, v243
	v_add_u32_e32 v156, s69, v243
	ds_read_b128 v[120:123], v132
	ds_read_b128 v[124:127], v132 offset:1024
	ds_read_b128 v[128:131], v132 offset:2048
	ds_read_b128 v[132:135], v132 offset:3072
	ds_read_b128 v[144:147], v156
	ds_read_b128 v[148:151], v156 offset:1024
	ds_read_b128 v[152:155], v156 offset:2048
	ds_read_b128 v[156:159], v156 offset:3072
	s_add_u32 s66, s80, 0xb0000
	s_addc_u32 s67, s81, 0
	s_mov_b32 m0, s18
	v_lshl_add_u64 v[212:213], s[66:67], 0, v[192:193]
	ds_read_b128 v[160:163], v247 offset:32768
	ds_read_b128 v[164:167], v247 offset:33792
	ds_read_b128 v[168:171], v247 offset:34816
	ds_read_b128 v[172:175], v247 offset:35840
	ds_read_b128 v[176:179], v247 offset:36864
	ds_read_b128 v[180:183], v247 offset:37888
	ds_read_b128 v[184:187], v247 offset:38912
	ds_read_b128 v[188:191], v247 offset:39936
	global_load_lds_dwordx4 v[212:213], off
	s_mov_b32 m0, s19
	v_lshl_add_u64 v[212:213], s[66:67], 0, v[196:197]
	global_load_lds_dwordx4 v[212:213], off
	s_waitcnt vmcnt(8) lgkmcnt(0)
	s_barrier
	s_setprio 1
	v_mfma_f32_16x16x32_bf16 v[140:143], v[120:123], v[160:163], v[140:143]
	v_mfma_f32_16x16x32_bf16 v[140:143], v[124:127], v[164:167], v[140:143]
	v_mfma_f32_16x16x32_bf16 v[136:139], v[128:131], v[160:163], v[136:139]
	v_mfma_f32_16x16x32_bf16 v[136:139], v[132:135], v[164:167], v[136:139]
	v_mfma_f32_16x16x32_bf16 v[108:111], v[120:123], v[168:171], v[108:111]
	v_mfma_f32_16x16x32_bf16 v[108:111], v[124:127], v[172:175], v[108:111]
	v_mfma_f32_16x16x32_bf16 v[104:107], v[128:131], v[168:171], v[104:107]
	v_mfma_f32_16x16x32_bf16 v[104:107], v[132:135], v[172:175], v[104:107]
	v_mfma_f32_16x16x32_bf16 v[92:95], v[120:123], v[176:179], v[92:95]
	v_mfma_f32_16x16x32_bf16 v[92:95], v[124:127], v[180:183], v[92:95]
	v_mfma_f32_16x16x32_bf16 v[88:91], v[128:131], v[176:179], v[88:91]
	v_mfma_f32_16x16x32_bf16 v[88:91], v[132:135], v[180:183], v[88:91]
	v_mfma_f32_16x16x32_bf16 v[76:79], v[120:123], v[184:187], v[76:79]
	v_mfma_f32_16x16x32_bf16 v[76:79], v[124:127], v[188:191], v[76:79]
	v_mfma_f32_16x16x32_bf16 v[72:75], v[128:131], v[184:187], v[72:75]
	v_mfma_f32_16x16x32_bf16 v[72:75], v[132:135], v[188:191], v[72:75]
	v_mfma_f32_16x16x32_bf16 v[116:119], v[144:147], v[160:163], v[116:119]
	v_mfma_f32_16x16x32_bf16 v[116:119], v[148:151], v[164:167], v[116:119]
	v_mfma_f32_16x16x32_bf16 v[112:115], v[152:155], v[160:163], v[112:115]
	v_mfma_f32_16x16x32_bf16 v[112:115], v[156:159], v[164:167], v[112:115]
	v_mfma_f32_16x16x32_bf16 v[100:103], v[144:147], v[168:171], v[100:103]
	v_mfma_f32_16x16x32_bf16 v[100:103], v[148:151], v[172:175], v[100:103]
	v_mfma_f32_16x16x32_bf16 v[96:99], v[152:155], v[168:171], v[96:99]
	v_mfma_f32_16x16x32_bf16 v[96:99], v[156:159], v[172:175], v[96:99]
	v_mfma_f32_16x16x32_bf16 v[84:87], v[144:147], v[176:179], v[84:87]
	v_mfma_f32_16x16x32_bf16 v[84:87], v[148:151], v[180:183], v[84:87]
	v_mfma_f32_16x16x32_bf16 v[80:83], v[152:155], v[176:179], v[80:83]
	v_mfma_f32_16x16x32_bf16 v[80:83], v[156:159], v[180:183], v[80:83]
	v_mfma_f32_16x16x32_bf16 v[68:71], v[144:147], v[184:187], v[68:71]
	s_setprio 3
	s_barrier
	v_mfma_f32_16x16x32_bf16 v[68:71], v[148:151], v[188:191], v[68:71]
	v_mfma_f32_16x16x32_bf16 v[64:67], v[152:155], v[184:187], v[64:67]
	v_mfma_f32_16x16x32_bf16 v[64:67], v[156:159], v[188:191], v[64:67]
	s_setprio 0
	s_add_i32 s66, s68, s15
	v_lshl_add_u64 v[204:205], v[204:205], 0, s[48:49]
	s_mov_b32 m0, s66
	ds_read_b128 v[160:163], v247 offset:49152
	ds_read_b128 v[164:167], v247 offset:50176
	ds_read_b128 v[168:171], v247 offset:51200
	ds_read_b128 v[172:175], v247 offset:52224
	ds_read_b128 v[176:179], v247 offset:53248
	ds_read_b128 v[180:183], v247 offset:54272
	ds_read_b128 v[184:187], v247 offset:55296
	ds_read_b128 v[188:191], v247 offset:56320
	global_load_lds_dwordx4 v[204:205], off
	s_add_i32 m0, s66, 0x2000
	s_add_u32 s66, s78, 0xb0080
	v_lshl_add_u64 v[204:205], v[206:207], 0, s[48:49]
	s_addc_u32 s67, s79, 0
	s_add_i32 s68, s69, s15
	global_load_lds_dwordx4 v[204:205], off
	s_mov_b32 m0, s68
	v_lshl_add_u64 v[204:205], s[66:67], 0, v[194:195]
	global_load_lds_dwordx4 v[204:205], off
	s_add_i32 m0, s68, 0x2000
	v_lshl_add_u64 v[204:205], s[66:67], 0, v[198:199]
	global_load_lds_dwordx4 v[204:205], off
	s_mov_b32 m0, s21
	v_lshl_add_u64 v[204:205], v[208:209], 0, s[48:49]
	global_load_lds_dwordx4 v[204:205], off
	s_mov_b32 m0, s22
	v_lshl_add_u64 v[204:205], v[210:211], 0, s[48:49]
	global_load_lds_dwordx4 v[204:205], off
	s_waitcnt vmcnt(8) lgkmcnt(0)
	s_barrier
	s_setprio 1
	v_mfma_f32_16x16x32_bf16 v[60:63], v[120:123], v[160:163], v[60:63]
	v_mfma_f32_16x16x32_bf16 v[60:63], v[124:127], v[164:167], v[60:63]
	v_mfma_f32_16x16x32_bf16 v[56:59], v[128:131], v[160:163], v[56:59]
	v_mfma_f32_16x16x32_bf16 v[56:59], v[132:135], v[164:167], v[56:59]
	v_mfma_f32_16x16x32_bf16 v[44:47], v[120:123], v[168:171], v[44:47]
	v_mfma_f32_16x16x32_bf16 v[44:47], v[124:127], v[172:175], v[44:47]
	v_mfma_f32_16x16x32_bf16 v[40:43], v[128:131], v[168:171], v[40:43]
	v_mfma_f32_16x16x32_bf16 v[40:43], v[132:135], v[172:175], v[40:43]
	v_mfma_f32_16x16x32_bf16 v[28:31], v[120:123], v[176:179], v[28:31]
	v_mfma_f32_16x16x32_bf16 v[28:31], v[124:127], v[180:183], v[28:31]
	v_mfma_f32_16x16x32_bf16 v[24:27], v[128:131], v[176:179], v[24:27]
	v_mfma_f32_16x16x32_bf16 v[24:27], v[132:135], v[180:183], v[24:27]
	v_mfma_f32_16x16x32_bf16 v[12:15], v[120:123], v[184:187], v[12:15]
	v_mfma_f32_16x16x32_bf16 v[12:15], v[124:127], v[188:191], v[12:15]
	v_mfma_f32_16x16x32_bf16 v[8:11], v[128:131], v[184:187], v[8:11]
	v_mfma_f32_16x16x32_bf16 v[8:11], v[132:135], v[188:191], v[8:11]
	v_mfma_f32_16x16x32_bf16 v[52:55], v[144:147], v[160:163], v[52:55]
	v_mfma_f32_16x16x32_bf16 v[52:55], v[148:151], v[164:167], v[52:55]
	v_mfma_f32_16x16x32_bf16 v[48:51], v[152:155], v[160:163], v[48:51]
	v_mfma_f32_16x16x32_bf16 v[48:51], v[156:159], v[164:167], v[48:51]
	v_mfma_f32_16x16x32_bf16 v[36:39], v[144:147], v[168:171], v[36:39]
	v_mfma_f32_16x16x32_bf16 v[36:39], v[148:151], v[172:175], v[36:39]
	v_mfma_f32_16x16x32_bf16 v[32:35], v[152:155], v[168:171], v[32:35]
	v_mfma_f32_16x16x32_bf16 v[32:35], v[156:159], v[172:175], v[32:35]
	v_mfma_f32_16x16x32_bf16 v[20:23], v[144:147], v[176:179], v[20:23]
	v_mfma_f32_16x16x32_bf16 v[20:23], v[148:151], v[180:183], v[20:23]
	v_mfma_f32_16x16x32_bf16 v[16:19], v[152:155], v[176:179], v[16:19]
	v_mfma_f32_16x16x32_bf16 v[16:19], v[156:159], v[180:183], v[16:19]
	v_mfma_f32_16x16x32_bf16 v[4:7], v[144:147], v[184:187], v[4:7]
	s_setprio 3
	s_barrier
	v_mfma_f32_16x16x32_bf16 v[4:7], v[148:151], v[188:191], v[4:7]
	v_mfma_f32_16x16x32_bf16 v[0:3], v[152:155], v[184:187], v[0:3]
	v_mfma_f32_16x16x32_bf16 v[0:3], v[156:159], v[188:191], v[0:3]
	s_setprio 0
	s_add_i32 s59, s59, 2
	s_add_u32 s76, s76, 0x100
	s_addc_u32 s77, s77, 0
	s_add_u32 s55, s55, 0x100
	s_addc_u32 s58, s58, 0
	s_cmp_gt_u32 s59, 41
	s_cbranch_scc0 .LBB0_1299
	s_branch .Lzskip_5

.LBB0_1760:
	ds_read_b128 v[128:131], v181
	ds_read_b128 v[132:135], v181 offset:1024
	ds_read_b128 v[136:139], v181 offset:2048
	ds_read_b128 v[160:163], v181 offset:3072
	ds_read_b128 v[164:167], v182
	ds_read_b128 v[168:171], v182 offset:1024
	ds_read_b128 v[186:189], v182 offset:2048
	ds_read_b128 v[190:193], v182 offset:3072
	s_add_u32 s69, s78, 0xfffc0080
	s_addc_u32 s73, s79, -1
	s_cmp_eq_u32 s68, 12
	s_cselect_b32 s83, s49, s73
	s_cselect_b32 s82, s54, s69
	s_cselect_b32 s81, s47, s67
	s_cselect_b32 s80, s55, s66
	v_lshl_add_u64 v[172:173], s[78:79], 0, v[152:153]
	s_add_i32 m0, s18, 0xc000
	ds_read_b128 v[194:197], v183
	ds_read_b128 v[198:201], v183 offset:1024
	ds_read_b128 v[202:205], v183 offset:2048
	ds_read_b128 v[206:209], v183 offset:3072
	ds_read_b128 v[210:213], v183 offset:4096
	ds_read_b128 v[214:217], v183 offset:5120
	ds_read_b128 v[218:221], v183 offset:6144
	ds_read_b128 v[222:225], v183 offset:7168
	global_load_lds_dwordx4 v[172:173], off
	s_add_i32 m0, s18, 0xe000
	v_lshl_add_u64 v[172:173], s[78:79], 0, v[154:155]
	global_load_lds_dwordx4 v[172:173], off
	s_cmp_eq_u32 s68, -2
	s_waitcnt vmcnt(8) lgkmcnt(0)
	s_barrier
	s_setprio 1
	s_cbranch_scc1 .Lzv_8_0
	v_mfma_f32_16x16x32_bf16 v[124:127], v[128:131], v[194:197], v[124:127]
	v_mfma_f32_16x16x32_bf16 v[124:127], v[132:135], v[198:201], v[124:127]
	v_mfma_f32_16x16x32_bf16 v[120:123], v[136:139], v[194:197], v[120:123]
	v_mfma_f32_16x16x32_bf16 v[120:123], v[160:163], v[198:201], v[120:123]
	v_mfma_f32_16x16x32_bf16 v[108:111], v[128:131], v[202:205], v[108:111]
	v_mfma_f32_16x16x32_bf16 v[108:111], v[132:135], v[206:209], v[108:111]
	v_mfma_f32_16x16x32_bf16 v[104:107], v[136:139], v[202:205], v[104:107]
	v_mfma_f32_16x16x32_bf16 v[104:107], v[160:163], v[206:209], v[104:107]
	v_mfma_f32_16x16x32_bf16 v[92:95], v[128:131], v[210:213], v[92:95]
	v_mfma_f32_16x16x32_bf16 v[92:95], v[132:135], v[214:217], v[92:95]
	v_mfma_f32_16x16x32_bf16 v[88:91], v[136:139], v[210:213], v[88:91]
	v_mfma_f32_16x16x32_bf16 v[88:91], v[160:163], v[214:217], v[88:91]
	v_mfma_f32_16x16x32_bf16 v[76:79], v[128:131], v[218:221], v[76:79]
	v_mfma_f32_16x16x32_bf16 v[76:79], v[132:135], v[222:225], v[76:79]
	v_mfma_f32_16x16x32_bf16 v[72:75], v[136:139], v[218:221], v[72:75]
	v_mfma_f32_16x16x32_bf16 v[72:75], v[160:163], v[222:225], v[72:75]
	v_mfma_f32_16x16x32_bf16 v[116:119], v[164:167], v[194:197], v[116:119]
	v_mfma_f32_16x16x32_bf16 v[116:119], v[168:171], v[198:201], v[116:119]
	v_mfma_f32_16x16x32_bf16 v[112:115], v[186:189], v[194:197], v[112:115]
	v_mfma_f32_16x16x32_bf16 v[112:115], v[190:193], v[198:201], v[112:115]
	v_mfma_f32_16x16x32_bf16 v[100:103], v[164:167], v[202:205], v[100:103]
	v_mfma_f32_16x16x32_bf16 v[100:103], v[168:171], v[206:209], v[100:103]
	v_mfma_f32_16x16x32_bf16 v[96:99], v[186:189], v[202:205], v[96:99]
	v_mfma_f32_16x16x32_bf16 v[96:99], v[190:193], v[206:209], v[96:99]
	v_mfma_f32_16x16x32_bf16 v[84:87], v[164:167], v[210:213], v[84:87]
	v_mfma_f32_16x16x32_bf16 v[84:87], v[168:171], v[214:217], v[84:87]
	v_mfma_f32_16x16x32_bf16 v[80:83], v[186:189], v[210:213], v[80:83]
	v_mfma_f32_16x16x32_bf16 v[80:83], v[190:193], v[214:217], v[80:83]
	v_mfma_f32_16x16x32_bf16 v[68:71], v[164:167], v[218:221], v[68:71]
	s_setprio 3
	s_barrier
	v_mfma_f32_16x16x32_bf16 v[68:71], v[168:171], v[222:225], v[68:71]
	v_mfma_f32_16x16x32_bf16 v[64:67], v[186:189], v[218:221], v[64:67]
	v_mfma_f32_16x16x32_bf16 v[64:67], v[190:193], v[222:225], v[64:67]
	s_setprio 0
.Lzj_8_0:
	s_add_i32 s69, s25, s17
	v_lshl_add_u64 v[172:173], s[80:81], 0, v[142:143]
	s_mov_b32 m0, s69
	ds_read_b128 v[194:197], v183 offset:16384
	ds_read_b128 v[198:201], v183 offset:17408
	ds_read_b128 v[202:205], v183 offset:18432
	ds_read_b128 v[206:209], v183 offset:19456
	ds_read_b128 v[210:213], v183 offset:20480
	ds_read_b128 v[214:217], v183 offset:21504
	ds_read_b128 v[218:221], v183 offset:22528
	ds_read_b128 v[222:225], v183 offset:23552
	global_load_lds_dwordx4 v[172:173], off
	s_add_i32 m0, s69, 0x2000
	s_add_u32 s84, s80, 0x40000
	v_lshl_add_u64 v[226:227], s[80:81], 0, v[146:147]
	s_addc_u32 s85, s81, 0
	s_add_i32 s69, s26, s17
	global_load_lds_dwordx4 v[226:227], off
	v_lshl_add_u64 v[228:229], s[84:85], 0, v[142:143]
	s_mov_b32 m0, s69
	global_load_lds_dwordx4 v[228:229], off
	s_add_i32 m0, s69, 0x2000
	v_lshl_add_u64 v[228:229], s[84:85], 0, v[146:147]
	global_load_lds_dwordx4 v[228:229], off
	s_mov_b32 m0, s18
	v_lshl_add_u64 v[228:229], s[82:83], 0, v[140:141]
	global_load_lds_dwordx4 v[228:229], off
	s_mov_b32 m0, s19
	v_lshl_add_u64 v[230:231], s[82:83], 0, v[144:145]
	global_load_lds_dwordx4 v[230:231], off
	s_cmp_eq_u32 s68, -2
	s_waitcnt vmcnt(8) lgkmcnt(0)
	s_barrier
	s_setprio 1
	s_cbranch_scc1 .Lzv_8_1
	v_mfma_f32_16x16x32_bf16 v[60:63], v[128:131], v[194:197], v[60:63]
	v_mfma_f32_16x16x32_bf16 v[60:63], v[132:135], v[198:201], v[60:63]
	v_mfma_f32_16x16x32_bf16 v[56:59], v[136:139], v[194:197], v[56:59]
	v_mfma_f32_16x16x32_bf16 v[56:59], v[160:163], v[198:201], v[56:59]
	v_mfma_f32_16x16x32_bf16 v[44:47], v[128:131], v[202:205], v[44:47]
	v_mfma_f32_16x16x32_bf16 v[44:47], v[132:135], v[206:209], v[44:47]
	v_mfma_f32_16x16x32_bf16 v[40:43], v[136:139], v[202:205], v[40:43]
	v_mfma_f32_16x16x32_bf16 v[40:43], v[160:163], v[206:209], v[40:43]
	v_mfma_f32_16x16x32_bf16 v[28:31], v[128:131], v[210:213], v[28:31]
	v_mfma_f32_16x16x32_bf16 v[28:31], v[132:135], v[214:217], v[28:31]
	v_mfma_f32_16x16x32_bf16 v[24:27], v[136:139], v[210:213], v[24:27]
	v_mfma_f32_16x16x32_bf16 v[24:27], v[160:163], v[214:217], v[24:27]
	v_mfma_f32_16x16x32_bf16 v[12:15], v[128:131], v[218:221], v[12:15]
	v_mfma_f32_16x16x32_bf16 v[12:15], v[132:135], v[222:225], v[12:15]
	v_mfma_f32_16x16x32_bf16 v[8:11], v[136:139], v[218:221], v[8:11]
	v_mfma_f32_16x16x32_bf16 v[8:11], v[160:163], v[222:225], v[8:11]
	v_mfma_f32_16x16x32_bf16 v[52:55], v[164:167], v[194:197], v[52:55]
	v_mfma_f32_16x16x32_bf16 v[52:55], v[168:171], v[198:201], v[52:55]
	v_mfma_f32_16x16x32_bf16 v[48:51], v[186:189], v[194:197], v[48:51]
	v_mfma_f32_16x16x32_bf16 v[48:51], v[190:193], v[198:201], v[48:51]
	v_mfma_f32_16x16x32_bf16 v[36:39], v[164:167], v[202:205], v[36:39]
	v_mfma_f32_16x16x32_bf16 v[36:39], v[168:171], v[206:209], v[36:39]
	v_mfma_f32_16x16x32_bf16 v[32:35], v[186:189], v[202:205], v[32:35]
	v_mfma_f32_16x16x32_bf16 v[32:35], v[190:193], v[206:209], v[32:35]
	v_mfma_f32_16x16x32_bf16 v[20:23], v[164:167], v[210:213], v[20:23]
	v_mfma_f32_16x16x32_bf16 v[20:23], v[168:171], v[214:217], v[20:23]
	v_mfma_f32_16x16x32_bf16 v[16:19], v[186:189], v[210:213], v[16:19]
	v_mfma_f32_16x16x32_bf16 v[16:19], v[190:193], v[214:217], v[16:19]
	v_mfma_f32_16x16x32_bf16 v[4:7], v[164:167], v[218:221], v[4:7]
	s_setprio 3
	s_barrier
	v_mfma_f32_16x16x32_bf16 v[4:7], v[168:171], v[222:225], v[4:7]
	v_mfma_f32_16x16x32_bf16 v[0:3], v[186:189], v[218:221], v[0:3]
	v_mfma_f32_16x16x32_bf16 v[0:3], v[190:193], v[222:225], v[0:3]
	s_setprio 0
.Lzj_8_1:
	s_add_i32 s69, 0, 0x18000
	v_add_u32_e32 v148, s69, v177
	s_add_i32 s73, 0, 0x1c000
	ds_read_b128 v[128:131], v148
	ds_read_b128 v[132:135], v148 offset:1024
	ds_read_b128 v[136:139], v148 offset:2048
	ds_read_b128 v[160:163], v148 offset:3072
	v_add_u32_e32 v148, s73, v177
	ds_read_b128 v[164:167], v148
	ds_read_b128 v[168:171], v148 offset:1024
	ds_read_b128 v[186:189], v148 offset:2048
	ds_read_b128 v[190:193], v148 offset:3072
	s_add_u32 s82, s82, 0x40000
	s_addc_u32 s83, s83, 0
	s_mov_b32 m0, s20
	v_lshl_add_u64 v[232:233], s[82:83], 0, v[140:141]
	ds_read_b128 v[194:197], v183 offset:32768
	ds_read_b128 v[198:201], v183 offset:33792
	ds_read_b128 v[202:205], v183 offset:34816
	ds_read_b128 v[206:209], v183 offset:35840
	ds_read_b128 v[210:213], v183 offset:36864
	ds_read_b128 v[214:217], v183 offset:37888
	ds_read_b128 v[218:221], v183 offset:38912
	ds_read_b128 v[222:225], v183 offset:39936
	global_load_lds_dwordx4 v[232:233], off
	s_mov_b32 m0, s21
	v_lshl_add_u64 v[232:233], s[82:83], 0, v[144:145]
	global_load_lds_dwordx4 v[232:233], off
	s_waitcnt vmcnt(8) lgkmcnt(0)
	s_barrier
	s_setprio 1
	v_mfma_f32_16x16x32_bf16 v[124:127], v[128:131], v[194:197], v[124:127]
	v_mfma_f32_16x16x32_bf16 v[124:127], v[132:135], v[198:201], v[124:127]
	v_mfma_f32_16x16x32_bf16 v[120:123], v[136:139], v[194:197], v[120:123]
	v_mfma_f32_16x16x32_bf16 v[120:123], v[160:163], v[198:201], v[120:123]
	v_mfma_f32_16x16x32_bf16 v[108:111], v[128:131], v[202:205], v[108:111]
	v_mfma_f32_16x16x32_bf16 v[108:111], v[132:135], v[206:209], v[108:111]
	v_mfma_f32_16x16x32_bf16 v[104:107], v[136:139], v[202:205], v[104:107]
	v_mfma_f32_16x16x32_bf16 v[104:107], v[160:163], v[206:209], v[104:107]
	v_mfma_f32_16x16x32_bf16 v[92:95], v[128:131], v[210:213], v[92:95]
	v_mfma_f32_16x16x32_bf16 v[92:95], v[132:135], v[214:217], v[92:95]
	v_mfma_f32_16x16x32_bf16 v[88:91], v[136:139], v[210:213], v[88:91]
	v_mfma_f32_16x16x32_bf16 v[88:91], v[160:163], v[214:217], v[88:91]
	v_mfma_f32_16x16x32_bf16 v[76:79], v[128:131], v[218:221], v[76:79]
	v_mfma_f32_16x16x32_bf16 v[76:79], v[132:135], v[222:225], v[76:79]
	v_mfma_f32_16x16x32_bf16 v[72:75], v[136:139], v[218:221], v[72:75]
	v_mfma_f32_16x16x32_bf16 v[72:75], v[160:163], v[222:225], v[72:75]
	v_mfma_f32_16x16x32_bf16 v[116:119], v[164:167], v[194:197], v[116:119]
	v_mfma_f32_16x16x32_bf16 v[116:119], v[168:171], v[198:201], v[116:119]
	v_mfma_f32_16x16x32_bf16 v[112:115], v[186:189], v[194:197], v[112:115]
	v_mfma_f32_16x16x32_bf16 v[112:115], v[190:193], v[198:201], v[112:115]
	v_mfma_f32_16x16x32_bf16 v[100:103], v[164:167], v[202:205], v[100:103]
	v_mfma_f32_16x16x32_bf16 v[100:103], v[168:171], v[206:209], v[100:103]
	v_mfma_f32_16x16x32_bf16 v[96:99], v[186:189], v[202:205], v[96:99]
	v_mfma_f32_16x16x32_bf16 v[96:99], v[190:193], v[206:209], v[96:99]
	v_mfma_f32_16x16x32_bf16 v[84:87], v[164:167], v[210:213], v[84:87]
	v_mfma_f32_16x16x32_bf16 v[84:87], v[168:171], v[214:217], v[84:87]
	v_mfma_f32_16x16x32_bf16 v[80:83], v[186:189], v[210:213], v[80:83]
	v_mfma_f32_16x16x32_bf16 v[80:83], v[190:193], v[214:217], v[80:83]
	v_mfma_f32_16x16x32_bf16 v[68:71], v[164:167], v[218:221], v[68:71]
	s_setprio 3
	s_barrier
	v_mfma_f32_16x16x32_bf16 v[68:71], v[168:171], v[222:225], v[68:71]
	v_mfma_f32_16x16x32_bf16 v[64:67], v[186:189], v[218:221], v[64:67]
	v_mfma_f32_16x16x32_bf16 v[64:67], v[190:193], v[222:225], v[64:67]
	s_setprio 0
	s_add_i32 s69, s69, s17
	v_lshl_add_u64 v[172:173], v[172:173], 0, s[10:11]
	s_mov_b32 m0, s69
	ds_read_b128 v[194:197], v183 offset:49152
	ds_read_b128 v[198:201], v183 offset:50176
	ds_read_b128 v[202:205], v183 offset:51200
	ds_read_b128 v[206:209], v183 offset:52224
	ds_read_b128 v[210:213], v183 offset:53248
	ds_read_b128 v[214:217], v183 offset:54272
	ds_read_b128 v[218:221], v183 offset:55296
	ds_read_b128 v[222:225], v183 offset:56320
	global_load_lds_dwordx4 v[172:173], off
	s_add_i32 m0, s69, 0x2000
	s_add_u32 s80, s80, 0x40080
	v_lshl_add_u64 v[172:173], v[226:227], 0, s[10:11]
	s_addc_u32 s81, s81, 0
	s_add_i32 s69, s73, s17
	global_load_lds_dwordx4 v[172:173], off
	s_mov_b32 m0, s69
	v_lshl_add_u64 v[172:173], s[80:81], 0, v[142:143]
	global_load_lds_dwordx4 v[172:173], off
	s_add_i32 m0, s69, 0x2000
	v_lshl_add_u64 v[172:173], s[80:81], 0, v[146:147]
	global_load_lds_dwordx4 v[172:173], off
	s_mov_b32 m0, s23
	v_lshl_add_u64 v[172:173], v[228:229], 0, s[10:11]
	global_load_lds_dwordx4 v[172:173], off
	s_mov_b32 m0, s24
	v_lshl_add_u64 v[172:173], v[230:231], 0, s[10:11]
	global_load_lds_dwordx4 v[172:173], off
	s_waitcnt vmcnt(8) lgkmcnt(0)
	s_barrier
	s_setprio 1
	v_mfma_f32_16x16x32_bf16 v[60:63], v[128:131], v[194:197], v[60:63]
	v_mfma_f32_16x16x32_bf16 v[60:63], v[132:135], v[198:201], v[60:63]
	v_mfma_f32_16x16x32_bf16 v[56:59], v[136:139], v[194:197], v[56:59]
	v_mfma_f32_16x16x32_bf16 v[56:59], v[160:163], v[198:201], v[56:59]
	v_mfma_f32_16x16x32_bf16 v[44:47], v[128:131], v[202:205], v[44:47]
	v_mfma_f32_16x16x32_bf16 v[44:47], v[132:135], v[206:209], v[44:47]
	v_mfma_f32_16x16x32_bf16 v[40:43], v[136:139], v[202:205], v[40:43]
	v_mfma_f32_16x16x32_bf16 v[40:43], v[160:163], v[206:209], v[40:43]
	v_mfma_f32_16x16x32_bf16 v[28:31], v[128:131], v[210:213], v[28:31]
	v_mfma_f32_16x16x32_bf16 v[28:31], v[132:135], v[214:217], v[28:31]
	v_mfma_f32_16x16x32_bf16 v[24:27], v[136:139], v[210:213], v[24:27]
	v_mfma_f32_16x16x32_bf16 v[24:27], v[160:163], v[214:217], v[24:27]
	v_mfma_f32_16x16x32_bf16 v[12:15], v[128:131], v[218:221], v[12:15]
	v_mfma_f32_16x16x32_bf16 v[12:15], v[132:135], v[222:225], v[12:15]
	v_mfma_f32_16x16x32_bf16 v[8:11], v[136:139], v[218:221], v[8:11]
	v_mfma_f32_16x16x32_bf16 v[8:11], v[160:163], v[222:225], v[8:11]
	v_mfma_f32_16x16x32_bf16 v[52:55], v[164:167], v[194:197], v[52:55]
	v_mfma_f32_16x16x32_bf16 v[52:55], v[168:171], v[198:201], v[52:55]
	v_mfma_f32_16x16x32_bf16 v[48:51], v[186:189], v[194:197], v[48:51]
	v_mfma_f32_16x16x32_bf16 v[48:51], v[190:193], v[198:201], v[48:51]
	v_mfma_f32_16x16x32_bf16 v[36:39], v[164:167], v[202:205], v[36:39]
	v_mfma_f32_16x16x32_bf16 v[36:39], v[168:171], v[206:209], v[36:39]
	v_mfma_f32_16x16x32_bf16 v[32:35], v[186:189], v[202:205], v[32:35]
	v_mfma_f32_16x16x32_bf16 v[32:35], v[190:193], v[206:209], v[32:35]
	v_mfma_f32_16x16x32_bf16 v[20:23], v[164:167], v[210:213], v[20:23]
	v_mfma_f32_16x16x32_bf16 v[20:23], v[168:171], v[214:217], v[20:23]
	v_mfma_f32_16x16x32_bf16 v[16:19], v[186:189], v[210:213], v[16:19]
	v_mfma_f32_16x16x32_bf16 v[16:19], v[190:193], v[214:217], v[16:19]
	v_mfma_f32_16x16x32_bf16 v[4:7], v[164:167], v[218:221], v[4:7]
	s_setprio 3
	s_barrier
	v_mfma_f32_16x16x32_bf16 v[4:7], v[168:171], v[222:225], v[4:7]
	v_mfma_f32_16x16x32_bf16 v[0:3], v[186:189], v[218:221], v[0:3]
	v_mfma_f32_16x16x32_bf16 v[0:3], v[190:193], v[222:225], v[0:3]
	s_setprio 0
	s_add_i32 s68, s68, 2
	s_add_u32 s78, s78, 0x100
	s_addc_u32 s79, s79, 0
	s_add_u32 s66, s66, 0x100
	s_addc_u32 s67, s67, 0
	s_cmp_gt_u32 s68, 13
	s_cbranch_scc0 .LBB0_1760
	s_branch .Lzskip_8
.Lzv_8_0:
	v_mfma_f32_16x16x32_bf16 v[124:127], v[128:131], v[194:197], 0
	v_mfma_f32_16x16x32_bf16 v[124:127], v[132:135], v[198:201], v[124:127]
	v_mfma_f32_16x16x32_bf16 v[120:123], v[136:139], v[194:197], 0
	v_mfma_f32_16x16x32_bf16 v[120:123], v[160:163], v[198:201], v[120:123]
	v_mfma_f32_16x16x32_bf16 v[108:111], v[128:131], v[202:205], 0
	v_mfma_f32_16x16x32_bf16 v[108:111], v[132:135], v[206:209], v[108:111]
	v_mfma_f32_16x16x32_bf16 v[104:107], v[136:139], v[202:205], 0
	v_mfma_f32_16x16x32_bf16 v[104:107], v[160:163], v[206:209], v[104:107]
	v_mfma_f32_16x16x32_bf16 v[92:95], v[128:131], v[210:213], 0
	v_mfma_f32_16x16x32_bf16 v[92:95], v[132:135], v[214:217], v[92:95]
	v_mfma_f32_16x16x32_bf16 v[88:91], v[136:139], v[210:213], 0
	v_mfma_f32_16x16x32_bf16 v[88:91], v[160:163], v[214:217], v[88:91]
	v_mfma_f32_16x16x32_bf16 v[76:79], v[128:131], v[218:221], 0
	v_mfma_f32_16x16x32_bf16 v[76:79], v[132:135], v[222:225], v[76:79]
	v_mfma_f32_16x16x32_bf16 v[72:75], v[136:139], v[218:221], 0
	v_mfma_f32_16x16x32_bf16 v[72:75], v[160:163], v[222:225], v[72:75]
	v_mfma_f32_16x16x32_bf16 v[116:119], v[164:167], v[194:197], 0
	v_mfma_f32_16x16x32_bf16 v[116:119], v[168:171], v[198:201], v[116:119]
	v_mfma_f32_16x16x32_bf16 v[112:115], v[186:189], v[194:197], 0
	v_mfma_f32_16x16x32_bf16 v[112:115], v[190:193], v[198:201], v[112:115]
	v_mfma_f32_16x16x32_bf16 v[100:103], v[164:167], v[202:205], 0
	v_mfma_f32_16x16x32_bf16 v[100:103], v[168:171], v[206:209], v[100:103]
	v_mfma_f32_16x16x32_bf16 v[96:99], v[186:189], v[202:205], 0
	v_mfma_f32_16x16x32_bf16 v[96:99], v[190:193], v[206:209], v[96:99]
	v_mfma_f32_16x16x32_bf16 v[84:87], v[164:167], v[210:213], 0
	v_mfma_f32_16x16x32_bf16 v[84:87], v[168:171], v[214:217], v[84:87]
	v_mfma_f32_16x16x32_bf16 v[80:83], v[186:189], v[210:213], 0
	v_mfma_f32_16x16x32_bf16 v[80:83], v[190:193], v[214:217], v[80:83]
	v_mfma_f32_16x16x32_bf16 v[68:71], v[164:167], v[218:221], 0
	s_setprio 3
	s_barrier
	v_mfma_f32_16x16x32_bf16 v[68:71], v[168:171], v[222:225], v[68:71]
	v_mfma_f32_16x16x32_bf16 v[64:67], v[186:189], v[218:221], 0
	v_mfma_f32_16x16x32_bf16 v[64:67], v[190:193], v[222:225], v[64:67]
	s_setprio 0
	s_branch .Lzj_8_0
.Lzv_8_1:
	v_mfma_f32_16x16x32_bf16 v[60:63], v[128:131], v[194:197], 0
	v_mfma_f32_16x16x32_bf16 v[60:63], v[132:135], v[198:201], v[60:63]
	v_mfma_f32_16x16x32_bf16 v[56:59], v[136:139], v[194:197], 0
	v_mfma_f32_16x16x32_bf16 v[56:59], v[160:163], v[198:201], v[56:59]
	v_mfma_f32_16x16x32_bf16 v[44:47], v[128:131], v[202:205], 0
	v_mfma_f32_16x16x32_bf16 v[44:47], v[132:135], v[206:209], v[44:47]
	v_mfma_f32_16x16x32_bf16 v[40:43], v[136:139], v[202:205], 0
	v_mfma_f32_16x16x32_bf16 v[40:43], v[160:163], v[206:209], v[40:43]
	v_mfma_f32_16x16x32_bf16 v[28:31], v[128:131], v[210:213], 0
	v_mfma_f32_16x16x32_bf16 v[28:31], v[132:135], v[214:217], v[28:31]
	v_mfma_f32_16x16x32_bf16 v[24:27], v[136:139], v[210:213], 0
	v_mfma_f32_16x16x32_bf16 v[24:27], v[160:163], v[214:217], v[24:27]
	v_mfma_f32_16x16x32_bf16 v[12:15], v[128:131], v[218:221], 0
	v_mfma_f32_16x16x32_bf16 v[12:15], v[132:135], v[222:225], v[12:15]
	v_mfma_f32_16x16x32_bf16 v[8:11], v[136:139], v[218:221], 0
	v_mfma_f32_16x16x32_bf16 v[8:11], v[160:163], v[222:225], v[8:11]
	v_mfma_f32_16x16x32_bf16 v[52:55], v[164:167], v[194:197], 0
	v_mfma_f32_16x16x32_bf16 v[52:55], v[168:171], v[198:201], v[52:55]
	v_mfma_f32_16x16x32_bf16 v[48:51], v[186:189], v[194:197], 0
	v_mfma_f32_16x16x32_bf16 v[48:51], v[190:193], v[198:201], v[48:51]
	v_mfma_f32_16x16x32_bf16 v[36:39], v[164:167], v[202:205], 0
	v_mfma_f32_16x16x32_bf16 v[36:39], v[168:171], v[206:209], v[36:39]
	v_mfma_f32_16x16x32_bf16 v[32:35], v[186:189], v[202:205], 0
	v_mfma_f32_16x16x32_bf16 v[32:35], v[190:193], v[206:209], v[32:35]
	v_mfma_f32_16x16x32_bf16 v[20:23], v[164:167], v[210:213], 0
	v_mfma_f32_16x16x32_bf16 v[20:23], v[168:171], v[214:217], v[20:23]
	v_mfma_f32_16x16x32_bf16 v[16:19], v[186:189], v[210:213], 0
	v_mfma_f32_16x16x32_bf16 v[16:19], v[190:193], v[214:217], v[16:19]
	v_mfma_f32_16x16x32_bf16 v[4:7], v[164:167], v[218:221], 0
	s_setprio 3
	s_barrier
	v_mfma_f32_16x16x32_bf16 v[4:7], v[168:171], v[222:225], v[4:7]
	v_mfma_f32_16x16x32_bf16 v[0:3], v[186:189], v[218:221], 0
	v_mfma_f32_16x16x32_bf16 v[0:3], v[190:193], v[222:225], v[0:3]
	s_setprio 0
	s_branch .Lzj_8_1

.LBB0_2037:
	ds_read_b128 v[120:123], v245
	ds_read_b128 v[124:127], v245 offset:1024
	ds_read_b128 v[128:131], v245 offset:2048
	ds_read_b128 v[132:135], v245 offset:3072
	ds_read_b128 v[144:147], v246
	ds_read_b128 v[148:151], v246 offset:1024
	ds_read_b128 v[152:155], v246 offset:2048
	ds_read_b128 v[156:159], v246 offset:3072
	s_add_u32 s67, s76, 0xfffc0080
	s_addc_u32 s68, s77, -1
	s_cmp_eq_u32 s66, 12
	s_cselect_b32 s81, s53, s68
	s_cselect_b32 s80, s54, s67
	s_cselect_b32 s79, s51, s57
	s_cselect_b32 s78, s55, s56
	v_lshl_add_u64 v[204:205], s[76:77], 0, v[200:201]
	s_add_i32 m0, s16, 0xc000
	ds_read_b128 v[160:163], v247
	ds_read_b128 v[164:167], v247 offset:1024
	ds_read_b128 v[168:171], v247 offset:2048
	ds_read_b128 v[172:175], v247 offset:3072
	ds_read_b128 v[176:179], v247 offset:4096
	ds_read_b128 v[180:183], v247 offset:5120
	ds_read_b128 v[184:187], v247 offset:6144
	ds_read_b128 v[188:191], v247 offset:7168
	global_load_lds_dwordx4 v[204:205], off
	s_add_i32 m0, s16, 0xe000
	v_lshl_add_u64 v[204:205], s[76:77], 0, v[202:203]
	global_load_lds_dwordx4 v[204:205], off
	s_cmp_eq_u32 s66, -2
	s_waitcnt vmcnt(8) lgkmcnt(0)
	s_barrier
	s_setprio 1
	s_cbranch_scc1 .Lzv_9_0
	v_mfma_f32_16x16x32_bf16 v[140:143], v[120:123], v[160:163], v[140:143]
	v_mfma_f32_16x16x32_bf16 v[140:143], v[124:127], v[164:167], v[140:143]
	v_mfma_f32_16x16x32_bf16 v[136:139], v[128:131], v[160:163], v[136:139]
	v_mfma_f32_16x16x32_bf16 v[136:139], v[132:135], v[164:167], v[136:139]
	v_mfma_f32_16x16x32_bf16 v[108:111], v[120:123], v[168:171], v[108:111]
	v_mfma_f32_16x16x32_bf16 v[108:111], v[124:127], v[172:175], v[108:111]
	v_mfma_f32_16x16x32_bf16 v[104:107], v[128:131], v[168:171], v[104:107]
	v_mfma_f32_16x16x32_bf16 v[104:107], v[132:135], v[172:175], v[104:107]
	v_mfma_f32_16x16x32_bf16 v[92:95], v[120:123], v[176:179], v[92:95]
	v_mfma_f32_16x16x32_bf16 v[92:95], v[124:127], v[180:183], v[92:95]
	v_mfma_f32_16x16x32_bf16 v[88:91], v[128:131], v[176:179], v[88:91]
	v_mfma_f32_16x16x32_bf16 v[88:91], v[132:135], v[180:183], v[88:91]
	v_mfma_f32_16x16x32_bf16 v[76:79], v[120:123], v[184:187], v[76:79]
	v_mfma_f32_16x16x32_bf16 v[76:79], v[124:127], v[188:191], v[76:79]
	v_mfma_f32_16x16x32_bf16 v[72:75], v[128:131], v[184:187], v[72:75]
	v_mfma_f32_16x16x32_bf16 v[72:75], v[132:135], v[188:191], v[72:75]
	v_mfma_f32_16x16x32_bf16 v[116:119], v[144:147], v[160:163], v[116:119]
	v_mfma_f32_16x16x32_bf16 v[116:119], v[148:151], v[164:167], v[116:119]
	v_mfma_f32_16x16x32_bf16 v[112:115], v[152:155], v[160:163], v[112:115]
	v_mfma_f32_16x16x32_bf16 v[112:115], v[156:159], v[164:167], v[112:115]
	v_mfma_f32_16x16x32_bf16 v[100:103], v[144:147], v[168:171], v[100:103]
	v_mfma_f32_16x16x32_bf16 v[100:103], v[148:151], v[172:175], v[100:103]
	v_mfma_f32_16x16x32_bf16 v[96:99], v[152:155], v[168:171], v[96:99]
	v_mfma_f32_16x16x32_bf16 v[96:99], v[156:159], v[172:175], v[96:99]
	v_mfma_f32_16x16x32_bf16 v[84:87], v[144:147], v[176:179], v[84:87]
	v_mfma_f32_16x16x32_bf16 v[84:87], v[148:151], v[180:183], v[84:87]
	v_mfma_f32_16x16x32_bf16 v[80:83], v[152:155], v[176:179], v[80:83]
	v_mfma_f32_16x16x32_bf16 v[80:83], v[156:159], v[180:183], v[80:83]
	v_mfma_f32_16x16x32_bf16 v[68:71], v[144:147], v[184:187], v[68:71]
	s_setprio 3
	s_barrier
	v_mfma_f32_16x16x32_bf16 v[68:71], v[148:151], v[188:191], v[68:71]
	v_mfma_f32_16x16x32_bf16 v[64:67], v[152:155], v[184:187], v[64:67]
	v_mfma_f32_16x16x32_bf16 v[64:67], v[156:159], v[188:191], v[64:67]
	s_setprio 0
.Lzj_9_0:
	s_add_i32 s67, s26, s15
	v_lshl_add_u64 v[204:205], s[78:79], 0, v[194:195]
	s_mov_b32 m0, s67
	ds_read_b128 v[160:163], v247 offset:16384
	ds_read_b128 v[164:167], v247 offset:17408
	ds_read_b128 v[168:171], v247 offset:18432
	ds_read_b128 v[172:175], v247 offset:19456
	ds_read_b128 v[176:179], v247 offset:20480
	ds_read_b128 v[180:183], v247 offset:21504
	ds_read_b128 v[184:187], v247 offset:22528
	ds_read_b128 v[188:191], v247 offset:23552
	global_load_lds_dwordx4 v[204:205], off
	s_add_i32 m0, s67, 0x2000
	s_add_u32 s68, s78, 0x40000
	v_lshl_add_u64 v[206:207], s[78:79], 0, v[198:199]
	s_addc_u32 s69, s79, 0
	s_add_i32 s67, s27, s15
	global_load_lds_dwordx4 v[206:207], off
	v_lshl_add_u64 v[208:209], s[68:69], 0, v[194:195]
	s_mov_b32 m0, s67
	global_load_lds_dwordx4 v[208:209], off
	s_add_i32 m0, s67, 0x2000
	v_lshl_add_u64 v[208:209], s[68:69], 0, v[198:199]
	global_load_lds_dwordx4 v[208:209], off
	s_mov_b32 m0, s16
	v_lshl_add_u64 v[208:209], s[80:81], 0, v[192:193]
	global_load_lds_dwordx4 v[208:209], off
	s_mov_b32 m0, s17
	v_lshl_add_u64 v[210:211], s[80:81], 0, v[196:197]
	global_load_lds_dwordx4 v[210:211], off
	s_cmp_eq_u32 s66, -2
	s_waitcnt vmcnt(8) lgkmcnt(0)
	s_barrier
	s_setprio 1
	s_cbranch_scc1 .Lzv_9_1
	v_mfma_f32_16x16x32_bf16 v[60:63], v[120:123], v[160:163], v[60:63]
	v_mfma_f32_16x16x32_bf16 v[60:63], v[124:127], v[164:167], v[60:63]
	v_mfma_f32_16x16x32_bf16 v[56:59], v[128:131], v[160:163], v[56:59]
	v_mfma_f32_16x16x32_bf16 v[56:59], v[132:135], v[164:167], v[56:59]
	v_mfma_f32_16x16x32_bf16 v[44:47], v[120:123], v[168:171], v[44:47]
	v_mfma_f32_16x16x32_bf16 v[44:47], v[124:127], v[172:175], v[44:47]
	v_mfma_f32_16x16x32_bf16 v[40:43], v[128:131], v[168:171], v[40:43]
	v_mfma_f32_16x16x32_bf16 v[40:43], v[132:135], v[172:175], v[40:43]
	v_mfma_f32_16x16x32_bf16 v[28:31], v[120:123], v[176:179], v[28:31]
	v_mfma_f32_16x16x32_bf16 v[28:31], v[124:127], v[180:183], v[28:31]
	v_mfma_f32_16x16x32_bf16 v[24:27], v[128:131], v[176:179], v[24:27]
	v_mfma_f32_16x16x32_bf16 v[24:27], v[132:135], v[180:183], v[24:27]
	v_mfma_f32_16x16x32_bf16 v[12:15], v[120:123], v[184:187], v[12:15]
	v_mfma_f32_16x16x32_bf16 v[12:15], v[124:127], v[188:191], v[12:15]
	v_mfma_f32_16x16x32_bf16 v[8:11], v[128:131], v[184:187], v[8:11]
	v_mfma_f32_16x16x32_bf16 v[8:11], v[132:135], v[188:191], v[8:11]
	v_mfma_f32_16x16x32_bf16 v[52:55], v[144:147], v[160:163], v[52:55]
	v_mfma_f32_16x16x32_bf16 v[52:55], v[148:151], v[164:167], v[52:55]
	v_mfma_f32_16x16x32_bf16 v[48:51], v[152:155], v[160:163], v[48:51]
	v_mfma_f32_16x16x32_bf16 v[48:51], v[156:159], v[164:167], v[48:51]
	v_mfma_f32_16x16x32_bf16 v[36:39], v[144:147], v[168:171], v[36:39]
	v_mfma_f32_16x16x32_bf16 v[36:39], v[148:151], v[172:175], v[36:39]
	v_mfma_f32_16x16x32_bf16 v[32:35], v[152:155], v[168:171], v[32:35]
	v_mfma_f32_16x16x32_bf16 v[32:35], v[156:159], v[172:175], v[32:35]
	v_mfma_f32_16x16x32_bf16 v[20:23], v[144:147], v[176:179], v[20:23]
	v_mfma_f32_16x16x32_bf16 v[20:23], v[148:151], v[180:183], v[20:23]
	v_mfma_f32_16x16x32_bf16 v[16:19], v[152:155], v[176:179], v[16:19]
	v_mfma_f32_16x16x32_bf16 v[16:19], v[156:159], v[180:183], v[16:19]
	v_mfma_f32_16x16x32_bf16 v[4:7], v[144:147], v[184:187], v[4:7]
	s_setprio 3
	s_barrier
	v_mfma_f32_16x16x32_bf16 v[4:7], v[148:151], v[188:191], v[4:7]
	v_mfma_f32_16x16x32_bf16 v[0:3], v[152:155], v[184:187], v[0:3]
	v_mfma_f32_16x16x32_bf16 v[0:3], v[156:159], v[188:191], v[0:3]
	s_setprio 0
.Lzj_9_1:
	s_add_i32 s67, 0, 0x18000
	s_add_i32 s75, 0, 0x1c000
	v_add_u32_e32 v132, s67, v243
	v_add_u32_e32 v156, s75, v243
	ds_read_b128 v[120:123], v132
	ds_read_b128 v[124:127], v132 offset:1024
	ds_read_b128 v[128:131], v132 offset:2048
	ds_read_b128 v[132:135], v132 offset:3072
	ds_read_b128 v[144:147], v156
	ds_read_b128 v[148:151], v156 offset:1024
	ds_read_b128 v[152:155], v156 offset:2048
	ds_read_b128 v[156:159], v156 offset:3072
	s_add_u32 s68, s80, 0x40000
	s_addc_u32 s69, s81, 0
	s_mov_b32 m0, s18
	v_lshl_add_u64 v[212:213], s[68:69], 0, v[192:193]
	ds_read_b128 v[160:163], v247 offset:32768
	ds_read_b128 v[164:167], v247 offset:33792
	ds_read_b128 v[168:171], v247 offset:34816
	ds_read_b128 v[172:175], v247 offset:35840
	ds_read_b128 v[176:179], v247 offset:36864
	ds_read_b128 v[180:183], v247 offset:37888
	ds_read_b128 v[184:187], v247 offset:38912
	ds_read_b128 v[188:191], v247 offset:39936
	global_load_lds_dwordx4 v[212:213], off
	s_mov_b32 m0, s19
	v_lshl_add_u64 v[212:213], s[68:69], 0, v[196:197]
	global_load_lds_dwordx4 v[212:213], off
	s_waitcnt vmcnt(8) lgkmcnt(0)
	s_barrier
	s_setprio 1
	v_mfma_f32_16x16x32_bf16 v[140:143], v[120:123], v[160:163], v[140:143]
	v_mfma_f32_16x16x32_bf16 v[140:143], v[124:127], v[164:167], v[140:143]
	v_mfma_f32_16x16x32_bf16 v[136:139], v[128:131], v[160:163], v[136:139]
	v_mfma_f32_16x16x32_bf16 v[136:139], v[132:135], v[164:167], v[136:139]
	v_mfma_f32_16x16x32_bf16 v[108:111], v[120:123], v[168:171], v[108:111]
	v_mfma_f32_16x16x32_bf16 v[108:111], v[124:127], v[172:175], v[108:111]
	v_mfma_f32_16x16x32_bf16 v[104:107], v[128:131], v[168:171], v[104:107]
	v_mfma_f32_16x16x32_bf16 v[104:107], v[132:135], v[172:175], v[104:107]
	v_mfma_f32_16x16x32_bf16 v[92:95], v[120:123], v[176:179], v[92:95]
	v_mfma_f32_16x16x32_bf16 v[92:95], v[124:127], v[180:183], v[92:95]
	v_mfma_f32_16x16x32_bf16 v[88:91], v[128:131], v[176:179], v[88:91]
	v_mfma_f32_16x16x32_bf16 v[88:91], v[132:135], v[180:183], v[88:91]
	v_mfma_f32_16x16x32_bf16 v[76:79], v[120:123], v[184:187], v[76:79]
	v_mfma_f32_16x16x32_bf16 v[76:79], v[124:127], v[188:191], v[76:79]
	v_mfma_f32_16x16x32_bf16 v[72:75], v[128:131], v[184:187], v[72:75]
	v_mfma_f32_16x16x32_bf16 v[72:75], v[132:135], v[188:191], v[72:75]
	v_mfma_f32_16x16x32_bf16 v[116:119], v[144:147], v[160:163], v[116:119]
	v_mfma_f32_16x16x32_bf16 v[116:119], v[148:151], v[164:167], v[116:119]
	v_mfma_f32_16x16x32_bf16 v[112:115], v[152:155], v[160:163], v[112:115]
	v_mfma_f32_16x16x32_bf16 v[112:115], v[156:159], v[164:167], v[112:115]
	v_mfma_f32_16x16x32_bf16 v[100:103], v[144:147], v[168:171], v[100:103]
	v_mfma_f32_16x16x32_bf16 v[100:103], v[148:151], v[172:175], v[100:103]
	v_mfma_f32_16x16x32_bf16 v[96:99], v[152:155], v[168:171], v[96:99]
	v_mfma_f32_16x16x32_bf16 v[96:99], v[156:159], v[172:175], v[96:99]
	v_mfma_f32_16x16x32_bf16 v[84:87], v[144:147], v[176:179], v[84:87]
	v_mfma_f32_16x16x32_bf16 v[84:87], v[148:151], v[180:183], v[84:87]
	v_mfma_f32_16x16x32_bf16 v[80:83], v[152:155], v[176:179], v[80:83]
	v_mfma_f32_16x16x32_bf16 v[80:83], v[156:159], v[180:183], v[80:83]
	v_mfma_f32_16x16x32_bf16 v[68:71], v[144:147], v[184:187], v[68:71]
	s_setprio 3
	s_barrier
	v_mfma_f32_16x16x32_bf16 v[68:71], v[148:151], v[188:191], v[68:71]
	v_mfma_f32_16x16x32_bf16 v[64:67], v[152:155], v[184:187], v[64:67]
	v_mfma_f32_16x16x32_bf16 v[64:67], v[156:159], v[188:191], v[64:67]
	s_setprio 0
	s_add_i32 s67, s67, s15
	v_lshl_add_u64 v[204:205], v[204:205], 0, s[46:47]
	s_mov_b32 m0, s67
	ds_read_b128 v[160:163], v247 offset:49152
	ds_read_b128 v[164:167], v247 offset:50176
	ds_read_b128 v[168:171], v247 offset:51200
	ds_read_b128 v[172:175], v247 offset:52224
	ds_read_b128 v[176:179], v247 offset:53248
	ds_read_b128 v[180:183], v247 offset:54272
	ds_read_b128 v[184:187], v247 offset:55296
	ds_read_b128 v[188:191], v247 offset:56320
	global_load_lds_dwordx4 v[204:205], off
	s_add_i32 m0, s67, 0x2000
	s_add_u32 s68, s78, 0x40080
	v_lshl_add_u64 v[204:205], v[206:207], 0, s[46:47]
	s_addc_u32 s69, s79, 0
	s_add_i32 s67, s75, s15
	global_load_lds_dwordx4 v[204:205], off
	s_mov_b32 m0, s67
	v_lshl_add_u64 v[204:205], s[68:69], 0, v[194:195]
	global_load_lds_dwordx4 v[204:205], off
	s_add_i32 m0, s67, 0x2000
	v_lshl_add_u64 v[204:205], s[68:69], 0, v[198:199]
	global_load_lds_dwordx4 v[204:205], off
	s_mov_b32 m0, s21
	v_lshl_add_u64 v[204:205], v[208:209], 0, s[46:47]
	global_load_lds_dwordx4 v[204:205], off
	s_mov_b32 m0, s22
	v_lshl_add_u64 v[204:205], v[210:211], 0, s[46:47]
	global_load_lds_dwordx4 v[204:205], off
	s_waitcnt vmcnt(8) lgkmcnt(0)
	s_barrier
	s_setprio 1
	v_mfma_f32_16x16x32_bf16 v[60:63], v[120:123], v[160:163], v[60:63]
	v_mfma_f32_16x16x32_bf16 v[60:63], v[124:127], v[164:167], v[60:63]
	v_mfma_f32_16x16x32_bf16 v[56:59], v[128:131], v[160:163], v[56:59]
	v_mfma_f32_16x16x32_bf16 v[56:59], v[132:135], v[164:167], v[56:59]
	v_mfma_f32_16x16x32_bf16 v[44:47], v[120:123], v[168:171], v[44:47]
	v_mfma_f32_16x16x32_bf16 v[44:47], v[124:127], v[172:175], v[44:47]
	v_mfma_f32_16x16x32_bf16 v[40:43], v[128:131], v[168:171], v[40:43]
	v_mfma_f32_16x16x32_bf16 v[40:43], v[132:135], v[172:175], v[40:43]
	v_mfma_f32_16x16x32_bf16 v[28:31], v[120:123], v[176:179], v[28:31]
	v_mfma_f32_16x16x32_bf16 v[28:31], v[124:127], v[180:183], v[28:31]
	v_mfma_f32_16x16x32_bf16 v[24:27], v[128:131], v[176:179], v[24:27]
	v_mfma_f32_16x16x32_bf16 v[24:27], v[132:135], v[180:183], v[24:27]
	v_mfma_f32_16x16x32_bf16 v[12:15], v[120:123], v[184:187], v[12:15]
	v_mfma_f32_16x16x32_bf16 v[12:15], v[124:127], v[188:191], v[12:15]
	v_mfma_f32_16x16x32_bf16 v[8:11], v[128:131], v[184:187], v[8:11]
	v_mfma_f32_16x16x32_bf16 v[8:11], v[132:135], v[188:191], v[8:11]
	v_mfma_f32_16x16x32_bf16 v[52:55], v[144:147], v[160:163], v[52:55]
	v_mfma_f32_16x16x32_bf16 v[52:55], v[148:151], v[164:167], v[52:55]
	v_mfma_f32_16x16x32_bf16 v[48:51], v[152:155], v[160:163], v[48:51]
	v_mfma_f32_16x16x32_bf16 v[48:51], v[156:159], v[164:167], v[48:51]
	v_mfma_f32_16x16x32_bf16 v[36:39], v[144:147], v[168:171], v[36:39]
	v_mfma_f32_16x16x32_bf16 v[36:39], v[148:151], v[172:175], v[36:39]
	v_mfma_f32_16x16x32_bf16 v[32:35], v[152:155], v[168:171], v[32:35]
	v_mfma_f32_16x16x32_bf16 v[32:35], v[156:159], v[172:175], v[32:35]
	v_mfma_f32_16x16x32_bf16 v[20:23], v[144:147], v[176:179], v[20:23]
	v_mfma_f32_16x16x32_bf16 v[20:23], v[148:151], v[180:183], v[20:23]
	v_mfma_f32_16x16x32_bf16 v[16:19], v[152:155], v[176:179], v[16:19]
	v_mfma_f32_16x16x32_bf16 v[16:19], v[156:159], v[180:183], v[16:19]
	v_mfma_f32_16x16x32_bf16 v[4:7], v[144:147], v[184:187], v[4:7]
	s_setprio 3
	s_barrier
	v_mfma_f32_16x16x32_bf16 v[4:7], v[148:151], v[188:191], v[4:7]
	v_mfma_f32_16x16x32_bf16 v[0:3], v[152:155], v[184:187], v[0:3]
	v_mfma_f32_16x16x32_bf16 v[0:3], v[156:159], v[188:191], v[0:3]
	s_setprio 0
	s_add_i32 s66, s66, 2
	s_add_u32 s76, s76, 0x100
	s_addc_u32 s77, s77, 0
	s_add_u32 s56, s56, 0x100
	s_addc_u32 s57, s57, 0
	s_cmp_gt_u32 s66, 13
	s_cbranch_scc0 .LBB0_2037
	s_branch .Lzskip_9

.LBB0_2192:
	ds_read_b128 v[146:149], v174
	ds_read_b128 v[150:153], v174 offset:1024
	ds_read_b128 v[154:157], v174 offset:2048
	ds_read_b128 v[158:161], v174 offset:3072
	ds_read_b128 v[162:165], v175
	ds_read_b128 v[178:181], v175 offset:1024
	ds_read_b128 v[182:185], v175 offset:2048
	ds_read_b128 v[186:189], v175 offset:3072
	s_add_u32 s70, s58, 0xfffc0080
	s_addc_u32 s71, s59, -1
	s_cmp_eq_u32 s69, 12
	s_cselect_b32 s73, s47, s71
	s_cselect_b32 s72, s53, s70
	s_cselect_b32 s71, s45, s68
	s_cselect_b32 s70, s66, s67
	v_lshl_add_u64 v[166:167], s[58:59], 0, v[136:137]
	s_add_i32 m0, s17, 0xc000
	ds_read_b128 v[190:193], v176
	ds_read_b128 v[194:197], v176 offset:1024
	ds_read_b128 v[198:201], v176 offset:2048
	ds_read_b128 v[202:205], v176 offset:3072
	ds_read_b128 v[206:209], v176 offset:4096
	ds_read_b128 v[210:213], v176 offset:5120
	ds_read_b128 v[214:217], v176 offset:6144
	ds_read_b128 v[218:221], v176 offset:7168
	global_load_lds_dwordx4 v[166:167], off
	s_add_i32 m0, s17, 0xe000
	v_lshl_add_u64 v[166:167], s[58:59], 0, v[140:141]
	global_load_lds_dwordx4 v[166:167], off
	s_cmp_eq_u32 s69, -2
	s_waitcnt vmcnt(8) lgkmcnt(0)
	s_barrier
	s_setprio 1
	s_cbranch_scc1 .Lzv_10_0
	v_mfma_f32_16x16x32_bf16 v[124:127], v[146:149], v[190:193], v[124:127]
	v_mfma_f32_16x16x32_bf16 v[124:127], v[150:153], v[194:197], v[124:127]
	v_mfma_f32_16x16x32_bf16 v[116:119], v[154:157], v[190:193], v[116:119]
	v_mfma_f32_16x16x32_bf16 v[116:119], v[158:161], v[194:197], v[116:119]
	v_mfma_f32_16x16x32_bf16 v[108:111], v[146:149], v[198:201], v[108:111]
	v_mfma_f32_16x16x32_bf16 v[108:111], v[150:153], v[202:205], v[108:111]
	v_mfma_f32_16x16x32_bf16 v[100:103], v[154:157], v[198:201], v[100:103]
	v_mfma_f32_16x16x32_bf16 v[100:103], v[158:161], v[202:205], v[100:103]
	v_mfma_f32_16x16x32_bf16 v[92:95], v[146:149], v[206:209], v[92:95]
	v_mfma_f32_16x16x32_bf16 v[92:95], v[150:153], v[210:213], v[92:95]
	v_mfma_f32_16x16x32_bf16 v[84:87], v[154:157], v[206:209], v[84:87]
	v_mfma_f32_16x16x32_bf16 v[84:87], v[158:161], v[210:213], v[84:87]
	v_mfma_f32_16x16x32_bf16 v[76:79], v[146:149], v[214:217], v[76:79]
	v_mfma_f32_16x16x32_bf16 v[76:79], v[150:153], v[218:221], v[76:79]
	v_mfma_f32_16x16x32_bf16 v[68:71], v[154:157], v[214:217], v[68:71]
	v_mfma_f32_16x16x32_bf16 v[68:71], v[158:161], v[218:221], v[68:71]
	v_mfma_f32_16x16x32_bf16 v[120:123], v[162:165], v[190:193], v[120:123]
	v_mfma_f32_16x16x32_bf16 v[120:123], v[178:181], v[194:197], v[120:123]
	v_mfma_f32_16x16x32_bf16 v[112:115], v[182:185], v[190:193], v[112:115]
	v_mfma_f32_16x16x32_bf16 v[112:115], v[186:189], v[194:197], v[112:115]
	v_mfma_f32_16x16x32_bf16 v[104:107], v[162:165], v[198:201], v[104:107]
	v_mfma_f32_16x16x32_bf16 v[104:107], v[178:181], v[202:205], v[104:107]
	v_mfma_f32_16x16x32_bf16 v[96:99], v[182:185], v[198:201], v[96:99]
	v_mfma_f32_16x16x32_bf16 v[96:99], v[186:189], v[202:205], v[96:99]
	v_mfma_f32_16x16x32_bf16 v[88:91], v[162:165], v[206:209], v[88:91]
	v_mfma_f32_16x16x32_bf16 v[88:91], v[178:181], v[210:213], v[88:91]
	v_mfma_f32_16x16x32_bf16 v[80:83], v[182:185], v[206:209], v[80:83]
	v_mfma_f32_16x16x32_bf16 v[80:83], v[186:189], v[210:213], v[80:83]
	v_mfma_f32_16x16x32_bf16 v[72:75], v[162:165], v[214:217], v[72:75]
	s_setprio 3
	s_barrier
	v_mfma_f32_16x16x32_bf16 v[72:75], v[178:181], v[218:221], v[72:75]
	v_mfma_f32_16x16x32_bf16 v[64:67], v[182:185], v[214:217], v[64:67]
	v_mfma_f32_16x16x32_bf16 v[64:67], v[186:189], v[218:221], v[64:67]
	s_setprio 0
.Lzj_10_0:
	s_add_i32 s74, s26, s16
	v_lshl_add_u64 v[166:167], s[70:71], 0, v[132:133]
	s_mov_b32 m0, s74
	ds_read_b128 v[190:193], v176 offset:16384
	ds_read_b128 v[194:197], v176 offset:17408
	ds_read_b128 v[198:201], v176 offset:18432
	ds_read_b128 v[202:205], v176 offset:19456
	ds_read_b128 v[206:209], v176 offset:20480
	ds_read_b128 v[210:213], v176 offset:21504
	ds_read_b128 v[214:217], v176 offset:22528
	ds_read_b128 v[218:221], v176 offset:23552
	global_load_lds_dwordx4 v[166:167], off
	s_add_i32 m0, s74, 0x2000
	s_add_u32 s74, s70, 0x40000
	v_lshl_add_u64 v[222:223], s[70:71], 0, v[128:129]
	s_addc_u32 s75, s71, 0
	s_add_i32 s76, s27, s16
	global_load_lds_dwordx4 v[222:223], off
	v_lshl_add_u64 v[224:225], s[74:75], 0, v[132:133]
	s_mov_b32 m0, s76
	global_load_lds_dwordx4 v[224:225], off
	s_add_i32 m0, s76, 0x2000
	v_lshl_add_u64 v[224:225], s[74:75], 0, v[128:129]
	global_load_lds_dwordx4 v[224:225], off
	s_mov_b32 m0, s17
	v_lshl_add_u64 v[224:225], s[72:73], 0, v[134:135]
	global_load_lds_dwordx4 v[224:225], off
	s_mov_b32 m0, s18
	v_lshl_add_u64 v[226:227], s[72:73], 0, v[130:131]
	global_load_lds_dwordx4 v[226:227], off
	s_cmp_eq_u32 s69, -2
	s_waitcnt vmcnt(8) lgkmcnt(0)
	s_barrier
	s_setprio 1
	s_cbranch_scc1 .Lzv_10_1
	v_mfma_f32_16x16x32_bf16 v[60:63], v[146:149], v[190:193], v[60:63]
	v_mfma_f32_16x16x32_bf16 v[60:63], v[150:153], v[194:197], v[60:63]
	v_mfma_f32_16x16x32_bf16 v[52:55], v[154:157], v[190:193], v[52:55]
	v_mfma_f32_16x16x32_bf16 v[52:55], v[158:161], v[194:197], v[52:55]
	v_mfma_f32_16x16x32_bf16 v[44:47], v[146:149], v[198:201], v[44:47]
	v_mfma_f32_16x16x32_bf16 v[44:47], v[150:153], v[202:205], v[44:47]
	v_mfma_f32_16x16x32_bf16 v[36:39], v[154:157], v[198:201], v[36:39]
	v_mfma_f32_16x16x32_bf16 v[36:39], v[158:161], v[202:205], v[36:39]
	v_mfma_f32_16x16x32_bf16 v[28:31], v[146:149], v[206:209], v[28:31]
	v_mfma_f32_16x16x32_bf16 v[28:31], v[150:153], v[210:213], v[28:31]
	v_mfma_f32_16x16x32_bf16 v[20:23], v[154:157], v[206:209], v[20:23]
	v_mfma_f32_16x16x32_bf16 v[20:23], v[158:161], v[210:213], v[20:23]
	v_mfma_f32_16x16x32_bf16 v[12:15], v[146:149], v[214:217], v[12:15]
	v_mfma_f32_16x16x32_bf16 v[12:15], v[150:153], v[218:221], v[12:15]
	v_mfma_f32_16x16x32_bf16 v[4:7], v[154:157], v[214:217], v[4:7]
	v_mfma_f32_16x16x32_bf16 v[4:7], v[158:161], v[218:221], v[4:7]
	v_mfma_f32_16x16x32_bf16 v[56:59], v[162:165], v[190:193], v[56:59]
	v_mfma_f32_16x16x32_bf16 v[56:59], v[178:181], v[194:197], v[56:59]
	v_mfma_f32_16x16x32_bf16 v[48:51], v[182:185], v[190:193], v[48:51]
	v_mfma_f32_16x16x32_bf16 v[48:51], v[186:189], v[194:197], v[48:51]
	v_mfma_f32_16x16x32_bf16 v[40:43], v[162:165], v[198:201], v[40:43]
	v_mfma_f32_16x16x32_bf16 v[40:43], v[178:181], v[202:205], v[40:43]
	v_mfma_f32_16x16x32_bf16 v[32:35], v[182:185], v[198:201], v[32:35]
	v_mfma_f32_16x16x32_bf16 v[32:35], v[186:189], v[202:205], v[32:35]
	v_mfma_f32_16x16x32_bf16 v[24:27], v[162:165], v[206:209], v[24:27]
	v_mfma_f32_16x16x32_bf16 v[24:27], v[178:181], v[210:213], v[24:27]
	v_mfma_f32_16x16x32_bf16 v[16:19], v[182:185], v[206:209], v[16:19]
	v_mfma_f32_16x16x32_bf16 v[16:19], v[186:189], v[210:213], v[16:19]
	v_mfma_f32_16x16x32_bf16 v[8:11], v[162:165], v[214:217], v[8:11]
	s_setprio 3
	s_barrier
	v_mfma_f32_16x16x32_bf16 v[8:11], v[178:181], v[218:221], v[8:11]
	v_mfma_f32_16x16x32_bf16 v[0:3], v[182:185], v[214:217], v[0:3]
	v_mfma_f32_16x16x32_bf16 v[0:3], v[186:189], v[218:221], v[0:3]
	s_setprio 0
.Lzj_10_1:
	s_add_i32 s74, 0, 0x18000
	s_add_i32 s75, 0, 0x1c000
	v_add_u32_e32 v158, s74, v171
	v_add_u32_e32 v186, s75, v171
	ds_read_b128 v[146:149], v158
	ds_read_b128 v[150:153], v158 offset:1024
	ds_read_b128 v[154:157], v158 offset:2048
	ds_read_b128 v[158:161], v158 offset:3072
	ds_read_b128 v[162:165], v186
	ds_read_b128 v[178:181], v186 offset:1024
	ds_read_b128 v[182:185], v186 offset:2048
	ds_read_b128 v[186:189], v186 offset:3072
	s_add_u32 s72, s72, 0x40000
	s_addc_u32 s73, s73, 0
	s_mov_b32 m0, s19
	v_lshl_add_u64 v[228:229], s[72:73], 0, v[134:135]
	ds_read_b128 v[190:193], v176 offset:32768
	ds_read_b128 v[194:197], v176 offset:33792
	ds_read_b128 v[198:201], v176 offset:34816
	ds_read_b128 v[202:205], v176 offset:35840
	ds_read_b128 v[206:209], v176 offset:36864
	ds_read_b128 v[210:213], v176 offset:37888
	ds_read_b128 v[214:217], v176 offset:38912
	ds_read_b128 v[218:221], v176 offset:39936
	global_load_lds_dwordx4 v[228:229], off
	s_mov_b32 m0, s20
	v_lshl_add_u64 v[228:229], s[72:73], 0, v[130:131]
	global_load_lds_dwordx4 v[228:229], off
	s_waitcnt vmcnt(8) lgkmcnt(0)
	s_barrier
	s_setprio 1
	v_mfma_f32_16x16x32_bf16 v[124:127], v[146:149], v[190:193], v[124:127]
	v_mfma_f32_16x16x32_bf16 v[124:127], v[150:153], v[194:197], v[124:127]
	v_mfma_f32_16x16x32_bf16 v[116:119], v[154:157], v[190:193], v[116:119]
	v_mfma_f32_16x16x32_bf16 v[116:119], v[158:161], v[194:197], v[116:119]
	v_mfma_f32_16x16x32_bf16 v[108:111], v[146:149], v[198:201], v[108:111]
	v_mfma_f32_16x16x32_bf16 v[108:111], v[150:153], v[202:205], v[108:111]
	v_mfma_f32_16x16x32_bf16 v[100:103], v[154:157], v[198:201], v[100:103]
	v_mfma_f32_16x16x32_bf16 v[100:103], v[158:161], v[202:205], v[100:103]
	v_mfma_f32_16x16x32_bf16 v[92:95], v[146:149], v[206:209], v[92:95]
	v_mfma_f32_16x16x32_bf16 v[92:95], v[150:153], v[210:213], v[92:95]
	v_mfma_f32_16x16x32_bf16 v[84:87], v[154:157], v[206:209], v[84:87]
	v_mfma_f32_16x16x32_bf16 v[84:87], v[158:161], v[210:213], v[84:87]
	v_mfma_f32_16x16x32_bf16 v[76:79], v[146:149], v[214:217], v[76:79]
	v_mfma_f32_16x16x32_bf16 v[76:79], v[150:153], v[218:221], v[76:79]
	v_mfma_f32_16x16x32_bf16 v[68:71], v[154:157], v[214:217], v[68:71]
	v_mfma_f32_16x16x32_bf16 v[68:71], v[158:161], v[218:221], v[68:71]
	v_mfma_f32_16x16x32_bf16 v[120:123], v[162:165], v[190:193], v[120:123]
	v_mfma_f32_16x16x32_bf16 v[120:123], v[178:181], v[194:197], v[120:123]
	v_mfma_f32_16x16x32_bf16 v[112:115], v[182:185], v[190:193], v[112:115]
	v_mfma_f32_16x16x32_bf16 v[112:115], v[186:189], v[194:197], v[112:115]
	v_mfma_f32_16x16x32_bf16 v[104:107], v[162:165], v[198:201], v[104:107]
	v_mfma_f32_16x16x32_bf16 v[104:107], v[178:181], v[202:205], v[104:107]
	v_mfma_f32_16x16x32_bf16 v[96:99], v[182:185], v[198:201], v[96:99]
	v_mfma_f32_16x16x32_bf16 v[96:99], v[186:189], v[202:205], v[96:99]
	v_mfma_f32_16x16x32_bf16 v[88:91], v[162:165], v[206:209], v[88:91]
	v_mfma_f32_16x16x32_bf16 v[88:91], v[178:181], v[210:213], v[88:91]
	v_mfma_f32_16x16x32_bf16 v[80:83], v[182:185], v[206:209], v[80:83]
	v_mfma_f32_16x16x32_bf16 v[80:83], v[186:189], v[210:213], v[80:83]
	v_mfma_f32_16x16x32_bf16 v[72:75], v[162:165], v[214:217], v[72:75]
	s_setprio 3
	s_barrier
	v_mfma_f32_16x16x32_bf16 v[72:75], v[178:181], v[218:221], v[72:75]
	v_mfma_f32_16x16x32_bf16 v[64:67], v[182:185], v[214:217], v[64:67]
	v_mfma_f32_16x16x32_bf16 v[64:67], v[186:189], v[218:221], v[64:67]
	s_setprio 0
	s_add_i32 s72, s74, s16
	v_lshl_add_u64 v[166:167], v[166:167], 0, s[10:11]
	s_mov_b32 m0, s72
	ds_read_b128 v[190:193], v176 offset:49152
	ds_read_b128 v[194:197], v176 offset:50176
	ds_read_b128 v[198:201], v176 offset:51200
	ds_read_b128 v[202:205], v176 offset:52224
	ds_read_b128 v[206:209], v176 offset:53248
	ds_read_b128 v[210:213], v176 offset:54272
	ds_read_b128 v[214:217], v176 offset:55296
	ds_read_b128 v[218:221], v176 offset:56320
	global_load_lds_dwordx4 v[166:167], off
	s_add_i32 m0, s72, 0x2000
	s_add_u32 s70, s70, 0x40080
	v_lshl_add_u64 v[166:167], v[222:223], 0, s[10:11]
	s_addc_u32 s71, s71, 0
	s_add_i32 s72, s75, s16
	global_load_lds_dwordx4 v[166:167], off
	s_mov_b32 m0, s72
	v_lshl_add_u64 v[166:167], s[70:71], 0, v[132:133]
	global_load_lds_dwordx4 v[166:167], off
	s_add_i32 m0, s72, 0x2000
	v_lshl_add_u64 v[166:167], s[70:71], 0, v[128:129]
	global_load_lds_dwordx4 v[166:167], off
	s_mov_b32 m0, s23
	v_lshl_add_u64 v[166:167], v[224:225], 0, s[10:11]
	global_load_lds_dwordx4 v[166:167], off
	s_mov_b32 m0, s24
	v_lshl_add_u64 v[166:167], v[226:227], 0, s[10:11]
	global_load_lds_dwordx4 v[166:167], off
	s_waitcnt vmcnt(8) lgkmcnt(0)
	s_barrier
	s_setprio 1
	v_mfma_f32_16x16x32_bf16 v[60:63], v[146:149], v[190:193], v[60:63]
	v_mfma_f32_16x16x32_bf16 v[60:63], v[150:153], v[194:197], v[60:63]
	v_mfma_f32_16x16x32_bf16 v[52:55], v[154:157], v[190:193], v[52:55]
	v_mfma_f32_16x16x32_bf16 v[52:55], v[158:161], v[194:197], v[52:55]
	v_mfma_f32_16x16x32_bf16 v[44:47], v[146:149], v[198:201], v[44:47]
	v_mfma_f32_16x16x32_bf16 v[44:47], v[150:153], v[202:205], v[44:47]
	v_mfma_f32_16x16x32_bf16 v[36:39], v[154:157], v[198:201], v[36:39]
	v_mfma_f32_16x16x32_bf16 v[36:39], v[158:161], v[202:205], v[36:39]
	v_mfma_f32_16x16x32_bf16 v[28:31], v[146:149], v[206:209], v[28:31]
	v_mfma_f32_16x16x32_bf16 v[28:31], v[150:153], v[210:213], v[28:31]
	v_mfma_f32_16x16x32_bf16 v[20:23], v[154:157], v[206:209], v[20:23]
	v_mfma_f32_16x16x32_bf16 v[20:23], v[158:161], v[210:213], v[20:23]
	v_mfma_f32_16x16x32_bf16 v[12:15], v[146:149], v[214:217], v[12:15]
	v_mfma_f32_16x16x32_bf16 v[12:15], v[150:153], v[218:221], v[12:15]
	v_mfma_f32_16x16x32_bf16 v[4:7], v[154:157], v[214:217], v[4:7]
	v_mfma_f32_16x16x32_bf16 v[4:7], v[158:161], v[218:221], v[4:7]
	v_mfma_f32_16x16x32_bf16 v[56:59], v[162:165], v[190:193], v[56:59]
	v_mfma_f32_16x16x32_bf16 v[56:59], v[178:181], v[194:197], v[56:59]
	v_mfma_f32_16x16x32_bf16 v[48:51], v[182:185], v[190:193], v[48:51]
	v_mfma_f32_16x16x32_bf16 v[48:51], v[186:189], v[194:197], v[48:51]
	v_mfma_f32_16x16x32_bf16 v[40:43], v[162:165], v[198:201], v[40:43]
	v_mfma_f32_16x16x32_bf16 v[40:43], v[178:181], v[202:205], v[40:43]
	v_mfma_f32_16x16x32_bf16 v[32:35], v[182:185], v[198:201], v[32:35]
	v_mfma_f32_16x16x32_bf16 v[32:35], v[186:189], v[202:205], v[32:35]
	v_mfma_f32_16x16x32_bf16 v[24:27], v[162:165], v[206:209], v[24:27]
	v_mfma_f32_16x16x32_bf16 v[24:27], v[178:181], v[210:213], v[24:27]
	v_mfma_f32_16x16x32_bf16 v[16:19], v[182:185], v[206:209], v[16:19]
	v_mfma_f32_16x16x32_bf16 v[16:19], v[186:189], v[210:213], v[16:19]
	v_mfma_f32_16x16x32_bf16 v[8:11], v[162:165], v[214:217], v[8:11]
	s_setprio 3
	s_barrier
	v_mfma_f32_16x16x32_bf16 v[8:11], v[178:181], v[218:221], v[8:11]
	v_mfma_f32_16x16x32_bf16 v[0:3], v[182:185], v[214:217], v[0:3]
	v_mfma_f32_16x16x32_bf16 v[0:3], v[186:189], v[218:221], v[0:3]
	s_setprio 0
	s_add_i32 s69, s69, 2
	s_add_u32 s58, s58, 0x100
	s_addc_u32 s59, s59, 0
	s_add_u32 s67, s67, 0x100
	s_addc_u32 s68, s68, 0
	s_cmp_gt_u32 s69, 13
	s_cbranch_scc0 .LBB0_2192
	s_branch .Lzskip_10

.LBB0_2341:
	ds_read_b128 v[128:131], v197
	ds_read_b128 v[132:135], v197 offset:1024
	ds_read_b128 v[136:139], v197 offset:2048
	ds_read_b128 v[140:143], v197 offset:3072
	ds_read_b128 v[144:147], v198
	ds_read_b128 v[148:151], v198 offset:1024
	ds_read_b128 v[152:155], v198 offset:2048
	ds_read_b128 v[156:159], v198 offset:3072
	s_add_u32 s18, s16, 0xfff50080
	s_addc_u32 s19, s17, -1
	s_cmp_eq_u32 s45, 40
	s_cselect_b32 s21, s5, s19
	s_cselect_b32 s20, s4, s18
	s_cselect_b32 s19, s15, s44
	s_cselect_b32 s18, s14, s43
	v_lshl_add_u64 v[192:193], s[16:17], 0, v[172:173]
	s_add_i32 m0, s25, 0xc000
	ds_read_b128 v[160:163], v199
	ds_read_b128 v[180:183], v199 offset:1024
	ds_read_b128 v[184:187], v199 offset:2048
	ds_read_b128 v[188:191], v199 offset:3072
	ds_read_b128 v[200:203], v199 offset:4096
	ds_read_b128 v[204:207], v199 offset:5120
	ds_read_b128 v[208:211], v199 offset:6144
	ds_read_b128 v[212:215], v199 offset:7168
	global_load_lds_dwordx4 v[192:193], off
	s_add_i32 m0, s25, 0xe000
	v_lshl_add_u64 v[192:193], s[16:17], 0, v[174:175]
	global_load_lds_dwordx4 v[192:193], off
	s_cmp_eq_u32 s45, -2
	s_waitcnt vmcnt(8) lgkmcnt(0)
	s_barrier
	s_setprio 1
	s_cbranch_scc1 .Lzv_11_0
	v_mfma_f32_16x16x32_bf16 v[124:127], v[128:131], v[160:163], v[124:127]
	v_mfma_f32_16x16x32_bf16 v[124:127], v[132:135], v[180:183], v[124:127]
	v_mfma_f32_16x16x32_bf16 v[120:123], v[136:139], v[160:163], v[120:123]
	v_mfma_f32_16x16x32_bf16 v[120:123], v[140:143], v[180:183], v[120:123]
	v_mfma_f32_16x16x32_bf16 v[108:111], v[128:131], v[184:187], v[108:111]
	v_mfma_f32_16x16x32_bf16 v[108:111], v[132:135], v[188:191], v[108:111]
	v_mfma_f32_16x16x32_bf16 v[104:107], v[136:139], v[184:187], v[104:107]
	v_mfma_f32_16x16x32_bf16 v[104:107], v[140:143], v[188:191], v[104:107]
	v_mfma_f32_16x16x32_bf16 v[96:99], v[128:131], v[200:203], v[96:99]
	v_mfma_f32_16x16x32_bf16 v[96:99], v[132:135], v[204:207], v[96:99]
	v_mfma_f32_16x16x32_bf16 v[88:91], v[136:139], v[200:203], v[88:91]
	v_mfma_f32_16x16x32_bf16 v[88:91], v[140:143], v[204:207], v[88:91]
	v_mfma_f32_16x16x32_bf16 v[80:83], v[128:131], v[208:211], v[80:83]
	v_mfma_f32_16x16x32_bf16 v[80:83], v[132:135], v[212:215], v[80:83]
	v_mfma_f32_16x16x32_bf16 v[72:75], v[136:139], v[208:211], v[72:75]
	v_mfma_f32_16x16x32_bf16 v[72:75], v[140:143], v[212:215], v[72:75]
	v_mfma_f32_16x16x32_bf16 v[116:119], v[144:147], v[160:163], v[116:119]
	v_mfma_f32_16x16x32_bf16 v[116:119], v[148:151], v[180:183], v[116:119]
	v_mfma_f32_16x16x32_bf16 v[112:115], v[152:155], v[160:163], v[112:115]
	v_mfma_f32_16x16x32_bf16 v[112:115], v[156:159], v[180:183], v[112:115]
	v_mfma_f32_16x16x32_bf16 v[100:103], v[144:147], v[184:187], v[100:103]
	v_mfma_f32_16x16x32_bf16 v[100:103], v[148:151], v[188:191], v[100:103]
	v_mfma_f32_16x16x32_bf16 v[92:95], v[152:155], v[184:187], v[92:95]
	v_mfma_f32_16x16x32_bf16 v[92:95], v[156:159], v[188:191], v[92:95]
	v_mfma_f32_16x16x32_bf16 v[84:87], v[144:147], v[200:203], v[84:87]
	v_mfma_f32_16x16x32_bf16 v[84:87], v[148:151], v[204:207], v[84:87]
	v_mfma_f32_16x16x32_bf16 v[76:79], v[152:155], v[200:203], v[76:79]
	v_mfma_f32_16x16x32_bf16 v[76:79], v[156:159], v[204:207], v[76:79]
	v_mfma_f32_16x16x32_bf16 v[68:71], v[144:147], v[208:211], v[68:71]
	s_setprio 3
	s_barrier
	v_mfma_f32_16x16x32_bf16 v[68:71], v[148:151], v[212:215], v[68:71]
	v_mfma_f32_16x16x32_bf16 v[64:67], v[152:155], v[208:211], v[64:67]
	v_mfma_f32_16x16x32_bf16 v[64:67], v[156:159], v[212:215], v[64:67]
	s_setprio 0
.Lzj_11_0:
	s_add_i32 s46, s37, s24
	v_lshl_add_u64 v[192:193], s[18:19], 0, v[166:167]
	s_mov_b32 m0, s46
	ds_read_b128 v[160:163], v199 offset:16384
	ds_read_b128 v[180:183], v199 offset:17408
	ds_read_b128 v[184:187], v199 offset:18432
	ds_read_b128 v[188:191], v199 offset:19456
	ds_read_b128 v[200:203], v199 offset:20480
	ds_read_b128 v[204:207], v199 offset:21504
	ds_read_b128 v[208:211], v199 offset:22528
	ds_read_b128 v[212:215], v199 offset:23552
	global_load_lds_dwordx4 v[192:193], off
	s_add_i32 m0, s46, 0x2000
	s_add_u32 s46, s18, 0xb0000
	v_lshl_add_u64 v[216:217], s[18:19], 0, v[170:171]
	s_addc_u32 s47, s19, 0
	s_add_i32 s48, s38, s24
	global_load_lds_dwordx4 v[216:217], off
	v_lshl_add_u64 v[218:219], s[46:47], 0, v[166:167]
	s_mov_b32 m0, s48
	global_load_lds_dwordx4 v[218:219], off
	s_add_i32 m0, s48, 0x2000
	v_lshl_add_u64 v[218:219], s[46:47], 0, v[170:171]
	global_load_lds_dwordx4 v[218:219], off
	s_mov_b32 m0, s25
	v_lshl_add_u64 v[218:219], s[20:21], 0, v[164:165]
	global_load_lds_dwordx4 v[218:219], off
	s_mov_b32 m0, s26
	v_lshl_add_u64 v[220:221], s[20:21], 0, v[168:169]
	global_load_lds_dwordx4 v[220:221], off
	s_cmp_eq_u32 s45, -2
	s_waitcnt vmcnt(8) lgkmcnt(0)
	s_barrier
	s_setprio 1
	s_cbranch_scc1 .Lzv_11_1
	v_mfma_f32_16x16x32_bf16 v[60:63], v[128:131], v[160:163], v[60:63]
	v_mfma_f32_16x16x32_bf16 v[60:63], v[132:135], v[180:183], v[60:63]
	v_mfma_f32_16x16x32_bf16 v[56:59], v[136:139], v[160:163], v[56:59]
	v_mfma_f32_16x16x32_bf16 v[56:59], v[140:143], v[180:183], v[56:59]
	v_mfma_f32_16x16x32_bf16 v[48:51], v[128:131], v[184:187], v[48:51]
	v_mfma_f32_16x16x32_bf16 v[48:51], v[132:135], v[188:191], v[48:51]
	v_mfma_f32_16x16x32_bf16 v[40:43], v[136:139], v[184:187], v[40:43]
	v_mfma_f32_16x16x32_bf16 v[40:43], v[140:143], v[188:191], v[40:43]
	v_mfma_f32_16x16x32_bf16 v[32:35], v[128:131], v[200:203], v[32:35]
	v_mfma_f32_16x16x32_bf16 v[32:35], v[132:135], v[204:207], v[32:35]
	v_mfma_f32_16x16x32_bf16 v[24:27], v[136:139], v[200:203], v[24:27]
	v_mfma_f32_16x16x32_bf16 v[24:27], v[140:143], v[204:207], v[24:27]
	v_mfma_f32_16x16x32_bf16 v[16:19], v[128:131], v[208:211], v[16:19]
	v_mfma_f32_16x16x32_bf16 v[16:19], v[132:135], v[212:215], v[16:19]
	v_mfma_f32_16x16x32_bf16 v[8:11], v[136:139], v[208:211], v[8:11]
	v_mfma_f32_16x16x32_bf16 v[8:11], v[140:143], v[212:215], v[8:11]
	v_mfma_f32_16x16x32_bf16 v[52:55], v[144:147], v[160:163], v[52:55]
	v_mfma_f32_16x16x32_bf16 v[52:55], v[148:151], v[180:183], v[52:55]
	v_mfma_f32_16x16x32_bf16 v[44:47], v[152:155], v[160:163], v[44:47]
	v_mfma_f32_16x16x32_bf16 v[44:47], v[156:159], v[180:183], v[44:47]
	v_mfma_f32_16x16x32_bf16 v[36:39], v[144:147], v[184:187], v[36:39]
	v_mfma_f32_16x16x32_bf16 v[36:39], v[148:151], v[188:191], v[36:39]
	v_mfma_f32_16x16x32_bf16 v[28:31], v[152:155], v[184:187], v[28:31]
	v_mfma_f32_16x16x32_bf16 v[28:31], v[156:159], v[188:191], v[28:31]
	v_mfma_f32_16x16x32_bf16 v[20:23], v[144:147], v[200:203], v[20:23]
	v_mfma_f32_16x16x32_bf16 v[20:23], v[148:151], v[204:207], v[20:23]
	v_mfma_f32_16x16x32_bf16 v[12:15], v[152:155], v[200:203], v[12:15]
	v_mfma_f32_16x16x32_bf16 v[12:15], v[156:159], v[204:207], v[12:15]
	v_mfma_f32_16x16x32_bf16 v[4:7], v[144:147], v[208:211], v[4:7]
	s_setprio 3
	s_barrier
	v_mfma_f32_16x16x32_bf16 v[4:7], v[148:151], v[212:215], v[4:7]
	v_mfma_f32_16x16x32_bf16 v[0:3], v[152:155], v[208:211], v[0:3]
	v_mfma_f32_16x16x32_bf16 v[0:3], v[156:159], v[212:215], v[0:3]
	s_setprio 0
.Lzj_11_1:
	s_add_i32 s46, 0, 0x18000
	s_add_i32 s47, 0, 0x1c000
	v_add_u32_e32 v140, s46, v195
	v_add_u32_e32 v156, s47, v195
	ds_read_b128 v[128:131], v140
	ds_read_b128 v[132:135], v140 offset:1024
	ds_read_b128 v[136:139], v140 offset:2048
	ds_read_b128 v[140:143], v140 offset:3072
	ds_read_b128 v[144:147], v156
	ds_read_b128 v[148:151], v156 offset:1024
	ds_read_b128 v[152:155], v156 offset:2048
	ds_read_b128 v[156:159], v156 offset:3072
	s_add_u32 s20, s20, 0xb0000
	s_addc_u32 s21, s21, 0
	s_mov_b32 m0, s27
	v_lshl_add_u64 v[222:223], s[20:21], 0, v[164:165]
	ds_read_b128 v[160:163], v199 offset:32768
	ds_read_b128 v[180:183], v199 offset:33792
	ds_read_b128 v[184:187], v199 offset:34816
	ds_read_b128 v[188:191], v199 offset:35840
	ds_read_b128 v[200:203], v199 offset:36864
	ds_read_b128 v[204:207], v199 offset:37888
	ds_read_b128 v[208:211], v199 offset:38912
	ds_read_b128 v[212:215], v199 offset:39936
	global_load_lds_dwordx4 v[222:223], off
	s_mov_b32 m0, s28
	v_lshl_add_u64 v[222:223], s[20:21], 0, v[168:169]
	global_load_lds_dwordx4 v[222:223], off
	s_waitcnt vmcnt(8) lgkmcnt(0)
	s_barrier
	s_setprio 1
	v_mfma_f32_16x16x32_bf16 v[124:127], v[128:131], v[160:163], v[124:127]
	v_mfma_f32_16x16x32_bf16 v[124:127], v[132:135], v[180:183], v[124:127]
	v_mfma_f32_16x16x32_bf16 v[120:123], v[136:139], v[160:163], v[120:123]
	v_mfma_f32_16x16x32_bf16 v[120:123], v[140:143], v[180:183], v[120:123]
	v_mfma_f32_16x16x32_bf16 v[108:111], v[128:131], v[184:187], v[108:111]
	v_mfma_f32_16x16x32_bf16 v[108:111], v[132:135], v[188:191], v[108:111]
	v_mfma_f32_16x16x32_bf16 v[104:107], v[136:139], v[184:187], v[104:107]
	v_mfma_f32_16x16x32_bf16 v[104:107], v[140:143], v[188:191], v[104:107]
	v_mfma_f32_16x16x32_bf16 v[96:99], v[128:131], v[200:203], v[96:99]
	v_mfma_f32_16x16x32_bf16 v[96:99], v[132:135], v[204:207], v[96:99]
	v_mfma_f32_16x16x32_bf16 v[88:91], v[136:139], v[200:203], v[88:91]
	v_mfma_f32_16x16x32_bf16 v[88:91], v[140:143], v[204:207], v[88:91]
	v_mfma_f32_16x16x32_bf16 v[80:83], v[128:131], v[208:211], v[80:83]
	v_mfma_f32_16x16x32_bf16 v[80:83], v[132:135], v[212:215], v[80:83]
	v_mfma_f32_16x16x32_bf16 v[72:75], v[136:139], v[208:211], v[72:75]
	v_mfma_f32_16x16x32_bf16 v[72:75], v[140:143], v[212:215], v[72:75]
	v_mfma_f32_16x16x32_bf16 v[116:119], v[144:147], v[160:163], v[116:119]
	v_mfma_f32_16x16x32_bf16 v[116:119], v[148:151], v[180:183], v[116:119]
	v_mfma_f32_16x16x32_bf16 v[112:115], v[152:155], v[160:163], v[112:115]
	v_mfma_f32_16x16x32_bf16 v[112:115], v[156:159], v[180:183], v[112:115]
	v_mfma_f32_16x16x32_bf16 v[100:103], v[144:147], v[184:187], v[100:103]
	v_mfma_f32_16x16x32_bf16 v[100:103], v[148:151], v[188:191], v[100:103]
	v_mfma_f32_16x16x32_bf16 v[92:95], v[152:155], v[184:187], v[92:95]
	v_mfma_f32_16x16x32_bf16 v[92:95], v[156:159], v[188:191], v[92:95]
	v_mfma_f32_16x16x32_bf16 v[84:87], v[144:147], v[200:203], v[84:87]
	v_mfma_f32_16x16x32_bf16 v[84:87], v[148:151], v[204:207], v[84:87]
	v_mfma_f32_16x16x32_bf16 v[76:79], v[152:155], v[200:203], v[76:79]
	v_mfma_f32_16x16x32_bf16 v[76:79], v[156:159], v[204:207], v[76:79]
	v_mfma_f32_16x16x32_bf16 v[68:71], v[144:147], v[208:211], v[68:71]
	s_setprio 3
	s_barrier
	v_mfma_f32_16x16x32_bf16 v[68:71], v[148:151], v[212:215], v[68:71]
	v_mfma_f32_16x16x32_bf16 v[64:67], v[152:155], v[208:211], v[64:67]
	v_mfma_f32_16x16x32_bf16 v[64:67], v[156:159], v[212:215], v[64:67]
	s_setprio 0
	s_add_i32 s20, s46, s24
	v_lshl_add_u64 v[192:193], v[192:193], 0, s[8:9]
	s_mov_b32 m0, s20
	ds_read_b128 v[160:163], v199 offset:49152
	ds_read_b128 v[180:183], v199 offset:50176
	ds_read_b128 v[184:187], v199 offset:51200
	ds_read_b128 v[188:191], v199 offset:52224
	ds_read_b128 v[200:203], v199 offset:53248
	ds_read_b128 v[204:207], v199 offset:54272
	ds_read_b128 v[208:211], v199 offset:55296
	ds_read_b128 v[212:215], v199 offset:56320
	global_load_lds_dwordx4 v[192:193], off
	s_add_i32 m0, s20, 0x2000
	s_add_u32 s18, s18, 0xb0080
	v_lshl_add_u64 v[192:193], v[216:217], 0, s[8:9]
	s_addc_u32 s19, s19, 0
	s_add_i32 s20, s47, s24
	global_load_lds_dwordx4 v[192:193], off
	s_mov_b32 m0, s20
	v_lshl_add_u64 v[192:193], s[18:19], 0, v[166:167]
	global_load_lds_dwordx4 v[192:193], off
	s_add_i32 m0, s20, 0x2000
	v_lshl_add_u64 v[192:193], s[18:19], 0, v[170:171]
	global_load_lds_dwordx4 v[192:193], off
	s_mov_b32 m0, s33
	v_lshl_add_u64 v[192:193], v[218:219], 0, s[8:9]
	global_load_lds_dwordx4 v[192:193], off
	s_mov_b32 m0, s35
	v_lshl_add_u64 v[192:193], v[220:221], 0, s[8:9]
	global_load_lds_dwordx4 v[192:193], off
	s_waitcnt vmcnt(8) lgkmcnt(0)
	s_barrier
	s_setprio 1
	v_mfma_f32_16x16x32_bf16 v[60:63], v[128:131], v[160:163], v[60:63]
	v_mfma_f32_16x16x32_bf16 v[60:63], v[132:135], v[180:183], v[60:63]
	v_mfma_f32_16x16x32_bf16 v[56:59], v[136:139], v[160:163], v[56:59]
	v_mfma_f32_16x16x32_bf16 v[56:59], v[140:143], v[180:183], v[56:59]
	v_mfma_f32_16x16x32_bf16 v[48:51], v[128:131], v[184:187], v[48:51]
	v_mfma_f32_16x16x32_bf16 v[48:51], v[132:135], v[188:191], v[48:51]
	v_mfma_f32_16x16x32_bf16 v[40:43], v[136:139], v[184:187], v[40:43]
	v_mfma_f32_16x16x32_bf16 v[40:43], v[140:143], v[188:191], v[40:43]
	v_mfma_f32_16x16x32_bf16 v[32:35], v[128:131], v[200:203], v[32:35]
	v_mfma_f32_16x16x32_bf16 v[32:35], v[132:135], v[204:207], v[32:35]
	v_mfma_f32_16x16x32_bf16 v[24:27], v[136:139], v[200:203], v[24:27]
	v_mfma_f32_16x16x32_bf16 v[24:27], v[140:143], v[204:207], v[24:27]
	v_mfma_f32_16x16x32_bf16 v[16:19], v[128:131], v[208:211], v[16:19]
	v_mfma_f32_16x16x32_bf16 v[16:19], v[132:135], v[212:215], v[16:19]
	v_mfma_f32_16x16x32_bf16 v[8:11], v[136:139], v[208:211], v[8:11]
	v_mfma_f32_16x16x32_bf16 v[8:11], v[140:143], v[212:215], v[8:11]
	v_mfma_f32_16x16x32_bf16 v[52:55], v[144:147], v[160:163], v[52:55]
	v_mfma_f32_16x16x32_bf16 v[52:55], v[148:151], v[180:183], v[52:55]
	v_mfma_f32_16x16x32_bf16 v[44:47], v[152:155], v[160:163], v[44:47]
	v_mfma_f32_16x16x32_bf16 v[44:47], v[156:159], v[180:183], v[44:47]
	v_mfma_f32_16x16x32_bf16 v[36:39], v[144:147], v[184:187], v[36:39]
	v_mfma_f32_16x16x32_bf16 v[36:39], v[148:151], v[188:191], v[36:39]
	v_mfma_f32_16x16x32_bf16 v[28:31], v[152:155], v[184:187], v[28:31]
	v_mfma_f32_16x16x32_bf16 v[28:31], v[156:159], v[188:191], v[28:31]
	v_mfma_f32_16x16x32_bf16 v[20:23], v[144:147], v[200:203], v[20:23]
	v_mfma_f32_16x16x32_bf16 v[20:23], v[148:151], v[204:207], v[20:23]
	v_mfma_f32_16x16x32_bf16 v[12:15], v[152:155], v[200:203], v[12:15]
	v_mfma_f32_16x16x32_bf16 v[12:15], v[156:159], v[204:207], v[12:15]
	v_mfma_f32_16x16x32_bf16 v[4:7], v[144:147], v[208:211], v[4:7]
	s_setprio 3
	s_barrier
	v_mfma_f32_16x16x32_bf16 v[4:7], v[148:151], v[212:215], v[4:7]
	v_mfma_f32_16x16x32_bf16 v[0:3], v[152:155], v[208:211], v[0:3]
	v_mfma_f32_16x16x32_bf16 v[0:3], v[156:159], v[212:215], v[0:3]
	s_setprio 0
	s_add_i32 s45, s45, 2
	s_add_u32 s16, s16, 0x100
	s_addc_u32 s17, s17, 0
	s_add_u32 s43, s43, 0x100
	s_addc_u32 s44, s44, 0
	s_cmp_gt_u32 s45, 41
	s_cbranch_scc0 .LBB0_2341
	s_branch .Lzskip_11
.Lzv_11_0:
	v_mfma_f32_16x16x32_bf16 v[124:127], v[128:131], v[160:163], 0
	v_mfma_f32_16x16x32_bf16 v[124:127], v[132:135], v[180:183], v[124:127]
	v_mfma_f32_16x16x32_bf16 v[120:123], v[136:139], v[160:163], 0
	v_mfma_f32_16x16x32_bf16 v[120:123], v[140:143], v[180:183], v[120:123]
	v_mfma_f32_16x16x32_bf16 v[108:111], v[128:131], v[184:187], 0
	v_mfma_f32_16x16x32_bf16 v[108:111], v[132:135], v[188:191], v[108:111]
	v_mfma_f32_16x16x32_bf16 v[104:107], v[136:139], v[184:187], 0
	v_mfma_f32_16x16x32_bf16 v[104:107], v[140:143], v[188:191], v[104:107]
	v_mfma_f32_16x16x32_bf16 v[96:99], v[128:131], v[200:203], 0
	v_mfma_f32_16x16x32_bf16 v[96:99], v[132:135], v[204:207], v[96:99]
	v_mfma_f32_16x16x32_bf16 v[88:91], v[136:139], v[200:203], 0
	v_mfma_f32_16x16x32_bf16 v[88:91], v[140:143], v[204:207], v[88:91]
	v_mfma_f32_16x16x32_bf16 v[80:83], v[128:131], v[208:211], 0
	v_mfma_f32_16x16x32_bf16 v[80:83], v[132:135], v[212:215], v[80:83]
	v_mfma_f32_16x16x32_bf16 v[72:75], v[136:139], v[208:211], 0
	v_mfma_f32_16x16x32_bf16 v[72:75], v[140:143], v[212:215], v[72:75]
	v_mfma_f32_16x16x32_bf16 v[116:119], v[144:147], v[160:163], 0
	v_mfma_f32_16x16x32_bf16 v[116:119], v[148:151], v[180:183], v[116:119]
	v_mfma_f32_16x16x32_bf16 v[112:115], v[152:155], v[160:163], 0
	v_mfma_f32_16x16x32_bf16 v[112:115], v[156:159], v[180:183], v[112:115]
	v_mfma_f32_16x16x32_bf16 v[100:103], v[144:147], v[184:187], 0
	v_mfma_f32_16x16x32_bf16 v[100:103], v[148:151], v[188:191], v[100:103]
	v_mfma_f32_16x16x32_bf16 v[92:95], v[152:155], v[184:187], 0
	v_mfma_f32_16x16x32_bf16 v[92:95], v[156:159], v[188:191], v[92:95]
	v_mfma_f32_16x16x32_bf16 v[84:87], v[144:147], v[200:203], 0
	v_mfma_f32_16x16x32_bf16 v[84:87], v[148:151], v[204:207], v[84:87]
	v_mfma_f32_16x16x32_bf16 v[76:79], v[152:155], v[200:203], 0
	v_mfma_f32_16x16x32_bf16 v[76:79], v[156:159], v[204:207], v[76:79]
	v_mfma_f32_16x16x32_bf16 v[68:71], v[144:147], v[208:211], 0
	s_setprio 3
	s_barrier
	v_mfma_f32_16x16x32_bf16 v[68:71], v[148:151], v[212:215], v[68:71]
	v_mfma_f32_16x16x32_bf16 v[64:67], v[152:155], v[208:211], 0
	v_mfma_f32_16x16x32_bf16 v[64:67], v[156:159], v[212:215], v[64:67]
	s_setprio 0
	s_branch .Lzj_11_0
.Lzv_11_1:
	v_mfma_f32_16x16x32_bf16 v[60:63], v[128:131], v[160:163], 0
	v_mfma_f32_16x16x32_bf16 v[60:63], v[132:135], v[180:183], v[60:63]
	v_mfma_f32_16x16x32_bf16 v[56:59], v[136:139], v[160:163], 0
	v_mfma_f32_16x16x32_bf16 v[56:59], v[140:143], v[180:183], v[56:59]
	v_mfma_f32_16x16x32_bf16 v[48:51], v[128:131], v[184:187], 0
	v_mfma_f32_16x16x32_bf16 v[48:51], v[132:135], v[188:191], v[48:51]
	v_mfma_f32_16x16x32_bf16 v[40:43], v[136:139], v[184:187], 0
	v_mfma_f32_16x16x32_bf16 v[40:43], v[140:143], v[188:191], v[40:43]
	v_mfma_f32_16x16x32_bf16 v[32:35], v[128:131], v[200:203], 0
	v_mfma_f32_16x16x32_bf16 v[32:35], v[132:135], v[204:207], v[32:35]
	v_mfma_f32_16x16x32_bf16 v[24:27], v[136:139], v[200:203], 0
	v_mfma_f32_16x16x32_bf16 v[24:27], v[140:143], v[204:207], v[24:27]
	v_mfma_f32_16x16x32_bf16 v[16:19], v[128:131], v[208:211], 0
	v_mfma_f32_16x16x32_bf16 v[16:19], v[132:135], v[212:215], v[16:19]
	v_mfma_f32_16x16x32_bf16 v[8:11], v[136:139], v[208:211], 0
	v_mfma_f32_16x16x32_bf16 v[8:11], v[140:143], v[212:215], v[8:11]
	v_mfma_f32_16x16x32_bf16 v[52:55], v[144:147], v[160:163], 0
	v_mfma_f32_16x16x32_bf16 v[52:55], v[148:151], v[180:183], v[52:55]
	v_mfma_f32_16x16x32_bf16 v[44:47], v[152:155], v[160:163], 0
	v_mfma_f32_16x16x32_bf16 v[44:47], v[156:159], v[180:183], v[44:47]
	v_mfma_f32_16x16x32_bf16 v[36:39], v[144:147], v[184:187], 0
	v_mfma_f32_16x16x32_bf16 v[36:39], v[148:151], v[188:191], v[36:39]
	v_mfma_f32_16x16x32_bf16 v[28:31], v[152:155], v[184:187], 0
	v_mfma_f32_16x16x32_bf16 v[28:31], v[156:159], v[188:191], v[28:31]
	v_mfma_f32_16x16x32_bf16 v[20:23], v[144:147], v[200:203], 0
	v_mfma_f32_16x16x32_bf16 v[20:23], v[148:151], v[204:207], v[20:23]
	v_mfma_f32_16x16x32_bf16 v[12:15], v[152:155], v[200:203], 0
	v_mfma_f32_16x16x32_bf16 v[12:15], v[156:159], v[204:207], v[12:15]
	v_mfma_f32_16x16x32_bf16 v[4:7], v[144:147], v[208:211], 0
	s_setprio 3
	s_barrier
	v_mfma_f32_16x16x32_bf16 v[4:7], v[148:151], v[212:215], v[4:7]
	v_mfma_f32_16x16x32_bf16 v[0:3], v[152:155], v[208:211], 0
	v_mfma_f32_16x16x32_bf16 v[0:3], v[156:159], v[212:215], v[0:3]
	s_setprio 0
	s_branch .Lzj_11_1
